# speedup vs baseline: 1.0102x; 1.0102x over previous
; #define SBAR() __builtin_amdgcn_sched_barrier(0)
; __device__ __forceinline__ void finishSM(f32x16& p0, f32x16& p1, float alpha, float& l_reg, bf16x8& pa0, bf16x8& pa1, bf16x8& pa2, bf16x8& pa3) {
; #pragma unroll
;   for (int r = 0; r < 16; ++r) p1[r] = __builtin_amdgcn_exp2f(p1[r]);
;   float ps = 0;
; #pragma unroll
;   for (int r = 0; r < 16; ++r) ps += p0[r];
; #pragma unroll
;   for (int r = 0; r < 16; ++r) ps += p1[r];
;   { auto rr = __builtin_amdgcn_permlane32_swap(__float_as_uint(ps), __float_as_uint(ps), false, false);
;     ps = __uint_as_float(rr[0]) + __uint_as_float(rr[1]); }
;   l_reg = l_reg * alpha + ps;
;     ...
;   PK4(p0, 0, pa0); PK4(p0, 8, pa1); PK4(p1, 0, pa2); PK4(p1, 8, pa3);
;     ...
; }
; template <int D0> __device__ __forceinline__ void pv_one_t(f32x16& od, int vb, bf16x8 pa0, bf16x8 pa1, bf16x8 pa2, bf16x8 pa3) {
;   const s16x4 l0 = tr_read<v_rd_off(D0, 0, 0)>(vb), h0 = tr_read<v_rd_off(D0, 0, 1)>(vb), l1 = tr_read<v_rd_off(D0, 1, 0)>(vb), h1 = tr_read<v_rd_off(D0, 1, 1)>(vb);
;   const s16x4 l2 = tr_read<v_rd_off(D0, 2, 0)>(vb), h2 = tr_read<v_rd_off(D0, 2, 1)>(vb), l3 = tr_read<v_rd_off(D0, 3, 0)>(vb), h3 = tr_read<v_rd_off(D0, 3, 1)>(vb);
;   asm volatile("s_waitcnt lgkmcnt(0)" ::: "memory"); SBAR();
;     ...
;   od = __builtin_amdgcn_mfma_f32_32x32x16_bf16(PK(l0, h0), pa0, od, 0, 0, 0);
;   od = __builtin_amdgcn_mfma_f32_32x32x16_bf16(PK(l1, h1), pa1, od, 0, 0, 0);
;   od = __builtin_amdgcn_mfma_f32_32x32x16_bf16(PK(l2, h2), pa2, od, 0, 0, 0);
;   od = __builtin_amdgcn_mfma_f32_32x32x16_bf16(PK(l3, h3), pa3, od, 0, 0, 0);
;     ...
; }
.LBB0_113:
	v_cndmask_b32_e64 v97, v97, v197, s[4:5]
	v_mul_f32_e32 v97, 0xbf800000, v97
	v_fmamk_f32 v80, v80, 0x3f800000, v97
	v_fmamk_f32 v81, v81, 0x3f800000, v97
	v_exp_f32_e32 v80, v80
	v_fmamk_f32 v82, v82, 0x3f800000, v97
	v_exp_f32_e32 v81, v81
	v_fmamk_f32 v83, v83, 0x3f800000, v97
	v_exp_f32_e32 v82, v82
	v_fmamk_f32 v84, v84, 0x3f800000, v97
	v_exp_f32_e32 v83, v83
	v_fmamk_f32 v65, v65, 0x3f800000, v97
	v_fmamk_f32 v85, v85, 0x3f800000, v97
	v_exp_f32_e32 v84, v84
	v_exp_f32_e32 v99, v65
	v_add_f32_e32 v65, 0, v80
	v_fmamk_f32 v86, v86, 0x3f800000, v97
	v_exp_f32_e32 v85, v85
	v_add_f32_e32 v65, v81, v65
	v_fmamk_f32 v87, v87, 0x3f800000, v97
	v_exp_f32_e32 v86, v86
	v_add_f32_e32 v65, v82, v65
	v_fmamk_f32 v88, v88, 0x3f800000, v97
	v_exp_f32_e32 v87, v87
	v_add_f32_e32 v65, v83, v65
	v_fmamk_f32 v89, v89, 0x3f800000, v97
	v_exp_f32_e32 v88, v88
	v_add_f32_e32 v65, v84, v65
	v_fmamk_f32 v90, v90, 0x3f800000, v97
	v_exp_f32_e32 v89, v89
	v_add_f32_e32 v65, v85, v65
	v_fmamk_f32 v91, v91, 0x3f800000, v97
	v_exp_f32_e32 v90, v90
	v_add_f32_e32 v65, v86, v65
	v_fmamk_f32 v92, v92, 0x3f800000, v97
	v_exp_f32_e32 v91, v91
	v_add_f32_e32 v65, v87, v65
	v_fmamk_f32 v93, v93, 0x3f800000, v97
	v_exp_f32_e32 v92, v92
	v_add_f32_e32 v65, v88, v65
	v_fmamk_f32 v94, v94, 0x3f800000, v97
	v_exp_f32_e32 v93, v93
	v_add_f32_e32 v65, v89, v65
	v_fmamk_f32 v95, v95, 0x3f800000, v97
	v_exp_f32_e32 v94, v94
	v_add_f32_e32 v65, v90, v65
	v_exp_f32_e32 v95, v95
	v_fmamk_f32 v79, v79, 0x3f800000, v97
	v_fmamk_f32 v78, v78, 0x3f800000, v97
	v_fmamk_f32 v77, v77, 0x3f800000, v97
	v_fmamk_f32 v76, v76, 0x3f800000, v97
	v_fmamk_f32 v75, v75, 0x3f800000, v97
	v_fmamk_f32 v74, v74, 0x3f800000, v97
	v_fmamk_f32 v73, v73, 0x3f800000, v97
	v_fmamk_f32 v72, v72, 0x3f800000, v97
	v_fmamk_f32 v71, v71, 0x3f800000, v97
	v_fmamk_f32 v70, v70, 0x3f800000, v97
	v_fmamk_f32 v69, v69, 0x3f800000, v97
	v_fmamk_f32 v68, v68, 0x3f800000, v97
	v_fmamk_f32 v67, v67, 0x3f800000, v97
	v_fmamk_f32 v98, v66, 0x3f800000, v97
	v_fmac_f32_e32 v97, 0x3f800000, v64
	v_add_f32_e32 v65, v91, v65
	v_exp_f32_e32 v97, v97
	v_add_f32_e32 v65, v92, v65
	v_add_f32_e32 v65, v93, v65
	v_exp_f32_e32 v98, v98
	v_add_f32_e32 v65, v94, v65
	v_add_f32_e32 v66, v100, v101
	v_exp_f32_e32 v100, v67
	v_add_f32_e32 v65, v95, v65
	v_exp_f32_e32 v101, v68
	v_add_f32_e32 v65, v97, v65
	v_exp_f32_e32 v102, v69
	v_add_f32_e32 v65, v99, v65
	v_exp_f32_e32 v103, v70
	v_add_f32_e32 v65, v98, v65
	v_exp_f32_e32 v104, v71
	v_add_f32_e32 v65, v100, v65
	v_exp_f32_e32 v105, v72
	v_add_f32_e32 v65, v101, v65
	v_exp_f32_e32 v106, v73
	v_add_f32_e32 v65, v102, v65
	v_exp_f32_e32 v107, v74
	v_add_f32_e32 v65, v103, v65
	v_exp_f32_e32 v108, v75
	v_add_f32_e32 v65, v104, v65
	v_exp_f32_e32 v109, v76
	v_add_f32_e32 v65, v105, v65
	v_exp_f32_e32 v110, v77
	v_add_f32_e32 v65, v106, v65
	v_exp_f32_e32 v111, v78
	v_add_f32_e32 v65, v107, v65
	v_exp_f32_e32 v112, v79
	v_add_f32_e32 v65, v108, v65
	v_add_f32_e32 v65, v109, v65
	v_add_f32_e32 v65, v110, v65
	v_add_f32_e32 v65, v111, v65
	s_lshl_b64 s[12:13], s[12:13], 11
	v_add_f32_e32 v65, v112, v65
	s_add_u32 s12, s28, s12
	v_mov_b32_e32 v67, v65
	s_addc_u32 s13, s29, s13
	s_lshl_b32 s14, s37, 1
	v_mul_f32_e32 v64, v162, v144
	v_permlane32_swap_b32_e32 v65, v67
	s_add_u32 s12, s12, s14
	v_pk_add_f32 v[64:65], v[64:65], v[66:67]
	v_cvt_pk_bf16_f32 v66, v80, v81
	v_cvt_pk_bf16_f32 v67, v82, v83
	v_cvt_pk_bf16_f32 v68, v84, v85
	v_cvt_pk_bf16_f32 v69, v86, v87
	v_cvt_pk_bf16_f32 v70, v88, v89
	v_cvt_pk_bf16_f32 v71, v90, v91
	v_cvt_pk_bf16_f32 v72, v92, v93
	v_cvt_pk_bf16_f32 v73, v94, v95
	v_cvt_pk_bf16_f32 v74, v97, v99
	v_cvt_pk_bf16_f32 v75, v98, v100
	v_cvt_pk_bf16_f32 v76, v101, v102
	v_cvt_pk_bf16_f32 v77, v103, v104
	v_cvt_pk_bf16_f32 v78, v105, v106
	v_cvt_pk_bf16_f32 v79, v107, v108
	v_cvt_pk_bf16_f32 v80, v109, v110
	v_cvt_pk_bf16_f32 v81, v111, v112
	s_addc_u32 s13, s13, 0
	v_fmac_f32_e32 v65, v64, v96
	ds_read_b64_tr_b16 v[82:83], v196 offset:0
	ds_read_b64_tr_b16 v[84:85], v196 offset:0x800
	ds_read_b64_tr_b16 v[86:87], v196 offset:0x1000
	ds_read_b64_tr_b16 v[88:89], v196 offset:0x1800
	ds_read_b64_tr_b16 v[90:91], v196 offset:0x2000
	ds_read_b64_tr_b16 v[92:93], v196 offset:0x2800
	ds_read_b64_tr_b16 v[94:95], v196 offset:0x3000
	ds_read_b64_tr_b16 v[96:97], v196 offset:0x3800
	s_waitcnt lgkmcnt(0)
	s_nop 0
	v_mfma_f32_32x32x16_bf16 v[0:15], v[82:85], v[66:69], v[0:15]
	ds_read_b64_tr_b16 v[82:83], v196 offset:0x200
	ds_read_b64_tr_b16 v[84:85], v196 offset:0xa00
	v_mfma_f32_32x32x16_bf16 v[0:15], v[86:89], v[70:73], v[0:15]
	ds_read_b64_tr_b16 v[86:87], v196 offset:0x1200
	ds_read_b64_tr_b16 v[88:89], v196 offset:0x1a00
	v_mfma_f32_32x32x16_bf16 v[0:15], v[90:93], v[74:77], v[0:15]
	ds_read_b64_tr_b16 v[90:91], v196 offset:0x2200
	ds_read_b64_tr_b16 v[92:93], v196 offset:0x2a00
	v_mfma_f32_32x32x16_bf16 v[0:15], v[94:97], v[78:81], v[0:15]
	ds_read_b64_tr_b16 v[94:95], v196 offset:0x3200
	ds_read_b64_tr_b16 v[96:97], v196 offset:0x3a00
	s_waitcnt lgkmcnt(0)
	v_mfma_f32_32x32x16_bf16 v[48:63], v[82:85], v[66:69], v[48:63]
	ds_read_b64_tr_b16 v[82:83], v196 offset:0x400
	ds_read_b64_tr_b16 v[84:85], v196 offset:0xc00
	v_mfma_f32_32x32x16_bf16 v[48:63], v[86:89], v[70:73], v[48:63]
	ds_read_b64_tr_b16 v[86:87], v196 offset:0x1400
	ds_read_b64_tr_b16 v[88:89], v196 offset:0x1c00
	v_mfma_f32_32x32x16_bf16 v[48:63], v[90:93], v[74:77], v[48:63]
	ds_read_b64_tr_b16 v[90:91], v196 offset:0x2400
	ds_read_b64_tr_b16 v[92:93], v196 offset:0x2c00
	v_mfma_f32_32x32x16_bf16 v[48:63], v[94:97], v[78:81], v[48:63]
	ds_read_b64_tr_b16 v[94:95], v196 offset:0x3400
	ds_read_b64_tr_b16 v[96:97], v196 offset:0x3c00
	s_waitcnt lgkmcnt(0)
; __device__ __forceinline__ void attn_mla_dma(const bf16_t* __restrict__ Qb, const bf16_t* __restrict__ Kh, const bf16_t* __restrict__ Vh, bf16_t* __restrict__ Ob,
;                                              int seq, char* lds, const int tid) {
;     ...
;   pv_d0_t(o, vb0 + vcur * SHM_VV, pa0, pa1, pa2, pa3);
;   int tide = tid; asm volatile("" : "+v"(tide));
;   const int wide = tide >> 6, r32e = tide & 31, hie = (tide >> 5) & 1;
;   const float rl = __builtin_amdgcn_rcpf(l_reg);
;   bf16_t* Ow = Ob + (long)(wide * QBLK + r32e) * LDO + hie * 8;
; #pragma unroll
;   for (int d0 = 0; d0 < 4; ++d0)
; #pragma unroll
;     for (int b = 0; b < 16; b += 8) {
;       const u32x4 w = pack8_row(o[d0][b] * rl, o[d0][b + 1] * rl, o[d0][b + 2] * rl, o[d0][b + 3] * rl, o[d0][b + 4] * rl, o[d0][b + 5] * rl, o[d0][b + 6] * rl, o[d0][b + 7] * rl);
;       *reinterpret_cast<u32x4*>(Ow + d0 * 32 + b * 2) = w;
;     }
;   __syncthreads();
	v_mfma_f32_32x32x16_bf16 v[32:47], v[82:85], v[66:69], v[32:47]
	ds_read_b64_tr_b16 v[82:83], v196 offset:0x600
	ds_read_b64_tr_b16 v[84:85], v196 offset:0xe00
	v_mfma_f32_32x32x16_bf16 v[32:47], v[86:89], v[70:73], v[32:47]
	ds_read_b64_tr_b16 v[86:87], v196 offset:0x1600
	ds_read_b64_tr_b16 v[88:89], v196 offset:0x1e00
	v_mfma_f32_32x32x16_bf16 v[32:47], v[90:93], v[74:77], v[32:47]
	ds_read_b64_tr_b16 v[90:91], v196 offset:0x2600
	ds_read_b64_tr_b16 v[92:93], v196 offset:0x2e00
	v_mfma_f32_32x32x16_bf16 v[32:47], v[94:97], v[78:81], v[32:47]
	ds_read_b64_tr_b16 v[94:95], v196 offset:0x3600
	ds_read_b64_tr_b16 v[96:97], v196 offset:0x3e00
	s_waitcnt lgkmcnt(0)
	v_mfma_f32_32x32x16_bf16 v[16:31], v[82:85], v[66:69], v[16:31]
	v_rcp_f32_e32 v66, v65
	s_movk_i32 s4, 0xffe0
	v_ashrrev_i32_e32 v64, 1, v156
	v_bfi_b32 v64, s4, v64, v156
	v_ashrrev_i32_e32 v65, 31, v64
	v_lshlrev_b64 v[64:65], 11, v[64:65]
	v_mfma_f32_32x32x16_bf16 v[16:31], v[86:89], v[70:73], v[16:31]
	v_lshrrev_b32_e32 v67, 1, v156
	v_mul_f32_e32 v0, v66, v0
	v_mul_f32_e32 v1, v66, v1
	v_mul_f32_e32 v2, v66, v2
	v_mul_f32_e32 v3, v66, v3
	v_lshl_add_u64 v[64:65], s[12:13], 0, v[64:65]
	v_and_b32_e32 v162, 16, v67
	v_mul_f32_e32 v4, v66, v4
	v_mul_f32_e32 v5, v66, v5
	v_mul_f32_e32 v6, v66, v6
	v_mul_f32_e32 v7, v66, v7
	v_cvt_pk_bf16_f32 v0, v0, v1
	v_cvt_pk_bf16_f32 v1, v2, v3
	v_cvt_pk_bf16_f32 v2, v4, v5
	v_cvt_pk_bf16_f32 v3, v6, v7
	v_mfma_f32_32x32x16_bf16 v[16:31], v[90:93], v[74:77], v[16:31]
	v_lshl_add_u64 v[64:65], v[64:65], 0, v[162:163]
	v_permlane32_swap_b32_e32 v0, v2
	v_permlane32_swap_b32_e32 v1, v3
	flat_store_dwordx4 v[64:65], v[0:3]
	v_mul_f32_e32 v4, v66, v12
	v_mul_f32_e32 v5, v66, v13
	v_mul_f32_e32 v0, v66, v8
	v_mul_f32_e32 v1, v66, v9
	v_mul_f32_e32 v2, v66, v10
	v_mul_f32_e32 v3, v66, v11
	v_mul_f32_e32 v6, v66, v14
	v_mul_f32_e32 v7, v66, v15
	v_cvt_pk_bf16_f32 v0, v0, v1
	v_cvt_pk_bf16_f32 v1, v2, v3
	v_cvt_pk_bf16_f32 v2, v4, v5
	v_cvt_pk_bf16_f32 v3, v6, v7
	v_mul_f32_e32 v4, v66, v52
	v_permlane32_swap_b32_e32 v0, v2
	v_permlane32_swap_b32_e32 v1, v3
	flat_store_dwordx4 v[64:65], v[0:3] offset:32
	v_mul_f32_e32 v5, v66, v53
	v_mul_f32_e32 v6, v66, v54
	v_mul_f32_e32 v0, v66, v48
	v_mul_f32_e32 v1, v66, v49
	v_mul_f32_e32 v2, v66, v50
	v_mul_f32_e32 v3, v66, v51
	v_mul_f32_e32 v7, v66, v55
	v_cvt_pk_bf16_f32 v0, v0, v1
	v_cvt_pk_bf16_f32 v1, v2, v3
	v_cvt_pk_bf16_f32 v2, v4, v5
	v_cvt_pk_bf16_f32 v3, v6, v7
	v_mfma_f32_32x32x16_bf16 v[16:31], v[94:97], v[78:81], v[16:31]
	v_permlane32_swap_b32_e32 v0, v2
	v_permlane32_swap_b32_e32 v1, v3
	flat_store_dwordx4 v[64:65], v[0:3] offset:64
	v_mul_f32_e32 v4, v66, v60
	v_mul_f32_e32 v5, v66, v61
	v_mul_f32_e32 v0, v66, v56
	v_mul_f32_e32 v1, v66, v57
	v_mul_f32_e32 v2, v66, v58
	v_mul_f32_e32 v3, v66, v59
	v_mul_f32_e32 v6, v66, v62
	v_mul_f32_e32 v7, v66, v63
	v_cvt_pk_bf16_f32 v0, v0, v1
	v_cvt_pk_bf16_f32 v1, v2, v3
	v_cvt_pk_bf16_f32 v2, v4, v5
	v_cvt_pk_bf16_f32 v3, v6, v7
	v_mul_f32_e32 v4, v66, v36
	v_permlane32_swap_b32_e32 v0, v2
	v_permlane32_swap_b32_e32 v1, v3
	flat_store_dwordx4 v[64:65], v[0:3] offset:96
	v_mul_f32_e32 v5, v66, v37
	v_mul_f32_e32 v6, v66, v38
	v_mul_f32_e32 v0, v66, v32
	v_mul_f32_e32 v1, v66, v33
	v_mul_f32_e32 v2, v66, v34
	v_mul_f32_e32 v3, v66, v35
	v_mul_f32_e32 v7, v66, v39
	v_cvt_pk_bf16_f32 v0, v0, v1
	v_cvt_pk_bf16_f32 v1, v2, v3
	v_cvt_pk_bf16_f32 v2, v4, v5
	v_cvt_pk_bf16_f32 v3, v6, v7
	v_mul_f32_e32 v4, v66, v44
	v_permlane32_swap_b32_e32 v0, v2
	v_permlane32_swap_b32_e32 v1, v3
	flat_store_dwordx4 v[64:65], v[0:3] offset:128
	v_mul_f32_e32 v5, v66, v45
	v_mul_f32_e32 v6, v66, v46
	v_mul_f32_e32 v0, v66, v40
	v_mul_f32_e32 v1, v66, v41
	v_mul_f32_e32 v2, v66, v42
	v_mul_f32_e32 v3, v66, v43
	v_mul_f32_e32 v7, v66, v47
	v_cvt_pk_bf16_f32 v0, v0, v1
	v_cvt_pk_bf16_f32 v1, v2, v3
	v_cvt_pk_bf16_f32 v2, v4, v5
	v_cvt_pk_bf16_f32 v3, v6, v7
	v_mul_f32_e32 v4, v66, v20
	v_permlane32_swap_b32_e32 v0, v2
	v_permlane32_swap_b32_e32 v1, v3
	flat_store_dwordx4 v[64:65], v[0:3] offset:160
	v_mul_f32_e32 v5, v66, v21
	v_mul_f32_e32 v6, v66, v22
	v_mul_f32_e32 v0, v66, v16
	v_mul_f32_e32 v1, v66, v17
	v_mul_f32_e32 v2, v66, v18
	v_mul_f32_e32 v3, v66, v19
	v_mul_f32_e32 v7, v66, v23
	v_cvt_pk_bf16_f32 v0, v0, v1
	v_cvt_pk_bf16_f32 v1, v2, v3
	v_cvt_pk_bf16_f32 v2, v4, v5
	v_cvt_pk_bf16_f32 v3, v6, v7
	v_mul_f32_e32 v4, v66, v28
	v_permlane32_swap_b32_e32 v0, v2
	v_permlane32_swap_b32_e32 v1, v3
	flat_store_dwordx4 v[64:65], v[0:3] offset:192
	v_mul_f32_e32 v5, v66, v29
	v_mul_f32_e32 v6, v66, v30
	v_mul_f32_e32 v0, v66, v24
	v_mul_f32_e32 v1, v66, v25
	v_mul_f32_e32 v2, v66, v26
	v_mul_f32_e32 v3, v66, v27
	v_mul_f32_e32 v7, v66, v31
	v_cvt_pk_bf16_f32 v0, v0, v1
	v_cvt_pk_bf16_f32 v1, v2, v3
	v_cvt_pk_bf16_f32 v2, v4, v5
	v_cvt_pk_bf16_f32 v3, v6, v7
	s_add_i32 s36, s36, s72
	s_add_i32 s31, s31, s72
	v_permlane32_swap_b32_e32 v0, v2
	v_permlane32_swap_b32_e32 v1, v3
	s_cmpk_gt_i32 s36, 0x1ff
	flat_store_dwordx4 v[64:65], v[0:3] offset:224
	s_setprio 0
	s_waitcnt vmcnt(0) lgkmcnt(0)
	s_barrier
	s_cbranch_scc1 .LBB0_125

; __device__ __forceinline__ void attn_mla_dma(const bf16_t* __restrict__ Qb, const bf16_t* __restrict__ Kh, const bf16_t* __restrict__ Vh, bf16_t* __restrict__ Ob,
;                                              int seq, char* lds, const int tid) {
;     ...
;   const int wid = tid >> 6, lane = tid & 63, r32 = lane & 31, hi = lane >> 5;
;   const int wu = __builtin_amdgcn_readfirstlane(wid);
;   char* V_lds = lds; char* K_lds = lds + 3 * SHM_VV;
;   float* wsl = (float*)(lds + 3 * SHM_VV + 2 * SHM_K) + wid * 64; float* li_l = wsl; float* al_l = wsl + 32;
;   float m_reg = -1e30f, l_reg = 0; f32x16 o[4] = {}; bf16x8 qr[12];
;   const bf16_t* Qw = Qb + (long)(wid * QBLK + r32) * LDQ + hi * 8;
; #pragma unroll
;   for (int d0 = 0; d0 < 12; ++d0) qr[d0] = ld8(Qw + d0 * 16);
;   const char* qlds = nullptr;
;   unsigned kof[3], vof[2];
; #pragma unroll
;   for (int i = 0; i < 3; ++i) { const int ob = (i * 8 + wid) * 1024 + lane * 16, row = ob / 384, within = ob - row * 384;
;     kof[i] = (unsigned)(row * (LDKK * 2) + (within ^ (((row >> 1) & 7) << 4))); }
; #pragma unroll
;   for (int i = 0; i < 2; ++i) { const int ob = (i * 8 + wid) * 1024 + lane * 16, st = ob >> 9, sw = (ob & 511) >> 1;
;     const int kk = (st >> 2) * 8 + (sw >> 5), c = (st & 3) * 32 + (sw & 31);
;     const int k = (kk & ~0xC) | ((kk & 4) << 1) | ((kk & 8) >> 1);
;     vof[i] = (unsigned)(k * (LDV * 2) + c * 2); }
;   const int vb0 = (int)(uintptr_t)V_lds + v_rd_base(lane);
;   int ka[4];
; #pragma unroll
;   for (int q = 0; q < 4; ++q) ka[q] = (int)(uintptr_t)K_lds + r32 * 384 + ((q * 32 + hi * 16) ^ (((r32 >> 1) & 7) << 4));
;     ...
;   f32x16 pA0, pA1, pB0, pB1; float mnA, mnB, alA, alB; bf16x8 pa0, pa1, pa2, pa3; const int NT = seq / KVBLK;
;   DMA_TILE(0, 0, 0); TILE_BAR();
; __global__ __launch_bounds__(512, 2) void mega(Params p) {
;     ...
;       for (int t = blockIdx.x; t < 512; t += gridDim.x) {
;         int bid = t & 255, rnd = t >> 8, h = bid & 7, qbg = (bid >> 3) + 32 * rnd;
;         int b = qbg / nqb_m, qb = qbg % nqb_m;
;         int ttid = tid; asm volatile("" : "+v"(ttid));
;         long tok0 = (long)b * S, q0 = tok0 + (long)qb * 256;
;         attn_mla_dma((const bf16_t*)(ws + O_Q) + q0 * 1536 + h * 192, (const bf16_t*)(ws + O_K) + tok0 * 1536 + h * 192,
;                      (const bf16_t*)(ws + O_V) + tok0 * 1024 + h * 128, (bf16_t*)(ws + O_OMLA) + q0 * 1024 + h * 128, S, shm, ttid);
.Lprio_m:
	s_ashr_i32 s5, s36, 3
	s_bfe_u32 s4, s36, 0x50003
	s_andn2_b32 s5, s5, 31
	s_or_b32 s5, s4, s5
	s_abs_i32 s12, s5
	s_mul_hi_u32 s13, s12, s35
	s_mul_i32 s14, s13, s30
	s_and_b32 s43, s31, 7
	s_ashr_i32 s4, s36, 31
	s_sub_i32 s12, s12, s14
	s_lshl_b32 s47, s43, 8
	s_and_b32 s16, s36, 7
	s_xor_b32 s4, s4, s34
	s_add_i32 s14, s13, 1
	s_sub_i32 s15, s12, s30
	s_cmp_ge_u32 s12, s30
	s_cselect_b32 s13, s14, s13
	s_cselect_b32 s12, s15, s12
	s_add_i32 s14, s13, 1
	s_cmp_ge_u32 s12, s30
	s_cselect_b32 s12, s14, s13
	s_xor_b32 s12, s12, s4
	s_sub_i32 s4, s12, s4
	s_mul_i32 s12, s4, s20
	s_sub_i32 s12, s5, s12
	s_ashr_i32 s5, s4, 31
	s_ashr_i32 s13, s12, 31
	s_lshl_b64 s[14:15], s[4:5], s18
	s_lshl_b64 s[4:5], s[12:13], 8
	s_add_u32 s12, s4, s14
	s_addc_u32 s13, s5, s15
	s_mul_i32 s4, s13, 0xc00
	s_mul_hi_u32 s5, s12, 0xc00
	s_add_i32 s5, s5, s4
	s_mul_i32 s4, s12, 0xc00
	s_add_u32 s4, s21, s4
	s_addc_u32 s5, s23, s5
	s_mul_i32 s17, s16, 0x180
	v_mov_b32_e32 v156, v168
	s_add_u32 s40, s4, s17
	s_addc_u32 s41, s5, 0
	v_ashrrev_i32_e32 v2, 6, v156
	v_and_b32_e32 v4, 31, v156
	v_lshl_or_b32 v5, v2, 5, v4
	v_mov_b64_e32 v[0:1], s[40:41]
	v_mad_i64_i32 v[0:1], s[40:41], v5, s33, v[0:1]
	v_lshrrev_b32_e32 v5, 1, v156
	v_and_b32_e32 v162, 16, v5
	v_lshl_add_u64 v[0:1], v[0:1], 0, v[162:163]
	global_load_dwordx4 v[140:143], v[0:1], off
	global_load_dwordx4 v[136:139], v[0:1], off offset:32
	global_load_dwordx4 v[132:135], v[0:1], off offset:64
	global_load_dwordx4 v[128:131], v[0:1], off offset:96
	global_load_dwordx4 v[124:127], v[0:1], off offset:128
	global_load_dwordx4 v[120:123], v[0:1], off offset:160
	global_load_dwordx4 v[116:119], v[0:1], off offset:192
	global_load_dwordx4 v[112:115], v[0:1], off offset:224
	global_load_dwordx4 v[108:111], v[0:1], off offset:256
	global_load_dwordx4 v[104:107], v[0:1], off offset:288
	global_load_dwordx4 v[100:103], v[0:1], off offset:320
	global_load_dwordx4 v[96:99], v[0:1], off offset:352
	v_and_b32_e32 v3, 63, v156
	v_lshlrev_b32_e32 v0, 10, v2
	v_lshlrev_b32_e32 v68, 4, v3
	v_or_b32_e32 v1, v0, v68
	v_mul_hi_i32 v6, v1, s49
	v_lshrrev_b32_e32 v7, 31, v6
	v_ashrrev_i32_e32 v6, 6, v6
	v_add_u32_e32 v6, v6, v7
	s_movk_i32 s40, 0xfe80
	v_mad_i32_i24 v7, v6, s40, v1
	v_mul_i32_i24_e32 v8, 0xc00, v6
	v_lshlrev_b32_e32 v6, 3, v6
	v_and_b32_e32 v6, 0x70, v6
	v_xad_u32 v188, v7, v6, v8
	v_add_u32_e32 v6, 0x2000, v1
	v_mul_hi_i32 v7, v6, s49
	v_lshrrev_b32_e32 v8, 31, v7
	v_ashrrev_i32_e32 v7, 6, v7
	v_add_u32_e32 v7, v7, v8
	v_mad_i32_i24 v6, v7, s40, v6
	v_mul_i32_i24_e32 v8, 0xc00, v7
	v_lshlrev_b32_e32 v7, 3, v7
	v_and_b32_e32 v7, 0x70, v7
	v_add_u32_e32 v1, 0x4000, v1
	s_mul_i32 s4, s15, 0xc00
	s_mul_hi_u32 s50, s14, 0xc00
	v_xad_u32 v189, v6, v7, v8
	v_mul_hi_i32 v6, v1, s49
	s_add_i32 s50, s50, s4
	s_mul_i32 s70, s14, 0xc00
	v_lshrrev_b32_e32 v7, 31, v6
	v_ashrrev_i32_e32 v6, 6, v6
	s_add_u32 s4, s24, s70
	v_add_u32_e32 v6, v6, v7
	s_addc_u32 s5, s25, s50
	v_mad_i32_i24 v1, v6, s40, v1
	v_mul_i32_i24_e32 v7, 0xc00, v6
	v_lshlrev_b32_e32 v6, 3, v6
	s_add_u32 s4, s4, s17
	v_and_b32_e32 v6, 0x70, v6
	s_addc_u32 s5, s5, 0
	s_lshl_b64 s[14:15], s[14:15], 11
	v_xad_u32 v191, v1, v6, v7
	v_lshlrev_b32_e32 v69, 3, v3
	v_ashrrev_i32_e32 v6, 8, v0
	s_add_u32 s17, s26, s14
	v_bfe_u32 v1, v156, 2, 2
	v_and_b32_e32 v70, 24, v69
	s_movk_i32 s56, 0x60
	v_and_b32_e32 v7, 0x1ffff0, v6
	v_lshrrev_b32_e32 v6, 1, v6
	s_addc_u32 s42, s27, s15
	s_lshl_b32 s37, s16, 7
	s_lshl_b32 s16, s16, 8
	v_and_or_b32 v3, v156, s56, v70
	v_and_or_b32 v1, v5, 8, v1
	v_and_b32_e32 v6, 4, v6
	v_add_u32_e32 v0, 0x2000, v0
	s_add_u32 s16, s17, s16
	v_lshlrev_b32_e32 v3, 1, v3
	v_or3_b32 v6, v7, v6, v1
	v_ashrrev_i32_e32 v0, 8, v0
	s_addc_u32 s17, s42, 0
	v_lshl_or_b32 v194, v6, 11, v3
	v_and_b32_e32 v6, 0x1ffff0, v0
	v_lshrrev_b32_e32 v0, 1, v0
	s_add_i32 s40, 0, 0xc000
	v_and_b32_e32 v0, 4, v0
	s_cmp_lg_u32 s40, -1
	v_or3_b32 v0, v6, v0, v1
	s_cselect_b32 s40, s40, 0
	v_lshl_or_b32 v195, v0, 11, v3
	v_mov_b32_e32 v0, s40
	s_movk_i32 s40, 0x180
	v_mad_u32_u24 v56, v4, s40, v0
	v_readfirstlane_b32 s40, v2
	s_cmp_lg_u32 0, -1
	v_lshlrev_b32_e32 v0, 3, v156
	s_cselect_b32 s44, 0, 0
	s_lshl_b32 s40, s40, 10
	v_and_b32_e32 v57, 0x70, v0
	s_add_i32 s40, s40, 0
	v_bitop3_b32 v0, v5, v57, 16 bitop3:0x6c
	s_add_i32 s41, s40, 0xc000
	v_bfe_u32 v244, v160, 2, 1
	v_bfe_u32 v245, v160, 3, 1
	v_xor_b32_e32 v243, v244, v245
	v_sub_u32_e32 v242, v244, v245
	v_mul_i32_i24_e32 v242, 0x600, v242
	v_mul_u32_u24_e32 v243, 0x60, v243
	v_add_u32_e32 v169, v0, v56
	v_xor_b32_e32 v169, v169, v243
	v_add_u32_e32 v169, v169, v242
	s_mov_b64 s[52:53], s[4:5]
	s_mov_b64 s[54:55], s[16:17]
	v_mov_b32_e32 v0, v189
	v_mov_b32_e32 v1, v194
	v_mov_b32_e32 v2, v188
	v_mov_b32_e32 v3, v191
	v_mov_b32_e32 v4, v195
	s_mov_b32 m0, s41
	s_add_i32 s42, s40, 0xe000
	v_bitop3_b32 v8, v162, v57, 32 bitop3:0x36
	global_load_lds_dwordx4 v2, s[52:53]
	s_mov_b32 m0, s42
	v_add_u32_e32 v190, v8, v56
	v_xor_b32_e32 v190, v190, v243
	v_add_u32_e32 v190, v190, v242
	global_load_lds_dwordx4 v0, s[52:53]
	s_add_i32 m0, s40, 0x10000
	v_bitop3_b32 v48, v162, v57, 64 bitop3:0x36
	global_load_lds_dwordx4 v3, s[52:53]
	s_mov_b32 m0, s40
	v_add_u32_e32 v193, v48, v56
	v_xor_b32_e32 v193, v193, v243
	v_add_u32_e32 v193, v193, v242
	global_load_lds_dwordx4 v1, s[54:55]
	s_add_i32 m0, s40, 0x2000
	v_bitop3_b32 v57, v162, v57, s56 bitop3:0x36
	global_load_lds_dwordx4 v4, s[54:55]
	s_waitcnt vmcnt(0) lgkmcnt(0)
	s_barrier
; #define TILE_BAR() do { asm volatile("s_waitcnt vmcnt(0) lgkmcnt(0)" ::: "memory"); __builtin_amdgcn_s_barrier(); } while (0)
; #define TILE_BAR() do { asm volatile("s_waitcnt vmcnt(0) lgkmcnt(0)" ::: "memory"); __builtin_amdgcn_s_barrier(); } while (0)
; template <int MLA>
; __device__ __forceinline__ void partialSM(f32x16& p0, f32x16& p1, float& m_reg, float& mn, float& alpha) {
;   constexpr float SCALE = AttC<MLA>::SCALE;
;   constexpr float C = SCALE * 1.4426950408889634f;
;   float pmax = p0[0];
; #pragma unroll
;   for (int r = 1; r < 16; ++r) pmax = fmaxf(pmax, p0[r]);
; #pragma unroll
;   for (int r = 0; r < 16; ++r) pmax = fmaxf(pmax, p1[r]);
;   { auto rr = __builtin_amdgcn_permlane32_swap(__float_as_uint(pmax), __float_as_uint(pmax), false, false);
;     pmax = fmaxf(__uint_as_float(rr[0]), __uint_as_float(rr[1])); }
;   if (__builtin_expect(__all(pmax - m_reg <= THR / SCALE), 1)) { mn = m_reg; alpha = 1.f; }
;   else { mn = fmaxf(m_reg, pmax); alpha = __builtin_amdgcn_exp2f((m_reg - mn) * C); m_reg = mn; }
;   float mnC = -mn * C;
; #pragma unroll
;   for (int r = 0; r < 16; ++r) p0[r] = fmaf(p0[r], C, mnC);
; #pragma unroll
;   for (int r = 0; r < 16; ++r) p1[r] = fmaf(p1[r], C, mnC);
; #pragma unroll
;   for (int r = 0; r < 16; ++r) p0[r] = __builtin_amdgcn_exp2f(p0[r]);
; }
; __device__ __forceinline__ void attn_mla_dma(const bf16_t* __restrict__ Qb, const bf16_t* __restrict__ Kh, const bf16_t* __restrict__ Vh, bf16_t* __restrict__ Ob,
;                                              int seq, char* lds, const int tid) {
;     ...
;   DMA_TILE(0, 0, 0); TILE_BAR();
;   qkt_mla<0>(pA0, pA1, ka, qr, qlds); partialSM<MLA>(pA0, pA1, m_reg, mnA, alA);
;   DMA_TILE(KVBLK, 1, 1); TILE_BAR();
	ds_read_b128 v[0:3], v169
	ds_read_b128 v[4:7], v169 offset:128
	s_waitcnt vmcnt(0) lgkmcnt(0)
	v_mfma_f32_32x32x16_bf16 v[16:31], v[0:3], v[140:143], 0
	ds_read_b128 v[0:3], v169 offset:12288
	ds_read_b128 v[8:11], v169 offset:256
	v_add_u32_e32 v192, v57, v56
	v_xor_b32_e32 v192, v192, v243
	v_add_u32_e32 v192, v192, v242
	s_mov_b32 s52, 0
	s_mov_b32 s53, s52
	s_add_u32 s4, s4, 0x30000
	s_mov_b32 s54, s52
	s_waitcnt lgkmcnt(1)
	v_mfma_f32_32x32x16_bf16 v[32:47], v[0:3], v[140:143], 0
	ds_read_b128 v[0:3], v190
	ds_read_b128 v[12:15], v190 offset:128
	ds_read_b128 v[48:51], v190 offset:256
	s_mov_b32 s55, s52
	s_mov_b32 s56, s52
	s_mov_b32 s57, s52
	s_mov_b32 s58, s52
	s_mov_b32 s59, s52
	s_waitcnt lgkmcnt(2)
	v_mfma_f32_32x32x16_bf16 v[16:31], v[0:3], v[136:139], v[16:31]
	ds_read_b128 v[0:3], v190 offset:12288
	s_mov_b32 s60, s52
	s_mov_b32 s61, s52
	s_mov_b32 s62, s52
	s_mov_b32 s63, s52
	s_mov_b32 s64, s52
	s_mov_b32 s65, s52
	s_waitcnt lgkmcnt(0)
	v_mfma_f32_32x32x16_bf16 v[32:47], v[0:3], v[136:139], v[32:47]
	ds_read_b128 v[0:3], v193
	ds_read_b128 v[52:55], v193 offset:128
	ds_read_b128 v[56:59], v193 offset:256
	s_mov_b32 s66, s52
	s_mov_b32 s67, s52
	s_addc_u32 s5, s5, 0
	s_mov_b32 s73, 0x4138aa3b
	s_mul_i32 s74, s43, 0x180
	s_waitcnt lgkmcnt(2)
	v_mfma_f32_32x32x16_bf16 v[16:31], v[0:3], v[132:135], v[16:31]
	ds_read_b128 v[0:3], v193 offset:12288
	s_mov_b32 s43, 1
	v_mov_b32_e32 v162, 0
	s_waitcnt lgkmcnt(0)
	v_mfma_f32_32x32x16_bf16 v[32:47], v[0:3], v[132:135], v[32:47]
	ds_read_b128 v[0:3], v192
	ds_read_b128 v[60:63], v192 offset:128
	s_waitcnt lgkmcnt(1)
	v_mfma_f32_32x32x16_bf16 v[16:31], v[0:3], v[128:131], v[16:31]
	ds_read_b128 v[0:3], v192 offset:12288
	ds_read_b128 v[64:67], v192 offset:256
	v_mfma_f32_32x32x16_bf16 v[16:31], v[4:7], v[124:127], v[16:31]
	v_mfma_f32_32x32x16_bf16 v[16:31], v[12:15], v[120:123], v[16:31]
	s_waitcnt lgkmcnt(1)
	v_mfma_f32_32x32x16_bf16 v[32:47], v[0:3], v[128:131], v[32:47]
	ds_read_b128 v[0:3], v169 offset:12416
	ds_read_b128 v[4:7], v169 offset:12544
	v_mfma_f32_32x32x16_bf16 v[16:31], v[52:55], v[116:119], v[16:31]
	s_waitcnt lgkmcnt(1)
	v_mfma_f32_32x32x16_bf16 v[32:47], v[0:3], v[124:127], v[32:47]
	ds_read_b128 v[0:3], v190 offset:12416
	ds_read_b128 v[12:15], v190 offset:12544
	v_mfma_f32_32x32x16_bf16 v[16:31], v[60:63], v[112:115], v[16:31]
	s_waitcnt lgkmcnt(1)
	v_mfma_f32_32x32x16_bf16 v[32:47], v[0:3], v[120:123], v[32:47]
	ds_read_b128 v[0:3], v193 offset:12416
	ds_read_b128 v[52:55], v193 offset:12544
	v_mfma_f32_32x32x16_bf16 v[16:31], v[8:11], v[108:111], v[16:31]
	s_waitcnt lgkmcnt(1)
	v_mfma_f32_32x32x16_bf16 v[32:47], v[0:3], v[116:119], v[32:47]
	ds_read_b128 v[0:3], v192 offset:12416
	ds_read_b128 v[60:63], v192 offset:12544
	v_mfma_f32_32x32x16_bf16 v[16:31], v[48:51], v[104:107], v[16:31]
	v_mov_b32_e32 v50, v191
	v_mov_b32_e32 v51, v195
	s_waitcnt lgkmcnt(1)
	v_mfma_f32_32x32x16_bf16 v[32:47], v[0:3], v[112:115], v[32:47]
	v_lshlrev_b32_e32 v0, 1, v156
	v_and_b32_e32 v0, 32, v0
	v_and_or_b32 v0, v68, s48, v0
	v_and_b32_e32 v1, 0x100, v69
	v_or3_b32 v0, v0, v1, v70
	v_add_u32_e32 v167, s44, v0
	v_mfma_f32_32x32x16_bf16 v[16:31], v[56:59], v[100:103], v[16:31]
	v_mfma_f32_32x32x16_bf16 v[32:47], v[4:7], v[108:111], v[32:47]
	v_mfma_f32_32x32x16_bf16 v[16:31], v[64:67], v[96:99], v[16:31]
	v_mfma_f32_32x32x16_bf16 v[32:47], v[12:15], v[104:107], v[32:47]
	v_mov_b64_e32 v[0:1], s[52:53]
	v_mov_b64_e32 v[2:3], s[54:55]
	v_mov_b64_e32 v[4:5], s[56:57]
	v_mov_b64_e32 v[6:7], s[58:59]
	v_mov_b64_e32 v[8:9], s[60:61]
	v_mov_b64_e32 v[10:11], s[62:63]
	v_mov_b64_e32 v[12:13], s[64:65]
	v_mov_b64_e32 v[14:15], s[66:67]
	s_add_u32 s54, s16, 0x20000
	s_nop 1
	v_max_f32_e32 v48, v17, v17
	v_max_f32_e32 v49, v16, v16
	s_addc_u32 s55, s17, 0
	s_add_i32 s16, s40, 0x12000
	v_mfma_f32_32x32x16_bf16 v[32:47], v[52:55], v[100:103], v[32:47]
	v_max_f32_e32 v48, v49, v48
	v_mov_b32_e32 v49, v188
	v_mov_b32_e32 v52, v189
	v_mov_b32_e32 v53, v194
	s_mov_b32 m0, s16
	s_add_i32 s17, s40, 0x14000
	s_add_i32 s44, s40, 0x16000
	global_load_lds_dwordx4 v49, s[4:5]
	s_mov_b32 m0, s17
	s_add_i32 s53, s40, 0x4000
	global_load_lds_dwordx4 v52, s[4:5]
	s_mov_b32 m0, s44
	s_waitcnt lgkmcnt(0)
	v_mfma_f32_32x32x16_bf16 v[32:47], v[60:63], v[96:99], v[32:47]
	global_load_lds_dwordx4 v50, s[4:5]
	s_mov_b32 m0, s53
	v_max3_f32 v48, v48, v18, v19
	global_load_lds_dwordx4 v53, s[54:55]
	s_add_i32 m0, s40, 0x6000
	v_max3_f32 v48, v48, v20, v21
	global_load_lds_dwordx4 v51, s[54:55]
	v_max3_f32 v48, v48, v22, v23
	v_max3_f32 v48, v48, v24, v25
	v_max3_f32 v48, v48, v26, v27
	v_max3_f32 v48, v48, v28, v29
	v_max3_f32 v48, v48, v30, v31
	v_max3_f32 v48, v48, v32, v33
	v_max3_f32 v48, v48, v34, v35
	v_max3_f32 v48, v48, v36, v37
	v_max3_f32 v48, v48, v38, v39
	v_max3_f32 v48, v48, v40, v41
	v_max3_f32 v48, v48, v42, v43
	v_max3_f32 v48, v48, v44, v45
	v_max3_f32 v48, v48, v46, v47
	v_mov_b32_e32 v49, v48
	s_nop 1
	v_permlane32_swap_b32_e32 v48, v49
	v_max_f32_e32 v49, v49, v49
	v_max_f32_e32 v48, v48, v48
	v_max_f32_e32 v48, v48, v49
	v_add_f32_e32 v49, 0x7149f2ca, v48
	v_cmp_ge_f32_e32 vcc, s73, v49
	s_cmp_eq_u64 vcc, exec
	v_max_f32_e32 v49, 0xf149f2ca, v48
	s_cselect_b64 vcc, -1, 0
	v_cndmask_b32_e32 v197, v49, v183, vcc
	v_mul_f32_e32 v48, 0xbf800000, v197
	v_fmamk_f32 v16, v16, 0x3f800000, v48
	v_exp_f32_e32 v145, v16
	v_fmamk_f32 v16, v17, 0x3f800000, v48
	v_exp_f32_e32 v210, v16
	v_fmamk_f32 v16, v18, 0x3f800000, v48
	v_exp_f32_e32 v208, v16
	v_fmamk_f32 v16, v19, 0x3f800000, v48
	v_exp_f32_e32 v212, v16
	v_fmamk_f32 v16, v20, 0x3f800000, v48
	v_exp_f32_e32 v211, v16
	v_fmamk_f32 v16, v21, 0x3f800000, v48
	v_exp_f32_e32 v213, v16
	v_fmamk_f32 v16, v22, 0x3f800000, v48
	v_exp_f32_e32 v207, v16
	v_fmamk_f32 v16, v23, 0x3f800000, v48
	v_exp_f32_e32 v209, v16
	v_fmamk_f32 v16, v24, 0x3f800000, v48
	v_exp_f32_e32 v200, v16
	v_fmamk_f32 v16, v25, 0x3f800000, v48
	v_exp_f32_e32 v203, v16
	v_fmamk_f32 v16, v26, 0x3f800000, v48
	v_exp_f32_e32 v202, v16
	v_fmamk_f32 v16, v27, 0x3f800000, v48
	v_exp_f32_e32 v205, v16
	v_fmamk_f32 v16, v28, 0x3f800000, v48
	v_sub_f32_e32 v17, 0xf149f2ca, v49
	v_exp_f32_e32 v199, v16
	v_fmamk_f32 v16, v29, 0x3f800000, v48
	v_mul_f32_e32 v17, 0x3f800000, v17
	v_exp_f32_e32 v201, v16
	v_fmamk_f32 v16, v30, 0x3f800000, v48
	v_exp_f32_e32 v17, v17
	v_exp_f32_e32 v204, v16
	v_fmamk_f32 v16, v31, 0x3f800000, v48
	v_exp_f32_e32 v206, v16
	s_waitcnt vmcnt(0) lgkmcnt(0)
; #define SBAR() __builtin_amdgcn_sched_barrier(0)
; __device__ __forceinline__ void finishSM(f32x16& p0, f32x16& p1, float alpha, float& l_reg, bf16x8& pa0, bf16x8& pa1, bf16x8& pa2, bf16x8& pa3) {
; #pragma unroll
;   for (int r = 0; r < 16; ++r) p1[r] = __builtin_amdgcn_exp2f(p1[r]);
;   float ps = 0;
; #pragma unroll
;   for (int r = 0; r < 16; ++r) ps += p0[r];
; #pragma unroll
;   for (int r = 0; r < 16; ++r) ps += p1[r];
;   { auto rr = __builtin_amdgcn_permlane32_swap(__float_as_uint(ps), __float_as_uint(ps), false, false);
;     ps = __uint_as_float(rr[0]) + __uint_as_float(rr[1]); }
;   l_reg = l_reg * alpha + ps;
; __device__ __forceinline__ void attn_mla_dma(const bf16_t* __restrict__ Qb, const bf16_t* __restrict__ Kh, const bf16_t* __restrict__ Vh, bf16_t* __restrict__ Ob,
;                                              int seq, char* lds, const int tid) {
;     ...
;   for (int j = 1; j + 1 < NT; j += 2) {
;     SBAR(); qkt_mla<(int)SHM_K192>(pB0, pB1, ka, qr, qlds);
;     finishSM(pA0, pA1, alA, l_reg, pa0, pa1, pa2, pa3); SBAR();
;     DMA_TILE((j + 1) * KVBLK, 0, vnxt); SBAR();
;     pv_d0_t(o, vb0 + vprev * SHM_VV, pa0, pa1, pa2, pa3); partialSM<MLA>(pB0, pB1, m_reg, mnB, alB);
	s_mov_b32 s4, 0x3f800000
	s_or_b32 s14, s14, s47
	v_cndmask_b32_e64 v198, v17, 1.0, vcc
	v_pk_fma_f32 v[154:155], v[46:47], s[4:5], v[48:49] op_sel_hi:[1,0,0]
	v_pk_fma_f32 v[146:147], v[44:45], s[4:5], v[48:49] op_sel_hi:[1,0,0]
	v_pk_fma_f32 v[148:149], v[42:43], s[4:5], v[48:49] op_sel_hi:[1,0,0]
	v_pk_fma_f32 v[150:151], v[40:41], s[4:5], v[48:49] op_sel_hi:[1,0,0]
	v_pk_fma_f32 v[152:153], v[38:39], s[4:5], v[48:49] op_sel_hi:[1,0,0]
	v_pk_fma_f32 v[158:159], v[36:37], s[4:5], v[48:49] op_sel_hi:[1,0,0]
	v_pk_fma_f32 v[170:171], v[34:35], s[4:5], v[48:49] op_sel_hi:[1,0,0]
	v_pk_fma_f32 v[172:173], v[32:33], s[4:5], v[48:49] op_sel_hi:[1,0,0]
	s_add_u32 s47, s70, s74
	v_mov_b64_e32 v[62:63], v[14:15]
	v_mov_b64_e32 v[46:47], v[14:15]
	v_mov_b64_e32 v[30:31], v[14:15]
	v_readlane_b32 s73, v249, 57
	s_mov_b32 s63, 0x4138aa3b
	s_addc_u32 s50, s50, 0
	s_mov_b32 s53, 2
	v_mov_b64_e32 v[60:61], v[12:13]
	v_mov_b64_e32 v[58:59], v[10:11]
	v_mov_b64_e32 v[56:57], v[8:9]
	v_mov_b64_e32 v[54:55], v[6:7]
	v_mov_b64_e32 v[52:53], v[4:5]
	v_mov_b64_e32 v[50:51], v[2:3]
	v_mov_b64_e32 v[48:49], v[0:1]
	v_mov_b64_e32 v[44:45], v[12:13]
	v_mov_b64_e32 v[42:43], v[10:11]
	v_mov_b64_e32 v[40:41], v[8:9]
	v_mov_b64_e32 v[38:39], v[6:7]
	v_mov_b64_e32 v[36:37], v[4:5]
	v_mov_b64_e32 v[34:35], v[2:3]
	v_mov_b64_e32 v[32:33], v[0:1]
	s_mov_b32 s54, 2
	v_mov_b64_e32 v[28:29], v[12:13]
	v_mov_b64_e32 v[26:27], v[10:11]
	v_mov_b64_e32 v[24:25], v[8:9]
	v_mov_b64_e32 v[22:23], v[6:7]
	v_mov_b64_e32 v[20:21], v[4:5]
	v_mov_b64_e32 v[18:19], v[2:3]
	v_mov_b64_e32 v[16:17], v[0:1]
	v_exp_f32_e32 v146, v146
	v_exp_f32_e32 v147, v147
	v_exp_f32_e32 v148, v148
	v_exp_f32_e32 v149, v149
	v_exp_f32_e32 v150, v150
	v_exp_f32_e32 v151, v151
	v_exp_f32_e32 v152, v152
	v_exp_f32_e32 v153, v153
	v_exp_f32_e32 v154, v154
	v_exp_f32_e32 v155, v155
	v_exp_f32_e32 v158, v158
	v_exp_f32_e32 v159, v159
	v_exp_f32_e32 v170, v170
	v_exp_f32_e32 v171, v171
	v_exp_f32_e32 v172, v172
	v_exp_f32_e32 v173, v173
	v_sub_f32_e32 v226, 0, v197
	v_sub_f32_e32 v227, 0, v197
	v_sub_f32_e32 v228, 0, v197
	v_sub_f32_e32 v229, 0, v197
	v_sub_f32_e32 v230, 0, v197
	v_sub_f32_e32 v231, 0, v197
	v_sub_f32_e32 v232, 0, v197
	v_sub_f32_e32 v233, 0, v197
	v_sub_f32_e32 v234, 0, v197
	v_sub_f32_e32 v235, 0, v197
	v_sub_f32_e32 v236, 0, v197
	v_sub_f32_e32 v237, 0, v197
	v_sub_f32_e32 v238, 0, v197
	v_sub_f32_e32 v239, 0, v197
	v_sub_f32_e32 v240, 0, v197
	v_sub_f32_e32 v241, 0, v197
	s_barrier
.LBB0_115:
	s_mov_b32 s55, s43
	s_mov_b32 s43, s52
	ds_read_b128 v[64:67], v169 offset:24576
	ds_read_b128 v[68:71], v169 offset:36864
	ds_read_b128 v[214:217], v190 offset:24576
	ds_read_b128 v[218:221], v190 offset:36864
	v_add_f32_e32 v144, v210, v145
	s_waitcnt lgkmcnt(0)
	v_mfma_f32_32x32x16_bf16 v[80:95], v[64:67], v[140:143], v[226:241]
	v_add_f32_e32 v144, v208, v144
	v_add_f32_e32 v144, v212, v144
	v_add_f32_e32 v144, v211, v144
	v_add_f32_e32 v144, v213, v144
	v_add_f32_e32 v144, v207, v144
	v_add_f32_e32 v144, v209, v144
	v_add_f32_e32 v144, v200, v144
	v_mfma_f32_32x32x16_bf16 v[64:79], v[68:71], v[140:143], v[226:241]
	v_add_f32_e32 v144, v203, v144
	v_add_f32_e32 v144, v202, v144
	v_add_f32_e32 v144, v205, v144
	v_add_f32_e32 v144, v199, v144
	v_add_f32_e32 v144, v201, v144
	v_mfma_f32_32x32x16_bf16 v[80:95], v[214:217], v[136:139], v[80:95]
	v_add_f32_e32 v144, v204, v144
	v_add_f32_e32 v144, v206, v144
	v_mov_b32_e32 v196, v158
	v_add_f32_e32 v144, v172, v144
	v_add_f32_e32 v144, v173, v144
	v_mfma_f32_32x32x16_bf16 v[64:79], v[218:221], v[136:139], v[64:79]
	ds_read_b128 v[214:217], v193 offset:24576
	ds_read_b128 v[218:221], v193 offset:36864
	v_add_f32_e32 v144, v170, v144
	v_add_f32_e32 v144, v171, v144
	v_add_f32_e32 v144, v196, v144
	v_mov_b32_e32 v222, v147
	v_mov_b32_e32 v223, v154
	v_mov_b32_e32 v224, v155
	s_waitcnt lgkmcnt(0)
	v_mfma_f32_32x32x16_bf16 v[80:95], v[214:217], v[132:135], v[80:95]
	v_mfma_f32_32x32x16_bf16 v[64:79], v[218:221], v[132:135], v[64:79]
	ds_read_b128 v[214:217], v192 offset:24576
	ds_read_b128 v[218:221], v192 offset:36864
	s_waitcnt lgkmcnt(0)
	v_mfma_f32_32x32x16_bf16 v[80:95], v[214:217], v[128:131], v[80:95]
	v_mfma_f32_32x32x16_bf16 v[64:79], v[218:221], v[128:131], v[64:79]
	ds_read_b128 v[214:217], v169 offset:24704
	ds_read_b128 v[218:221], v169 offset:36992
	s_waitcnt lgkmcnt(0)
	v_mfma_f32_32x32x16_bf16 v[80:95], v[214:217], v[124:127], v[80:95]
	v_mfma_f32_32x32x16_bf16 v[64:79], v[218:221], v[124:127], v[64:79]
	ds_read_b128 v[214:217], v190 offset:24704
	ds_read_b128 v[218:221], v190 offset:36992
	s_waitcnt lgkmcnt(0)
	v_mfma_f32_32x32x16_bf16 v[80:95], v[214:217], v[120:123], v[80:95]
	v_mfma_f32_32x32x16_bf16 v[64:79], v[218:221], v[120:123], v[64:79]
	ds_read_b128 v[214:217], v193 offset:24704
	ds_read_b128 v[218:221], v193 offset:36992
	s_waitcnt lgkmcnt(0)
	v_mfma_f32_32x32x16_bf16 v[80:95], v[214:217], v[116:119], v[80:95]
	v_mfma_f32_32x32x16_bf16 v[64:79], v[218:221], v[116:119], v[64:79]
	ds_read_b128 v[214:217], v192 offset:24704
	ds_read_b128 v[218:221], v192 offset:36992
	s_waitcnt lgkmcnt(0)
	v_mfma_f32_32x32x16_bf16 v[80:95], v[214:217], v[112:115], v[80:95]
	v_mfma_f32_32x32x16_bf16 v[64:79], v[218:221], v[112:115], v[64:79]
	ds_read_b128 v[214:217], v169 offset:24832
	ds_read_b128 v[218:221], v169 offset:37120
	s_waitcnt lgkmcnt(0)
	v_mfma_f32_32x32x16_bf16 v[80:95], v[214:217], v[108:111], v[80:95]
	v_mfma_f32_32x32x16_bf16 v[64:79], v[218:221], v[108:111], v[64:79]
	ds_read_b128 v[214:217], v190 offset:24832
	ds_read_b128 v[218:221], v190 offset:37120
	s_waitcnt lgkmcnt(0)
; #define SBAR() __builtin_amdgcn_sched_barrier(0)
; #define TILE_BAR() do { asm volatile("s_waitcnt vmcnt(0) lgkmcnt(0)" ::: "memory"); __builtin_amdgcn_s_barrier(); } while (0)
; #define TILE_BAR() do { asm volatile("s_waitcnt vmcnt(0) lgkmcnt(0)" ::: "memory"); __builtin_amdgcn_s_barrier(); } while (0)
; template <int MLA>
; __device__ __forceinline__ void partialSM(f32x16& p0, f32x16& p1, float& m_reg, float& mn, float& alpha) {
;   constexpr float SCALE = AttC<MLA>::SCALE;
;   constexpr float C = SCALE * 1.4426950408889634f;
;   float pmax = p0[0];
; #pragma unroll
;   for (int r = 1; r < 16; ++r) pmax = fmaxf(pmax, p0[r]);
; #pragma unroll
;   for (int r = 0; r < 16; ++r) pmax = fmaxf(pmax, p1[r]);
;   { auto rr = __builtin_amdgcn_permlane32_swap(__float_as_uint(pmax), __float_as_uint(pmax), false, false);
;     pmax = fmaxf(__uint_as_float(rr[0]), __uint_as_float(rr[1])); }
;   if (__builtin_expect(__all(pmax - m_reg <= THR / SCALE), 1)) { mn = m_reg; alpha = 1.f; }
;   else { mn = fmaxf(m_reg, pmax); alpha = __builtin_amdgcn_exp2f((m_reg - mn) * C); m_reg = mn; }
; __device__ __forceinline__ void attn_mla_dma(const bf16_t* __restrict__ Qb, const bf16_t* __restrict__ Kh, const bf16_t* __restrict__ Vh, bf16_t* __restrict__ Ob,
;                                              int seq, char* lds, const int tid) {
;     ...
;   for (int j = 1; j + 1 < NT; j += 2) {
;     SBAR(); qkt_mla<(int)SHM_K192>(pB0, pB1, ka, qr, qlds);
;     finishSM(pA0, pA1, alA, l_reg, pa0, pa1, pa2, pa3); SBAR();
;     DMA_TILE((j + 1) * KVBLK, 0, vnxt); SBAR();
;     pv_d0_t(o, vb0 + vprev * SHM_VV, pa0, pa1, pa2, pa3); partialSM<MLA>(pB0, pB1, m_reg, mnB, alB);
;     TILE_BAR();
	v_mfma_f32_32x32x16_bf16 v[80:95], v[214:217], v[104:107], v[80:95]
	v_mfma_f32_32x32x16_bf16 v[64:79], v[218:221], v[104:107], v[64:79]
	ds_read_b128 v[214:217], v193 offset:24832
	ds_read_b128 v[218:221], v193 offset:37120
	s_waitcnt lgkmcnt(0)
	v_mfma_f32_32x32x16_bf16 v[80:95], v[214:217], v[100:103], v[80:95]
	v_mfma_f32_32x32x16_bf16 v[64:79], v[218:221], v[100:103], v[64:79]
	ds_read_b128 v[214:217], v192 offset:24832
	ds_read_b128 v[218:221], v192 offset:37120
	s_waitcnt lgkmcnt(0)
	v_mfma_f32_32x32x16_bf16 v[80:95], v[214:217], v[96:99], v[80:95]
	v_mov_b32_e32 v214, v159
	v_mov_b32_e32 v215, v152
	v_mov_b32_e32 v216, v153
	v_mov_b32_e32 v217, v150
	v_add_f32_e32 v144, v214, v144
	v_add_f32_e32 v144, v215, v144
	v_add_f32_e32 v144, v216, v144
	v_mfma_f32_32x32x16_bf16 v[64:79], v[218:221], v[96:99], v[64:79]
	v_mov_b32_e32 v218, v151
	v_mov_b32_e32 v219, v148
	v_mov_b32_e32 v220, v149
	v_mov_b32_e32 v221, v146
	v_add_f32_e32 v144, v217, v144
	v_add_f32_e32 v144, v218, v144
	v_add_f32_e32 v144, v219, v144
	v_add_f32_e32 v144, v220, v144
	v_add_f32_e32 v144, v221, v144
	v_add_f32_e32 v144, v222, v144
	v_add_f32_e32 v144, v223, v144
	v_add_f32_e32 v158, v224, v144
	v_mov_b32_e32 v159, v158
	v_cvt_pk_bf16_f32 v144, v145, v210
	v_cvt_pk_bf16_f32 v145, v208, v212
	v_cvt_pk_bf16_f32 v146, v211, v213
	v_cvt_pk_bf16_f32 v147, v207, v209
	v_cvt_pk_bf16_f32 v148, v200, v203
	v_cvt_pk_bf16_f32 v149, v202, v205
	v_cvt_pk_bf16_f32 v150, v199, v201
	v_cvt_pk_bf16_f32 v151, v204, v206
	v_cvt_pk_bf16_f32 v152, v172, v173
	v_cvt_pk_bf16_f32 v153, v170, v171
	v_cvt_pk_bf16_f32 v154, v196, v214
	s_nop 1
	v_permlane32_swap_b32_e32 v158, v159
	v_cvt_pk_bf16_f32 v155, v215, v216
	v_cvt_pk_bf16_f32 v170, v217, v218
	v_cvt_pk_bf16_f32 v171, v219, v220
	v_cvt_pk_bf16_f32 v172, v221, v222
	v_cvt_pk_bf16_f32 v173, v223, v224
	v_readlane_b32 s58, v249, 37
	v_readlane_b32 s59, v249, 38
	s_add_u32 s56, s58, s47
	s_addc_u32 s57, s59, s50
	s_add_u32 s4, s56, 0x17060000
	s_addc_u32 s5, s57, 0
	s_add_u32 s58, s58, s14
	s_addc_u32 s59, s59, s15
	s_add_u32 s60, s58, 0x1a040000
	s_mov_b32 m0, s41
	s_addc_u32 s61, s59, 0
	s_lshl_b32 s52, s54, 14
	s_add_i32 s62, s40, s52
	global_load_lds_dwordx4 v188, s[4:5]
	s_mov_b32 m0, s42
	s_nop 0
	global_load_lds_dwordx4 v189, s[4:5]
	s_add_i32 m0, s41, 0x4000
	s_nop 0
	global_load_lds_dwordx4 v191, s[4:5]
	s_mov_b32 m0, s62
	s_nop 0
	global_load_lds_dwordx4 v194, s[60:61]
	s_add_i32 m0, s62, 0x2000
	s_nop 0
	global_load_lds_dwordx4 v195, s[60:61]
	s_lshl_b32 s60, s43, 14
	v_add_u32_e32 v196, s60, v167
	ds_read_b64_tr_b16 v[200:201], v196 offset:0
	ds_read_b64_tr_b16 v[202:203], v196 offset:0x800
	ds_read_b64_tr_b16 v[204:205], v196 offset:0x1000
	ds_read_b64_tr_b16 v[206:207], v196 offset:0x1800
	ds_read_b64_tr_b16 v[208:209], v196 offset:0x2000
	ds_read_b64_tr_b16 v[210:211], v196 offset:0x2800
	ds_read_b64_tr_b16 v[212:213], v196 offset:0x3000
	ds_read_b64_tr_b16 v[214:215], v196 offset:0x3800
	s_waitcnt lgkmcnt(0)
	s_nop 0
	v_mfma_f32_32x32x16_bf16 v[0:15], v[200:203], v[144:147], v[0:15]
	ds_read_b64_tr_b16 v[200:201], v196 offset:0x200
	ds_read_b64_tr_b16 v[202:203], v196 offset:0xa00
	v_mfma_f32_32x32x16_bf16 v[0:15], v[204:207], v[148:151], v[0:15]
	ds_read_b64_tr_b16 v[204:205], v196 offset:0x1200
	ds_read_b64_tr_b16 v[206:207], v196 offset:0x1a00
	v_mfma_f32_32x32x16_bf16 v[0:15], v[208:211], v[152:155], v[0:15]
	ds_read_b64_tr_b16 v[208:209], v196 offset:0x2200
	ds_read_b64_tr_b16 v[210:211], v196 offset:0x2a00
	v_mfma_f32_32x32x16_bf16 v[0:15], v[212:215], v[170:173], v[0:15]
	ds_read_b64_tr_b16 v[212:213], v196 offset:0x3200
	ds_read_b64_tr_b16 v[214:215], v196 offset:0x3a00
	s_waitcnt lgkmcnt(0)
	v_mfma_f32_32x32x16_bf16 v[48:63], v[200:203], v[144:147], v[48:63]
	ds_read_b64_tr_b16 v[200:201], v196 offset:0x400
	ds_read_b64_tr_b16 v[202:203], v196 offset:0xc00
	v_mfma_f32_32x32x16_bf16 v[48:63], v[204:207], v[148:151], v[48:63]
	ds_read_b64_tr_b16 v[204:205], v196 offset:0x1400
	ds_read_b64_tr_b16 v[206:207], v196 offset:0x1c00
	v_mfma_f32_32x32x16_bf16 v[48:63], v[208:211], v[152:155], v[48:63]
	ds_read_b64_tr_b16 v[208:209], v196 offset:0x2400
	ds_read_b64_tr_b16 v[210:211], v196 offset:0x2c00
	v_mfma_f32_32x32x16_bf16 v[48:63], v[212:215], v[170:173], v[48:63]
	ds_read_b64_tr_b16 v[212:213], v196 offset:0x3400
	ds_read_b64_tr_b16 v[214:215], v196 offset:0x3c00
	s_waitcnt lgkmcnt(0)
	v_mfma_f32_32x32x16_bf16 v[32:47], v[200:203], v[144:147], v[32:47]
	ds_read_b64_tr_b16 v[200:201], v196 offset:0x600
	ds_read_b64_tr_b16 v[202:203], v196 offset:0xe00
	v_mfma_f32_32x32x16_bf16 v[32:47], v[204:207], v[148:151], v[32:47]
	ds_read_b64_tr_b16 v[204:205], v196 offset:0x1600
	ds_read_b64_tr_b16 v[206:207], v196 offset:0x1e00
	v_mfma_f32_32x32x16_bf16 v[32:47], v[208:211], v[152:155], v[32:47]
	ds_read_b64_tr_b16 v[208:209], v196 offset:0x2600
	ds_read_b64_tr_b16 v[210:211], v196 offset:0x2e00
	v_mfma_f32_32x32x16_bf16 v[32:47], v[212:215], v[170:173], v[32:47]
	ds_read_b64_tr_b16 v[212:213], v196 offset:0x3600
	ds_read_b64_tr_b16 v[214:215], v196 offset:0x3e00
	s_waitcnt lgkmcnt(0)
	v_mfma_f32_32x32x16_bf16 v[16:31], v[200:203], v[144:147], v[16:31]
	v_max_f32_e32 v144, v80, v81
	v_max3_f32 v144, v144, v82, v83
	v_max3_f32 v144, v144, v84, v85
	v_max3_f32 v144, v144, v86, v87
	v_max3_f32 v144, v144, v88, v89
	v_max3_f32 v144, v144, v90, v91
	v_max3_f32 v144, v144, v92, v93
	v_mfma_f32_32x32x16_bf16 v[16:31], v[204:207], v[148:151], v[16:31]
	v_max3_f32 v144, v144, v94, v95
	v_max3_f32 v144, v144, v64, v65
	v_max3_f32 v144, v144, v66, v67
	v_max3_f32 v144, v144, v68, v69
	v_max3_f32 v144, v144, v70, v71
	v_max3_f32 v144, v144, v72, v73
	v_max3_f32 v144, v144, v74, v75
	v_max3_f32 v144, v144, v76, v77
	v_mfma_f32_32x32x16_bf16 v[16:31], v[208:211], v[152:155], v[16:31]
	v_max3_f32 v144, v144, v78, v79
	v_mov_b32_e32 v145, v144
	s_nop 1
	v_permlane32_swap_b32_e32 v144, v145
	v_max_f32_e32 v144, v144, v145
	v_cmp_ge_f32_e32 vcc, s63, v144
	v_mfma_f32_32x32x16_bf16 v[16:31], v[212:215], v[170:173], v[16:31]
	s_cmp_eq_u64 vcc, exec
	s_cselect_b64 s[4:5], -1, 0
	s_waitcnt vmcnt(0) lgkmcnt(0)
	s_barrier
; #define SBAR() __builtin_amdgcn_sched_barrier(0)
; #define RESC(a) do { if (__any((a) < 1.f)) { if (hi == 0) al_l[r32] = (a); asm volatile("s_waitcnt lgkmcnt(0)" ::: "memory"); \
;     for (int d = 0; d < 4; ++d) for (int r = 0; r < 16; ++r) o[d][r] *= al_l[crow_(r, hi)]; } } while (0)
; #define TILE_BAR() do { asm volatile("s_waitcnt vmcnt(0) lgkmcnt(0)" ::: "memory"); __builtin_amdgcn_s_barrier(); } while (0)
; #define RESC(a) do { if (__any((a) < 1.f)) { for (int d = 0; d < 4; ++d) for (int r = 0; r < 16; ++r) o[d][r] *= (a); } } while (0)
; #define TILE_BAR() do { asm volatile("s_waitcnt vmcnt(0) lgkmcnt(0)" ::: "memory"); __builtin_amdgcn_s_barrier(); } while (0)
; #define RESC(a) do { if (__any((a) < 1.f)) { for (int d = 0; d < 4; ++d) for (int r = 0; r < 16; ++r) o[d][r] *= (a); } } while (0)
; template <int MLA>
; __device__ __forceinline__ void partialSM(f32x16& p0, f32x16& p1, float& m_reg, float& mn, float& alpha) {
;     ...
;   if (__builtin_expect(__all(pmax - m_reg <= THR / SCALE), 1)) { mn = m_reg; alpha = 1.f; }
;   else { mn = fmaxf(m_reg, pmax); alpha = __builtin_amdgcn_exp2f((m_reg - mn) * C); m_reg = mn; }
;   float mnC = -mn * C;
; #pragma unroll
;   for (int r = 0; r < 16; ++r) p0[r] = fmaf(p0[r], C, mnC);
; #pragma unroll
;   for (int r = 0; r < 16; ++r) p1[r] = fmaf(p1[r], C, mnC);
; #pragma unroll
;   for (int r = 0; r < 16; ++r) p0[r] = __builtin_amdgcn_exp2f(p0[r]);
; __device__ __forceinline__ void attn_mla_dma(const bf16_t* __restrict__ Qb, const bf16_t* __restrict__ Kh, const bf16_t* __restrict__ Vh, bf16_t* __restrict__ Ob,
;                                              int seq, char* lds, const int tid) {
;     ...
;     pv_d0_t(o, vb0 + vprev * SHM_VV, pa0, pa1, pa2, pa3); partialSM<MLA>(pB0, pB1, m_reg, mnB, alB);
;     TILE_BAR();
;     RESC(alB);
;     { const int t = vprev; vprev = vcur; vcur = vnxt; vnxt = t; }
;     SBAR(); qkt_mla<0>(pA0, pA1, ka, qr, qlds);
	s_cbranch_scc1 .Lal_c_m1
	v_max_f32_e32 v242, 0, v144
	v_exp_f32_e64 v152, -v242
	s_nop 0
	v_pk_mul_f32 v[14:15], v[14:15], v[152:153] op_sel_hi:[1,0]
	v_pk_mul_f32 v[12:13], v[12:13], v[152:153] op_sel_hi:[1,0]
	v_pk_mul_f32 v[10:11], v[10:11], v[152:153] op_sel_hi:[1,0]
	v_pk_mul_f32 v[8:9], v[8:9], v[152:153] op_sel_hi:[1,0]
	v_pk_mul_f32 v[6:7], v[6:7], v[152:153] op_sel_hi:[1,0]
	v_pk_mul_f32 v[4:5], v[4:5], v[152:153] op_sel_hi:[1,0]
	v_pk_mul_f32 v[2:3], v[2:3], v[152:153] op_sel_hi:[1,0]
	v_pk_mul_f32 v[0:1], v[0:1], v[152:153] op_sel_hi:[1,0]
	v_pk_mul_f32 v[62:63], v[62:63], v[152:153] op_sel_hi:[1,0]
	v_pk_mul_f32 v[60:61], v[60:61], v[152:153] op_sel_hi:[1,0]
	v_pk_mul_f32 v[58:59], v[58:59], v[152:153] op_sel_hi:[1,0]
	v_pk_mul_f32 v[56:57], v[56:57], v[152:153] op_sel_hi:[1,0]
	v_pk_mul_f32 v[54:55], v[54:55], v[152:153] op_sel_hi:[1,0]
	v_pk_mul_f32 v[52:53], v[52:53], v[152:153] op_sel_hi:[1,0]
	v_pk_mul_f32 v[50:51], v[50:51], v[152:153] op_sel_hi:[1,0]
	v_pk_mul_f32 v[48:49], v[48:49], v[152:153] op_sel_hi:[1,0]
	v_pk_mul_f32 v[46:47], v[46:47], v[152:153] op_sel_hi:[1,0]
	v_pk_mul_f32 v[44:45], v[44:45], v[152:153] op_sel_hi:[1,0]
	v_pk_mul_f32 v[42:43], v[42:43], v[152:153] op_sel_hi:[1,0]
	v_pk_mul_f32 v[40:41], v[40:41], v[152:153] op_sel_hi:[1,0]
	v_pk_mul_f32 v[38:39], v[38:39], v[152:153] op_sel_hi:[1,0]
	v_pk_mul_f32 v[36:37], v[36:37], v[152:153] op_sel_hi:[1,0]
	v_pk_mul_f32 v[34:35], v[34:35], v[152:153] op_sel_hi:[1,0]
	v_pk_mul_f32 v[32:33], v[32:33], v[152:153] op_sel_hi:[1,0]
	v_pk_mul_f32 v[30:31], v[30:31], v[152:153] op_sel_hi:[1,0]
	v_pk_mul_f32 v[28:29], v[28:29], v[152:153] op_sel_hi:[1,0]
	v_pk_mul_f32 v[26:27], v[26:27], v[152:153] op_sel_hi:[1,0]
	v_pk_mul_f32 v[24:25], v[24:25], v[152:153] op_sel_hi:[1,0]
	v_pk_mul_f32 v[22:23], v[22:23], v[152:153] op_sel_hi:[1,0]
	v_pk_mul_f32 v[20:21], v[20:21], v[152:153] op_sel_hi:[1,0]
	v_pk_mul_f32 v[18:19], v[18:19], v[152:153] op_sel_hi:[1,0]
	v_pk_mul_f32 v[16:17], v[16:17], v[152:153] op_sel_hi:[1,0]
	v_sub_f32_e32 v80, v80, v242
	v_sub_f32_e32 v81, v81, v242
	v_sub_f32_e32 v82, v82, v242
	v_sub_f32_e32 v83, v83, v242
	v_sub_f32_e32 v84, v84, v242
	v_sub_f32_e32 v85, v85, v242
	v_sub_f32_e32 v86, v86, v242
	v_sub_f32_e32 v87, v87, v242
	v_sub_f32_e32 v88, v88, v242
	v_sub_f32_e32 v89, v89, v242
	v_sub_f32_e32 v90, v90, v242
	v_sub_f32_e32 v91, v91, v242
	v_sub_f32_e32 v92, v92, v242
	v_sub_f32_e32 v93, v93, v242
	v_sub_f32_e32 v94, v94, v242
	v_sub_f32_e32 v95, v95, v242
	v_sub_f32_e32 v64, v64, v242
	v_sub_f32_e32 v65, v65, v242
	v_sub_f32_e32 v66, v66, v242
	v_sub_f32_e32 v67, v67, v242
	v_sub_f32_e32 v68, v68, v242
	v_sub_f32_e32 v69, v69, v242
	v_sub_f32_e32 v70, v70, v242
	v_sub_f32_e32 v71, v71, v242
	v_sub_f32_e32 v72, v72, v242
	v_sub_f32_e32 v73, v73, v242
	v_sub_f32_e32 v74, v74, v242
	v_sub_f32_e32 v75, v75, v242
	v_sub_f32_e32 v76, v76, v242
	v_sub_f32_e32 v77, v77, v242
	v_sub_f32_e32 v78, v78, v242
	v_sub_f32_e32 v79, v79, v242
	v_sub_f32_e32 v226, v226, v242
	v_sub_f32_e32 v227, v227, v242
	v_sub_f32_e32 v228, v228, v242
	v_sub_f32_e32 v229, v229, v242
	v_sub_f32_e32 v230, v230, v242
	v_sub_f32_e32 v231, v231, v242
	v_sub_f32_e32 v232, v232, v242
	v_sub_f32_e32 v233, v233, v242
	v_sub_f32_e32 v234, v234, v242
	v_sub_f32_e32 v235, v235, v242
	v_sub_f32_e32 v236, v236, v242
	v_sub_f32_e32 v237, v237, v242
	v_sub_f32_e32 v238, v238, v242
	v_sub_f32_e32 v239, v239, v242
	v_sub_f32_e32 v240, v240, v242
	v_sub_f32_e32 v241, v241, v242
	s_branch .LBB0_117
.Lal_c_m1:
	v_mov_b32_e32 v152, 1.0
.LBB0_117:
	v_exp_f32_e32 v155, v64
	v_exp_f32_e32 v170, v65
	v_exp_f32_e32 v171, v66
	v_exp_f32_e32 v172, v67
	v_exp_f32_e32 v173, v68
	v_exp_f32_e32 v197, v69
	v_exp_f32_e32 v199, v70
	v_exp_f32_e32 v200, v71
	v_exp_f32_e32 v201, v72
	v_exp_f32_e32 v202, v73
	v_exp_f32_e32 v203, v74
	v_exp_f32_e32 v204, v75
	v_exp_f32_e32 v205, v76
	v_exp_f32_e32 v222, v77
	v_exp_f32_e32 v223, v78
	v_exp_f32_e32 v154, v79
	v_exp_f32_e32 v206, v80
	v_exp_f32_e32 v207, v81
	v_exp_f32_e32 v208, v82
	v_exp_f32_e32 v209, v83
	v_exp_f32_e32 v210, v84
	v_exp_f32_e32 v211, v85
	v_exp_f32_e32 v212, v86
	v_exp_f32_e32 v213, v87
	v_exp_f32_e32 v214, v88
	v_exp_f32_e32 v215, v89
	v_exp_f32_e32 v216, v90
	v_exp_f32_e32 v217, v91
	v_exp_f32_e32 v218, v92
	v_exp_f32_e32 v219, v93
	v_exp_f32_e32 v220, v94
	v_exp_f32_e32 v221, v95
	ds_read_b128 v[64:67], v169
	ds_read_b128 v[68:71], v169 offset:12288
	ds_read_b128 v[144:147], v190
	ds_read_b128 v[148:151], v190 offset:12288
	v_mov_b32_e32 v224, v155
	s_waitcnt lgkmcnt(0)
	v_mfma_f32_32x32x16_bf16 v[80:95], v[64:67], v[140:143], v[226:241]
	v_mfma_f32_32x32x16_bf16 v[64:79], v[68:71], v[140:143], v[226:241]
	v_mov_b32_e32 v225, v154
	v_mfma_f32_32x32x16_bf16 v[80:95], v[144:147], v[136:139], v[80:95]
	v_mfma_f32_32x32x16_bf16 v[64:79], v[148:151], v[136:139], v[64:79]
	ds_read_b128 v[144:147], v193
	ds_read_b128 v[148:151], v193 offset:12288
	s_waitcnt lgkmcnt(0)
	v_mfma_f32_32x32x16_bf16 v[80:95], v[144:147], v[132:135], v[80:95]
	v_mfma_f32_32x32x16_bf16 v[64:79], v[148:151], v[132:135], v[64:79]
	ds_read_b128 v[144:147], v192
	ds_read_b128 v[148:151], v192 offset:12288
	s_waitcnt lgkmcnt(0)
	v_mfma_f32_32x32x16_bf16 v[80:95], v[144:147], v[128:131], v[80:95]
	v_mfma_f32_32x32x16_bf16 v[64:79], v[148:151], v[128:131], v[64:79]
	ds_read_b128 v[144:147], v169 offset:128
	ds_read_b128 v[148:151], v169 offset:12416
	s_waitcnt lgkmcnt(0)
	v_mfma_f32_32x32x16_bf16 v[80:95], v[144:147], v[124:127], v[80:95]
	v_mfma_f32_32x32x16_bf16 v[64:79], v[148:151], v[124:127], v[64:79]
	ds_read_b128 v[144:147], v190 offset:128
	ds_read_b128 v[148:151], v190 offset:12416
	s_waitcnt lgkmcnt(0)
; #define SBAR() __builtin_amdgcn_sched_barrier(0)
; __device__ __forceinline__ void finishSM(f32x16& p0, f32x16& p1, float alpha, float& l_reg, bf16x8& pa0, bf16x8& pa1, bf16x8& pa2, bf16x8& pa3) {
; #pragma unroll
;   for (int r = 0; r < 16; ++r) p1[r] = __builtin_amdgcn_exp2f(p1[r]);
;   float ps = 0;
; #pragma unroll
;   for (int r = 0; r < 16; ++r) ps += p0[r];
; #pragma unroll
;   for (int r = 0; r < 16; ++r) ps += p1[r];
;   { auto rr = __builtin_amdgcn_permlane32_swap(__float_as_uint(ps), __float_as_uint(ps), false, false);
;     ps = __uint_as_float(rr[0]) + __uint_as_float(rr[1]); }
;   l_reg = l_reg * alpha + ps;
;     ...
;   PK4(p0, 0, pa0); PK4(p0, 8, pa1); PK4(p1, 0, pa2); PK4(p1, 8, pa3);
;     ...
; }
; __device__ __forceinline__ void attn_mla_dma(const bf16_t* __restrict__ Qb, const bf16_t* __restrict__ Kh, const bf16_t* __restrict__ Vh, bf16_t* __restrict__ Ob,
;                                              int seq, char* lds, const int tid) {
;     ...
;     SBAR(); qkt_mla<0>(pA0, pA1, ka, qr, qlds);
;     finishSM(pB0, pB1, alB, l_reg, pa0, pa1, pa2, pa3); SBAR();
;     DMA_TILE((j + 2) * KVBLK, 1, vnxt); SBAR();
;     pv_d0_t(o, vb0 + vprev * SHM_VV, pa0, pa1, pa2, pa3); partialSM<MLA>(pA0, pA1, m_reg, mnA, alA);
	v_mfma_f32_32x32x16_bf16 v[80:95], v[144:147], v[120:123], v[80:95]
	v_mfma_f32_32x32x16_bf16 v[64:79], v[148:151], v[120:123], v[64:79]
	ds_read_b128 v[144:147], v193 offset:128
	ds_read_b128 v[148:151], v193 offset:12416
	s_waitcnt lgkmcnt(0)
	v_mfma_f32_32x32x16_bf16 v[80:95], v[144:147], v[116:119], v[80:95]
	v_mfma_f32_32x32x16_bf16 v[64:79], v[148:151], v[116:119], v[64:79]
	ds_read_b128 v[144:147], v192 offset:128
	ds_read_b128 v[148:151], v192 offset:12416
	s_waitcnt lgkmcnt(0)
	v_mfma_f32_32x32x16_bf16 v[80:95], v[144:147], v[112:115], v[80:95]
	v_mfma_f32_32x32x16_bf16 v[64:79], v[148:151], v[112:115], v[64:79]
	ds_read_b128 v[144:147], v169 offset:256
	ds_read_b128 v[148:151], v169 offset:12544
	s_waitcnt lgkmcnt(0)
	v_mfma_f32_32x32x16_bf16 v[80:95], v[144:147], v[108:111], v[80:95]
	v_mfma_f32_32x32x16_bf16 v[64:79], v[148:151], v[108:111], v[64:79]
	ds_read_b128 v[144:147], v190 offset:256
	ds_read_b128 v[148:151], v190 offset:12544
	s_waitcnt lgkmcnt(0)
	v_mfma_f32_32x32x16_bf16 v[80:95], v[144:147], v[104:107], v[80:95]
	v_mfma_f32_32x32x16_bf16 v[64:79], v[148:151], v[104:107], v[64:79]
	ds_read_b128 v[144:147], v193 offset:256
	ds_read_b128 v[148:151], v193 offset:12544
	s_waitcnt lgkmcnt(0)
	v_mfma_f32_32x32x16_bf16 v[80:95], v[144:147], v[100:103], v[80:95]
	v_mfma_f32_32x32x16_bf16 v[64:79], v[148:151], v[100:103], v[64:79]
	ds_read_b128 v[144:147], v192 offset:256
	ds_read_b128 v[148:151], v192 offset:12544
	s_waitcnt lgkmcnt(0)
	v_mfma_f32_32x32x16_bf16 v[80:95], v[144:147], v[96:99], v[80:95]
	v_add_f32_e32 v144, 0, v206
	v_add_f32_e32 v144, v207, v144
	v_add_f32_e32 v144, v208, v144
	v_add_f32_e32 v144, v209, v144
	v_add_f32_e32 v144, v210, v144
	v_add_f32_e32 v144, v211, v144
	v_add_f32_e32 v144, v212, v144
	v_add_f32_e32 v144, v213, v144
	v_add_f32_e32 v144, v214, v144
	v_add_f32_e32 v144, v215, v144
	v_add_f32_e32 v144, v216, v144
	v_add_f32_e32 v144, v217, v144
	v_add_f32_e32 v144, v218, v144
	v_add_f32_e32 v144, v219, v144
	v_add_f32_e32 v144, v220, v144
	v_add_f32_e32 v144, v221, v144
	v_add_f32_e32 v144, v224, v144
	v_add_f32_e32 v144, v170, v144
	v_add_f32_e32 v144, v171, v144
	v_add_f32_e32 v144, v172, v144
	v_add_f32_e32 v144, v173, v144
	v_add_f32_e32 v144, v197, v144
	v_add_f32_e32 v144, v199, v144
	v_add_f32_e32 v144, v200, v144
	v_add_f32_e32 v144, v201, v144
	v_add_f32_e32 v144, v202, v144
	v_mfma_f32_32x32x16_bf16 v[64:79], v[148:151], v[96:99], v[64:79]
	v_add_f32_e32 v144, v203, v144
	v_add_f32_e32 v144, v204, v144
	v_add_f32_e32 v144, v205, v144
	v_add_f32_e32 v144, v222, v144
	v_add_f32_e32 v144, v223, v144
	v_add_f32_e32 v154, v225, v144
	v_mov_b32_e32 v155, v154
	v_cvt_pk_bf16_f32 v144, v206, v207
	v_cvt_pk_bf16_f32 v145, v208, v209
	v_cvt_pk_bf16_f32 v146, v210, v211
	v_cvt_pk_bf16_f32 v147, v212, v213
	s_nop 1
	v_permlane32_swap_b32_e32 v154, v155
	v_cvt_pk_bf16_f32 v148, v214, v215
	v_cvt_pk_bf16_f32 v149, v216, v217
	v_cvt_pk_bf16_f32 v150, v218, v219
	v_cvt_pk_bf16_f32 v151, v220, v221
	v_cvt_pk_bf16_f32 v170, v224, v170
	v_cvt_pk_bf16_f32 v171, v171, v172
	v_cvt_pk_bf16_f32 v172, v173, v197
	v_cvt_pk_bf16_f32 v173, v199, v200
	v_cvt_pk_bf16_f32 v200, v201, v202
	v_cvt_pk_bf16_f32 v201, v203, v204
	v_cvt_pk_bf16_f32 v202, v205, v222
	v_cvt_pk_bf16_f32 v203, v223, v225
	s_nop 0
	s_add_u32 s4, s56, 0x17090000
	s_addc_u32 s5, s57, 0
	s_add_u32 s56, s58, 0x1a060000
	s_mov_b32 m0, s16
	s_addc_u32 s57, s59, 0
	s_add_i32 s58, s40, s60
	global_load_lds_dwordx4 v188, s[4:5]
	s_mov_b32 m0, s17
	s_nop 0
	global_load_lds_dwordx4 v189, s[4:5]
	s_mov_b32 m0, s44
	s_nop 0
	global_load_lds_dwordx4 v191, s[4:5]
	s_mov_b32 m0, s58
	s_nop 0
	global_load_lds_dwordx4 v194, s[56:57]
	s_add_i32 m0, s58, 0x2000
	s_nop 0
	global_load_lds_dwordx4 v195, s[56:57]
	v_lshl_add_u32 v197, s55, 14, v167
	ds_read_b64_tr_b16 v[204:205], v197 offset:0
	ds_read_b64_tr_b16 v[206:207], v197 offset:0x800
	ds_read_b64_tr_b16 v[208:209], v197 offset:0x1000
	ds_read_b64_tr_b16 v[210:211], v197 offset:0x1800
	ds_read_b64_tr_b16 v[212:213], v197 offset:0x2000
	ds_read_b64_tr_b16 v[214:215], v197 offset:0x2800
	ds_read_b64_tr_b16 v[216:217], v197 offset:0x3000
	ds_read_b64_tr_b16 v[218:219], v197 offset:0x3800
	s_waitcnt lgkmcnt(0)
	s_nop 0
	v_mfma_f32_32x32x16_bf16 v[0:15], v[204:207], v[144:147], v[0:15]
	ds_read_b64_tr_b16 v[204:205], v197 offset:0x200
	ds_read_b64_tr_b16 v[206:207], v197 offset:0xa00
	v_mfma_f32_32x32x16_bf16 v[0:15], v[208:211], v[148:151], v[0:15]
	ds_read_b64_tr_b16 v[208:209], v197 offset:0x1200
	ds_read_b64_tr_b16 v[210:211], v197 offset:0x1a00
	v_mfma_f32_32x32x16_bf16 v[0:15], v[212:215], v[170:173], v[0:15]
	ds_read_b64_tr_b16 v[212:213], v197 offset:0x2200
	ds_read_b64_tr_b16 v[214:215], v197 offset:0x2a00
	v_mfma_f32_32x32x16_bf16 v[0:15], v[216:219], v[200:203], v[0:15]
	ds_read_b64_tr_b16 v[216:217], v197 offset:0x3200
	ds_read_b64_tr_b16 v[218:219], v197 offset:0x3a00
	s_waitcnt lgkmcnt(0)
	v_mfma_f32_32x32x16_bf16 v[48:63], v[204:207], v[144:147], v[48:63]
	ds_read_b64_tr_b16 v[204:205], v197 offset:0x400
	ds_read_b64_tr_b16 v[206:207], v197 offset:0xc00
	v_mfma_f32_32x32x16_bf16 v[48:63], v[208:211], v[148:151], v[48:63]
	ds_read_b64_tr_b16 v[208:209], v197 offset:0x1400
	ds_read_b64_tr_b16 v[210:211], v197 offset:0x1c00
	v_mfma_f32_32x32x16_bf16 v[48:63], v[212:215], v[170:173], v[48:63]
	ds_read_b64_tr_b16 v[212:213], v197 offset:0x2400
	ds_read_b64_tr_b16 v[214:215], v197 offset:0x2c00
	v_mfma_f32_32x32x16_bf16 v[48:63], v[216:219], v[200:203], v[48:63]
	ds_read_b64_tr_b16 v[216:217], v197 offset:0x3400
	ds_read_b64_tr_b16 v[218:219], v197 offset:0x3c00
	s_waitcnt lgkmcnt(0)
; #define RESC(a) do { if (__any((a) < 1.f)) { if (hi == 0) al_l[r32] = (a); asm volatile("s_waitcnt lgkmcnt(0)" ::: "memory"); \
;     for (int d = 0; d < 4; ++d) for (int r = 0; r < 16; ++r) o[d][r] *= al_l[crow_(r, hi)]; } } while (0)
; #define TILE_BAR() do { asm volatile("s_waitcnt vmcnt(0) lgkmcnt(0)" ::: "memory"); __builtin_amdgcn_s_barrier(); } while (0)
; #define RESC(a) do { if (__any((a) < 1.f)) { for (int d = 0; d < 4; ++d) for (int r = 0; r < 16; ++r) o[d][r] *= (a); } } while (0)
; #define TILE_BAR() do { asm volatile("s_waitcnt vmcnt(0) lgkmcnt(0)" ::: "memory"); __builtin_amdgcn_s_barrier(); } while (0)
; #define RESC(a) do { if (__any((a) < 1.f)) { for (int d = 0; d < 4; ++d) for (int r = 0; r < 16; ++r) o[d][r] *= (a); } } while (0)
; template <int MLA>
; __device__ __forceinline__ void partialSM(f32x16& p0, f32x16& p1, float& m_reg, float& mn, float& alpha) {
;     ...
;   { auto rr = __builtin_amdgcn_permlane32_swap(__float_as_uint(pmax), __float_as_uint(pmax), false, false);
;     pmax = fmaxf(__uint_as_float(rr[0]), __uint_as_float(rr[1])); }
;   if (__builtin_expect(__all(pmax - m_reg <= THR / SCALE), 1)) { mn = m_reg; alpha = 1.f; }
;   else { mn = fmaxf(m_reg, pmax); alpha = __builtin_amdgcn_exp2f((m_reg - mn) * C); m_reg = mn; }
;   float mnC = -mn * C;
; #pragma unroll
;   for (int r = 0; r < 16; ++r) p0[r] = fmaf(p0[r], C, mnC);
; #pragma unroll
;   for (int r = 0; r < 16; ++r) p1[r] = fmaf(p1[r], C, mnC);
; #pragma unroll
;   for (int r = 0; r < 16; ++r) p0[r] = __builtin_amdgcn_exp2f(p0[r]);
; __device__ __forceinline__ void attn_mla_dma(const bf16_t* __restrict__ Qb, const bf16_t* __restrict__ Kh, const bf16_t* __restrict__ Vh, bf16_t* __restrict__ Ob,
;                                              int seq, char* lds, const int tid) {
;     ...
;     pv_d0_t(o, vb0 + vprev * SHM_VV, pa0, pa1, pa2, pa3); partialSM<MLA>(pA0, pA1, m_reg, mnA, alA);
;     TILE_BAR();
;     RESC(alA);
	v_mfma_f32_32x32x16_bf16 v[32:47], v[204:207], v[144:147], v[32:47]
	ds_read_b64_tr_b16 v[204:205], v197 offset:0x600
	ds_read_b64_tr_b16 v[206:207], v197 offset:0xe00
	v_mfma_f32_32x32x16_bf16 v[32:47], v[208:211], v[148:151], v[32:47]
	ds_read_b64_tr_b16 v[208:209], v197 offset:0x1600
	ds_read_b64_tr_b16 v[210:211], v197 offset:0x1e00
	v_mfma_f32_32x32x16_bf16 v[32:47], v[212:215], v[170:173], v[32:47]
	ds_read_b64_tr_b16 v[212:213], v197 offset:0x2600
	ds_read_b64_tr_b16 v[214:215], v197 offset:0x2e00
	v_mfma_f32_32x32x16_bf16 v[32:47], v[216:219], v[200:203], v[32:47]
	ds_read_b64_tr_b16 v[216:217], v197 offset:0x3600
	ds_read_b64_tr_b16 v[218:219], v197 offset:0x3e00
	s_waitcnt lgkmcnt(0)
	v_mfma_f32_32x32x16_bf16 v[16:31], v[204:207], v[144:147], v[16:31]
	v_max_f32_e32 v144, v80, v81
	v_max3_f32 v144, v144, v82, v83
	v_max3_f32 v144, v144, v84, v85
	v_max3_f32 v144, v144, v86, v87
	v_max3_f32 v144, v144, v88, v89
	v_max3_f32 v144, v144, v90, v91
	v_max3_f32 v144, v144, v92, v93
	v_mfma_f32_32x32x16_bf16 v[16:31], v[208:211], v[148:151], v[16:31]
	v_max3_f32 v144, v144, v94, v95
	v_max3_f32 v144, v144, v64, v65
	v_max3_f32 v144, v144, v66, v67
	v_max3_f32 v144, v144, v68, v69
	v_max3_f32 v144, v144, v70, v71
	v_max3_f32 v144, v144, v72, v73
	v_max3_f32 v144, v144, v74, v75
	v_max3_f32 v144, v144, v76, v77
	v_mfma_f32_32x32x16_bf16 v[16:31], v[212:215], v[170:173], v[16:31]
	v_max3_f32 v144, v144, v78, v79
	v_mov_b32_e32 v145, v144
	s_nop 1
	v_permlane32_swap_b32_e32 v144, v145
	v_max_f32_e32 v144, v144, v145
	v_cmp_ge_f32_e32 vcc, s63, v144
	v_mfma_f32_32x32x16_bf16 v[16:31], v[216:219], v[200:203], v[16:31]
	s_cmp_eq_u64 vcc, exec
	s_cselect_b64 s[4:5], -1, 0
	s_waitcnt vmcnt(0) lgkmcnt(0)
	s_barrier
	s_cbranch_scc1 .Lal_c_m2
	v_max_f32_e32 v242, 0, v144
	v_exp_f32_e64 v144, -v242
	s_nop 0
	v_pk_mul_f32 v[14:15], v[14:15], v[144:145] op_sel_hi:[1,0]
	v_pk_mul_f32 v[12:13], v[12:13], v[144:145] op_sel_hi:[1,0]
	v_pk_mul_f32 v[10:11], v[10:11], v[144:145] op_sel_hi:[1,0]
	v_pk_mul_f32 v[8:9], v[8:9], v[144:145] op_sel_hi:[1,0]
	v_pk_mul_f32 v[6:7], v[6:7], v[144:145] op_sel_hi:[1,0]
	v_pk_mul_f32 v[4:5], v[4:5], v[144:145] op_sel_hi:[1,0]
	v_pk_mul_f32 v[2:3], v[2:3], v[144:145] op_sel_hi:[1,0]
	v_pk_mul_f32 v[0:1], v[0:1], v[144:145] op_sel_hi:[1,0]
	v_pk_mul_f32 v[62:63], v[62:63], v[144:145] op_sel_hi:[1,0]
	v_pk_mul_f32 v[60:61], v[60:61], v[144:145] op_sel_hi:[1,0]
	v_pk_mul_f32 v[58:59], v[58:59], v[144:145] op_sel_hi:[1,0]
	v_pk_mul_f32 v[56:57], v[56:57], v[144:145] op_sel_hi:[1,0]
	v_pk_mul_f32 v[54:55], v[54:55], v[144:145] op_sel_hi:[1,0]
	v_pk_mul_f32 v[52:53], v[52:53], v[144:145] op_sel_hi:[1,0]
	v_pk_mul_f32 v[50:51], v[50:51], v[144:145] op_sel_hi:[1,0]
	v_pk_mul_f32 v[48:49], v[48:49], v[144:145] op_sel_hi:[1,0]
	v_pk_mul_f32 v[46:47], v[46:47], v[144:145] op_sel_hi:[1,0]
	v_pk_mul_f32 v[44:45], v[44:45], v[144:145] op_sel_hi:[1,0]
	v_pk_mul_f32 v[42:43], v[42:43], v[144:145] op_sel_hi:[1,0]
	v_pk_mul_f32 v[40:41], v[40:41], v[144:145] op_sel_hi:[1,0]
	v_pk_mul_f32 v[38:39], v[38:39], v[144:145] op_sel_hi:[1,0]
	v_pk_mul_f32 v[36:37], v[36:37], v[144:145] op_sel_hi:[1,0]
	v_pk_mul_f32 v[34:35], v[34:35], v[144:145] op_sel_hi:[1,0]
	v_pk_mul_f32 v[32:33], v[32:33], v[144:145] op_sel_hi:[1,0]
	v_pk_mul_f32 v[30:31], v[30:31], v[144:145] op_sel_hi:[1,0]
	v_pk_mul_f32 v[28:29], v[28:29], v[144:145] op_sel_hi:[1,0]
	v_pk_mul_f32 v[26:27], v[26:27], v[144:145] op_sel_hi:[1,0]
	v_pk_mul_f32 v[24:25], v[24:25], v[144:145] op_sel_hi:[1,0]
	v_pk_mul_f32 v[22:23], v[22:23], v[144:145] op_sel_hi:[1,0]
	v_pk_mul_f32 v[20:21], v[20:21], v[144:145] op_sel_hi:[1,0]
	v_pk_mul_f32 v[18:19], v[18:19], v[144:145] op_sel_hi:[1,0]
	v_pk_mul_f32 v[16:17], v[16:17], v[144:145] op_sel_hi:[1,0]
	v_sub_f32_e32 v80, v80, v242
	v_sub_f32_e32 v81, v81, v242
	v_sub_f32_e32 v82, v82, v242
	v_sub_f32_e32 v83, v83, v242
	v_sub_f32_e32 v84, v84, v242
	v_sub_f32_e32 v85, v85, v242
	v_sub_f32_e32 v86, v86, v242
	v_sub_f32_e32 v87, v87, v242
	v_sub_f32_e32 v88, v88, v242
	v_sub_f32_e32 v89, v89, v242
	v_sub_f32_e32 v90, v90, v242
	v_sub_f32_e32 v91, v91, v242
	v_sub_f32_e32 v92, v92, v242
	v_sub_f32_e32 v93, v93, v242
	v_sub_f32_e32 v94, v94, v242
	v_sub_f32_e32 v95, v95, v242
	v_sub_f32_e32 v64, v64, v242
	v_sub_f32_e32 v65, v65, v242
	v_sub_f32_e32 v66, v66, v242
	v_sub_f32_e32 v67, v67, v242
	v_sub_f32_e32 v68, v68, v242
	v_sub_f32_e32 v69, v69, v242
	v_sub_f32_e32 v70, v70, v242
	v_sub_f32_e32 v71, v71, v242
	v_sub_f32_e32 v72, v72, v242
	v_sub_f32_e32 v73, v73, v242
	v_sub_f32_e32 v74, v74, v242
	v_sub_f32_e32 v75, v75, v242
	v_sub_f32_e32 v76, v76, v242
	v_sub_f32_e32 v77, v77, v242
	v_sub_f32_e32 v78, v78, v242
	v_sub_f32_e32 v79, v79, v242
	v_sub_f32_e32 v226, v226, v242
	v_sub_f32_e32 v227, v227, v242
	v_sub_f32_e32 v228, v228, v242
	v_sub_f32_e32 v229, v229, v242
	v_sub_f32_e32 v230, v230, v242
	v_sub_f32_e32 v231, v231, v242
	v_sub_f32_e32 v232, v232, v242
	v_sub_f32_e32 v233, v233, v242
	v_sub_f32_e32 v234, v234, v242
	v_sub_f32_e32 v235, v235, v242
	v_sub_f32_e32 v236, v236, v242
	v_sub_f32_e32 v237, v237, v242
	v_sub_f32_e32 v238, v238, v242
	v_sub_f32_e32 v239, v239, v242
	v_sub_f32_e32 v240, v240, v242
	v_sub_f32_e32 v241, v241, v242
	s_branch .LBB0_119
.Lal_c_m2:
	v_mov_b32_e32 v144, 1.0
; #define SBAR() __builtin_amdgcn_sched_barrier(0)
; #define RESC(a) do { if (__any((a) < 1.f)) { if (hi == 0) al_l[r32] = (a); asm volatile("s_waitcnt lgkmcnt(0)" ::: "memory"); \
;     for (int d = 0; d < 4; ++d) for (int r = 0; r < 16; ++r) o[d][r] *= al_l[crow_(r, hi)]; } } while (0)
; #define TILE_BAR() do { asm volatile("s_waitcnt vmcnt(0) lgkmcnt(0)" ::: "memory"); __builtin_amdgcn_s_barrier(); } while (0)
; #define RESC(a) do { if (__any((a) < 1.f)) { for (int d = 0; d < 4; ++d) for (int r = 0; r < 16; ++r) o[d][r] *= (a); } } while (0)
; #define TILE_BAR() do { asm volatile("s_waitcnt vmcnt(0) lgkmcnt(0)" ::: "memory"); __builtin_amdgcn_s_barrier(); } while (0)
; #define RESC(a) do { if (__any((a) < 1.f)) { for (int d = 0; d < 4; ++d) for (int r = 0; r < 16; ++r) o[d][r] *= (a); } } while (0)
; template <int BUFOFF>
; __device__ __forceinline__ void qkt_mla(f32x16& p0, f32x16& p1, const int* ka, const bf16x8* qr, const char* qlds) {
;   typedef __attribute__((address_space(3))) const bf16x8* lp;
;   p0 = f32x16{}; p1 = f32x16{};
; #pragma unroll
;   for (int d0 = 0; d0 < 12; ++d0) {
;     const int a = ka[d0 & 3] + (d0 >> 2) * 128 + BUFOFF;
;     const bf16x8 b0 = *(lp)(a), b1 = *(lp)(a + 12288);
;     bf16x8 qf;
;     qf = qr[d0];
;     p0 = __builtin_amdgcn_mfma_f32_32x32x16_bf16(b0, qf, p0, 0, 0, 0);
;     p1 = __builtin_amdgcn_mfma_f32_32x32x16_bf16(b1, qf, p1, 0, 0, 0);
;   }
; __device__ __forceinline__ void attn_mla_dma(const bf16_t* __restrict__ Qb, const bf16_t* __restrict__ Kh, const bf16_t* __restrict__ Vh, bf16_t* __restrict__ Ob,
;                                              int seq, char* lds, const int tid) {
;     ...
;     SBAR(); qkt_mla<0>(pA0, pA1, ka, qr, qlds);
;     finishSM(pB0, pB1, alB, l_reg, pa0, pa1, pa2, pa3); SBAR();
;     DMA_TILE((j + 2) * KVBLK, 1, vnxt); SBAR();
;     pv_d0_t(o, vb0 + vprev * SHM_VV, pa0, pa1, pa2, pa3); partialSM<MLA>(pA0, pA1, m_reg, mnA, alA);
;     TILE_BAR();
;     RESC(alA);
;     { const int t = vprev; vprev = vcur; vcur = vnxt; vnxt = t; }
;   }
;   SBAR(); qkt_mla<(int)SHM_K192>(pB0, pB1, ka, qr, qlds);
;   finishSM(pA0, pA1, alA, l_reg, pa0, pa1, pa2, pa3); SBAR();
;   pv_d0_t(o, vb0 + vprev * SHM_VV, pa0, pa1, pa2, pa3); partialSM<MLA>(pB0, pB1, m_reg, mnB, alB);
.LBB0_119:
	s_add_u32 s14, s14, 0x40000
	v_exp_f32_e32 v145, v80
	v_exp_f32_e32 v210, v81
	v_exp_f32_e32 v208, v82
	v_exp_f32_e32 v212, v83
	v_exp_f32_e32 v211, v84
	v_exp_f32_e32 v213, v85
	v_exp_f32_e32 v207, v86
	v_exp_f32_e32 v209, v87
	v_exp_f32_e32 v200, v88
	v_exp_f32_e32 v203, v89
	v_exp_f32_e32 v202, v90
	v_exp_f32_e32 v205, v91
	v_exp_f32_e32 v199, v92
	v_exp_f32_e32 v201, v93
	v_exp_f32_e32 v204, v94
	v_exp_f32_e32 v206, v95
	s_addc_u32 s15, s15, 0
	v_add_f32_e32 v80, v158, v159
	s_add_u32 s47, s47, 0x60000
	v_fmac_f32_e32 v80, v198, v162
	v_add_f32_e32 v162, v154, v155
	s_mov_b32 s4, 0x3f800000
	s_addc_u32 s50, s50, 0
	s_add_i32 s53, s53, 2
	v_fmac_f32_e32 v162, v80, v152
	v_exp_f32_e32 v172, v64
	v_exp_f32_e32 v173, v65
	v_exp_f32_e32 v170, v66
	v_exp_f32_e32 v171, v67
	v_exp_f32_e32 v158, v68
	v_exp_f32_e32 v159, v69
	v_exp_f32_e32 v152, v70
	v_exp_f32_e32 v153, v71
	v_exp_f32_e32 v150, v72
	v_exp_f32_e32 v151, v73
	v_exp_f32_e32 v148, v74
	v_exp_f32_e32 v149, v75
	v_exp_f32_e32 v146, v76
	v_exp_f32_e32 v147, v77
	s_cmp_ge_u32 s53, s19
	v_exp_f32_e32 v154, v78
	v_exp_f32_e32 v155, v79
	s_cbranch_scc1 .LBB0_121
	s_mov_b32 s52, s54
	s_mov_b32 s54, s55
	v_mov_b32_e32 v198, v144
	s_branch .LBB0_115
.LBB0_121:
	v_sub_f32_e32 v197, 0, v226
	ds_read_b128 v[64:67], v169 offset:24576
	ds_read_b128 v[68:71], v169 offset:36864
	s_waitcnt lgkmcnt(0)
	v_mfma_f32_32x32x16_bf16 v[80:95], v[64:67], v[140:143], 0
	v_mfma_f32_32x32x16_bf16 v[64:79], v[68:71], v[140:143], 0
	ds_read_b128 v[140:143], v190 offset:24576
	ds_read_b128 v[214:217], v190 offset:36864
	s_waitcnt lgkmcnt(0)
	v_mfma_f32_32x32x16_bf16 v[80:95], v[140:143], v[136:139], v[80:95]
	v_mfma_f32_32x32x16_bf16 v[64:79], v[214:217], v[136:139], v[64:79]
	ds_read_b128 v[136:139], v193 offset:24576
	ds_read_b128 v[140:143], v193 offset:36864
	s_waitcnt lgkmcnt(0)
	v_mfma_f32_32x32x16_bf16 v[80:95], v[136:139], v[132:135], v[80:95]
	v_mfma_f32_32x32x16_bf16 v[64:79], v[140:143], v[132:135], v[64:79]
	ds_read_b128 v[132:135], v192 offset:24576
	ds_read_b128 v[136:139], v192 offset:36864
	s_waitcnt lgkmcnt(0)
	v_mfma_f32_32x32x16_bf16 v[80:95], v[132:135], v[128:131], v[80:95]
	v_mfma_f32_32x32x16_bf16 v[64:79], v[136:139], v[128:131], v[64:79]
	ds_read_b128 v[128:131], v169 offset:24704
	ds_read_b128 v[132:135], v169 offset:36992
	s_waitcnt lgkmcnt(0)
	v_mfma_f32_32x32x16_bf16 v[80:95], v[128:131], v[124:127], v[80:95]
	v_mfma_f32_32x32x16_bf16 v[64:79], v[132:135], v[124:127], v[64:79]
	ds_read_b128 v[124:127], v190 offset:24704
	ds_read_b128 v[128:131], v190 offset:36992
	s_waitcnt lgkmcnt(0)
	v_mfma_f32_32x32x16_bf16 v[80:95], v[124:127], v[120:123], v[80:95]
	v_mfma_f32_32x32x16_bf16 v[64:79], v[128:131], v[120:123], v[64:79]
	ds_read_b128 v[120:123], v193 offset:24704
	ds_read_b128 v[124:127], v193 offset:36992
	s_waitcnt lgkmcnt(0)
	v_mfma_f32_32x32x16_bf16 v[80:95], v[120:123], v[116:119], v[80:95]
	v_mfma_f32_32x32x16_bf16 v[64:79], v[124:127], v[116:119], v[64:79]
	ds_read_b128 v[116:119], v192 offset:24704
	ds_read_b128 v[120:123], v192 offset:36992
	s_waitcnt lgkmcnt(0)
	v_mfma_f32_32x32x16_bf16 v[80:95], v[116:119], v[112:115], v[80:95]
	v_mfma_f32_32x32x16_bf16 v[64:79], v[120:123], v[112:115], v[64:79]
	ds_read_b128 v[112:115], v169 offset:24832
	ds_read_b128 v[116:119], v169 offset:37120
	v_mov_b32_e32 v120, v154
	v_mov_b32_e32 v121, v155
	s_waitcnt lgkmcnt(0)
	v_mfma_f32_32x32x16_bf16 v[80:95], v[112:115], v[108:111], v[80:95]
	v_mfma_f32_32x32x16_bf16 v[64:79], v[116:119], v[108:111], v[64:79]
	ds_read_b128 v[108:111], v190 offset:24832
	ds_read_b128 v[112:115], v190 offset:37120
	v_mov_b32_e32 v116, v148
	v_mov_b32_e32 v117, v149
	v_mov_b32_e32 v118, v146
	v_mov_b32_e32 v119, v147
	s_waitcnt lgkmcnt(0)
	v_mfma_f32_32x32x16_bf16 v[80:95], v[108:111], v[104:107], v[80:95]
	v_mfma_f32_32x32x16_bf16 v[64:79], v[112:115], v[104:107], v[64:79]
	ds_read_b128 v[104:107], v193 offset:24832
	ds_read_b128 v[108:111], v193 offset:37120
	v_mov_b32_e32 v112, v152
	v_mov_b32_e32 v113, v153
	v_mov_b32_e32 v114, v150
	v_mov_b32_e32 v115, v151
	s_waitcnt lgkmcnt(0)
	v_mfma_f32_32x32x16_bf16 v[80:95], v[104:107], v[100:103], v[80:95]
	v_mfma_f32_32x32x16_bf16 v[64:79], v[108:111], v[100:103], v[64:79]
	ds_read_b128 v[100:103], v192 offset:24832
	ds_read_b128 v[104:107], v192 offset:37120
	v_mov_b32_e32 v108, v170
	v_mov_b32_e32 v109, v171
	v_mov_b32_e32 v110, v158
	v_mov_b32_e32 v111, v159
	s_waitcnt lgkmcnt(0)
	v_mfma_f32_32x32x16_bf16 v[80:95], v[100:103], v[96:99], v[80:95]
	v_mfma_f32_32x32x16_bf16 v[64:79], v[104:107], v[96:99], v[64:79]
	v_add_f32_e32 v96, 0, v145
	v_add_f32_e32 v96, v210, v96
	v_add_f32_e32 v96, v208, v96
	v_add_f32_e32 v96, v212, v96
	v_add_f32_e32 v96, v211, v96
	v_add_f32_e32 v96, v213, v96
	v_add_f32_e32 v96, v207, v96
	v_add_f32_e32 v96, v209, v96
	v_add_f32_e32 v96, v200, v96
	v_add_f32_e32 v96, v203, v96
	v_add_f32_e32 v96, v202, v96
	v_add_f32_e32 v96, v205, v96
	v_mov_b32_e32 v106, v172
	v_add_f32_e32 v96, v199, v96
	v_mov_b32_e32 v107, v173
	v_add_f32_e32 v96, v201, v96
	v_add_f32_e32 v96, v204, v96
	v_add_f32_e32 v96, v206, v96
	v_add_f32_e32 v96, v106, v96
	v_add_f32_e32 v96, v107, v96
	v_add_f32_e32 v96, v108, v96
	v_add_f32_e32 v96, v109, v96
	v_add_f32_e32 v96, v110, v96
	v_add_f32_e32 v96, v111, v96
	v_add_f32_e32 v96, v112, v96
	v_add_f32_e32 v96, v113, v96
	v_add_f32_e32 v96, v114, v96
	v_add_f32_e32 v96, v115, v96
	v_add_f32_e32 v96, v116, v96
	v_add_f32_e32 v96, v117, v96
	v_add_f32_e32 v96, v118, v96
	v_add_f32_e32 v96, v119, v96
	v_add_f32_e32 v96, v120, v96
	v_add_f32_e32 v100, v121, v96
	v_mov_b32_e32 v101, v100
	v_cvt_pk_bf16_f32 v96, v145, v210
	v_cvt_pk_bf16_f32 v97, v208, v212
	v_cvt_pk_bf16_f32 v98, v211, v213
	v_cvt_pk_bf16_f32 v99, v207, v209
	s_nop 1
	v_permlane32_swap_b32_e32 v100, v101
	v_cvt_pk_bf16_f32 v102, v200, v203
	v_cvt_pk_bf16_f32 v103, v202, v205
	v_cvt_pk_bf16_f32 v104, v199, v201
	v_cvt_pk_bf16_f32 v105, v204, v206
	v_cvt_pk_bf16_f32 v106, v106, v107
	v_cvt_pk_bf16_f32 v107, v108, v109
	v_cvt_pk_bf16_f32 v108, v110, v111
	v_cvt_pk_bf16_f32 v109, v112, v113
	v_cvt_pk_bf16_f32 v110, v114, v115
	v_cvt_pk_bf16_f32 v111, v116, v117
	v_cvt_pk_bf16_f32 v112, v118, v119
	v_cvt_pk_bf16_f32 v113, v120, v121
	s_nop 0
	v_add_u32_e32 v130, s52, v167
	ds_read_b64_tr_b16 v[114:115], v130 offset:0
	ds_read_b64_tr_b16 v[116:117], v130 offset:0x800
	ds_read_b64_tr_b16 v[118:119], v130 offset:0x1000
	ds_read_b64_tr_b16 v[120:121], v130 offset:0x1800
	ds_read_b64_tr_b16 v[122:123], v130 offset:0x2000
	ds_read_b64_tr_b16 v[124:125], v130 offset:0x2800
	ds_read_b64_tr_b16 v[126:127], v130 offset:0x3000
	ds_read_b64_tr_b16 v[128:129], v130 offset:0x3800
	s_waitcnt lgkmcnt(0)
; #define SBAR() __builtin_amdgcn_sched_barrier(0)
; template <int MLA>
; __device__ __forceinline__ void partialSM(f32x16& p0, f32x16& p1, float& m_reg, float& mn, float& alpha) {
;     ...
;   float pmax = p0[0];
; #pragma unroll
;   for (int r = 1; r < 16; ++r) pmax = fmaxf(pmax, p0[r]);
; #pragma unroll
;   for (int r = 0; r < 16; ++r) pmax = fmaxf(pmax, p1[r]);
;   { auto rr = __builtin_amdgcn_permlane32_swap(__float_as_uint(pmax), __float_as_uint(pmax), false, false);
;     pmax = fmaxf(__uint_as_float(rr[0]), __uint_as_float(rr[1])); }
;   if (__builtin_expect(__all(pmax - m_reg <= THR / SCALE), 1)) { mn = m_reg; alpha = 1.f; }
;   else { mn = fmaxf(m_reg, pmax); alpha = __builtin_amdgcn_exp2f((m_reg - mn) * C); m_reg = mn; }
; template <int D0> __device__ __forceinline__ void pv_one_t(f32x16& od, int vb, bf16x8 pa0, bf16x8 pa1, bf16x8 pa2, bf16x8 pa3) {
;   const s16x4 l0 = tr_read<v_rd_off(D0, 0, 0)>(vb), h0 = tr_read<v_rd_off(D0, 0, 1)>(vb), l1 = tr_read<v_rd_off(D0, 1, 0)>(vb), h1 = tr_read<v_rd_off(D0, 1, 1)>(vb);
;   const s16x4 l2 = tr_read<v_rd_off(D0, 2, 0)>(vb), h2 = tr_read<v_rd_off(D0, 2, 1)>(vb), l3 = tr_read<v_rd_off(D0, 3, 0)>(vb), h3 = tr_read<v_rd_off(D0, 3, 1)>(vb);
;   asm volatile("s_waitcnt lgkmcnt(0)" ::: "memory"); SBAR();
;     ...
;   od = __builtin_amdgcn_mfma_f32_32x32x16_bf16(PK(l0, h0), pa0, od, 0, 0, 0);
;   od = __builtin_amdgcn_mfma_f32_32x32x16_bf16(PK(l1, h1), pa1, od, 0, 0, 0);
;   od = __builtin_amdgcn_mfma_f32_32x32x16_bf16(PK(l2, h2), pa2, od, 0, 0, 0);
;   od = __builtin_amdgcn_mfma_f32_32x32x16_bf16(PK(l3, h3), pa3, od, 0, 0, 0);
	s_nop 0
	v_mfma_f32_32x32x16_bf16 v[0:15], v[114:117], v[96:99], v[0:15]
	ds_read_b64_tr_b16 v[114:115], v130 offset:0x200
	ds_read_b64_tr_b16 v[116:117], v130 offset:0xa00
	v_mfma_f32_32x32x16_bf16 v[0:15], v[118:121], v[102:105], v[0:15]
	ds_read_b64_tr_b16 v[118:119], v130 offset:0x1200
	ds_read_b64_tr_b16 v[120:121], v130 offset:0x1a00
	v_mfma_f32_32x32x16_bf16 v[0:15], v[122:125], v[106:109], v[0:15]
	ds_read_b64_tr_b16 v[122:123], v130 offset:0x2200
	ds_read_b64_tr_b16 v[124:125], v130 offset:0x2a00
	v_mfma_f32_32x32x16_bf16 v[0:15], v[126:129], v[110:113], v[0:15]
	ds_read_b64_tr_b16 v[126:127], v130 offset:0x3200
	ds_read_b64_tr_b16 v[128:129], v130 offset:0x3a00
	s_waitcnt lgkmcnt(0)
	v_mfma_f32_32x32x16_bf16 v[48:63], v[114:117], v[96:99], v[48:63]
	ds_read_b64_tr_b16 v[114:115], v130 offset:0x400
	ds_read_b64_tr_b16 v[116:117], v130 offset:0xc00
	v_mfma_f32_32x32x16_bf16 v[48:63], v[118:121], v[102:105], v[48:63]
	ds_read_b64_tr_b16 v[118:119], v130 offset:0x1400
	ds_read_b64_tr_b16 v[120:121], v130 offset:0x1c00
	v_mfma_f32_32x32x16_bf16 v[48:63], v[122:125], v[106:109], v[48:63]
	ds_read_b64_tr_b16 v[122:123], v130 offset:0x2400
	ds_read_b64_tr_b16 v[124:125], v130 offset:0x2c00
	v_mfma_f32_32x32x16_bf16 v[48:63], v[126:129], v[110:113], v[48:63]
	ds_read_b64_tr_b16 v[126:127], v130 offset:0x3400
	ds_read_b64_tr_b16 v[128:129], v130 offset:0x3c00
	s_waitcnt lgkmcnt(0)
	v_mfma_f32_32x32x16_bf16 v[32:47], v[114:117], v[96:99], v[32:47]
	ds_read_b64_tr_b16 v[114:115], v130 offset:0x600
	ds_read_b64_tr_b16 v[116:117], v130 offset:0xe00
	v_mfma_f32_32x32x16_bf16 v[32:47], v[118:121], v[102:105], v[32:47]
	ds_read_b64_tr_b16 v[118:119], v130 offset:0x1600
	ds_read_b64_tr_b16 v[120:121], v130 offset:0x1e00
	v_mfma_f32_32x32x16_bf16 v[32:47], v[122:125], v[106:109], v[32:47]
	ds_read_b64_tr_b16 v[122:123], v130 offset:0x2600
	ds_read_b64_tr_b16 v[124:125], v130 offset:0x2e00
	v_mfma_f32_32x32x16_bf16 v[32:47], v[126:129], v[110:113], v[32:47]
	ds_read_b64_tr_b16 v[126:127], v130 offset:0x3600
	ds_read_b64_tr_b16 v[128:129], v130 offset:0x3e00
	s_waitcnt lgkmcnt(0)
	v_mfma_f32_32x32x16_bf16 v[16:31], v[114:117], v[96:99], v[16:31]
	v_max_f32_e32 v96, v81, v81
	v_max_f32_e32 v97, v80, v80
	v_max_f32_e32 v96, v97, v96
	v_max3_f32 v96, v96, v82, v83
	v_max3_f32 v96, v96, v84, v85
	v_max3_f32 v96, v96, v86, v87
	v_max3_f32 v96, v96, v88, v89
	v_max3_f32 v96, v96, v90, v91
	v_max3_f32 v96, v96, v92, v93
	v_mfma_f32_32x32x16_bf16 v[16:31], v[118:121], v[102:105], v[16:31]
	v_max3_f32 v96, v96, v94, v95
	v_max3_f32 v96, v96, v64, v65
	v_max3_f32 v96, v96, v66, v67
	v_max3_f32 v96, v96, v68, v69
	v_max3_f32 v96, v96, v70, v71
	v_max3_f32 v96, v96, v72, v73
	v_max3_f32 v96, v96, v74, v75
	v_max3_f32 v96, v96, v76, v77
	v_mfma_f32_32x32x16_bf16 v[16:31], v[122:125], v[106:109], v[16:31]
	v_max3_f32 v96, v96, v78, v79
	v_mov_b32_e32 v97, v96
	s_nop 1
	v_permlane32_swap_b32_e32 v96, v97
	v_max_f32_e32 v97, v97, v97
	v_max_f32_e32 v96, v96, v96
	v_max_f32_e32 v96, v96, v97
	v_sub_f32_e32 v97, v96, v197
	v_cmp_ge_f32_e32 vcc, s63, v97
	v_max_f32_e32 v97, v197, v197
	v_max_f32_e32 v97, v97, v96
	v_mfma_f32_32x32x16_bf16 v[16:31], v[126:129], v[110:113], v[16:31]
	v_sub_f32_e32 v96, v197, v97
	v_mul_f32_e32 v96, 0x3f800000, v96
	v_exp_f32_e32 v96, v96
	s_cmp_eq_u64 vcc, exec
	s_cselect_b64 s[4:5], -1, 0
	v_cndmask_b32_e64 v96, v96, 1.0, s[4:5]
	v_cmp_gt_f32_e32 vcc, 1.0, v96
	s_cbranch_vccz .LBB0_113
	v_pk_mul_f32 v[14:15], v[14:15], v[96:97] op_sel_hi:[1,0]
	v_pk_mul_f32 v[12:13], v[12:13], v[96:97] op_sel_hi:[1,0]
	v_pk_mul_f32 v[10:11], v[10:11], v[96:97] op_sel_hi:[1,0]
	v_pk_mul_f32 v[8:9], v[8:9], v[96:97] op_sel_hi:[1,0]
	v_pk_mul_f32 v[6:7], v[6:7], v[96:97] op_sel_hi:[1,0]
	v_pk_mul_f32 v[4:5], v[4:5], v[96:97] op_sel_hi:[1,0]
	v_pk_mul_f32 v[2:3], v[2:3], v[96:97] op_sel_hi:[1,0]
	v_pk_mul_f32 v[0:1], v[0:1], v[96:97] op_sel_hi:[1,0]
	v_pk_mul_f32 v[62:63], v[62:63], v[96:97] op_sel_hi:[1,0]
	v_pk_mul_f32 v[60:61], v[60:61], v[96:97] op_sel_hi:[1,0]
	v_pk_mul_f32 v[58:59], v[58:59], v[96:97] op_sel_hi:[1,0]
	v_pk_mul_f32 v[56:57], v[56:57], v[96:97] op_sel_hi:[1,0]
	v_pk_mul_f32 v[54:55], v[54:55], v[96:97] op_sel_hi:[1,0]
	v_pk_mul_f32 v[52:53], v[52:53], v[96:97] op_sel_hi:[1,0]
	v_pk_mul_f32 v[50:51], v[50:51], v[96:97] op_sel_hi:[1,0]
	v_pk_mul_f32 v[48:49], v[48:49], v[96:97] op_sel_hi:[1,0]
	v_pk_mul_f32 v[46:47], v[46:47], v[96:97] op_sel_hi:[1,0]
	v_pk_mul_f32 v[44:45], v[44:45], v[96:97] op_sel_hi:[1,0]
	v_pk_mul_f32 v[42:43], v[42:43], v[96:97] op_sel_hi:[1,0]
	v_pk_mul_f32 v[40:41], v[40:41], v[96:97] op_sel_hi:[1,0]
	v_pk_mul_f32 v[38:39], v[38:39], v[96:97] op_sel_hi:[1,0]
	v_pk_mul_f32 v[36:37], v[36:37], v[96:97] op_sel_hi:[1,0]
	v_pk_mul_f32 v[34:35], v[34:35], v[96:97] op_sel_hi:[1,0]
	v_pk_mul_f32 v[32:33], v[32:33], v[96:97] op_sel_hi:[1,0]
	v_pk_mul_f32 v[30:31], v[30:31], v[96:97] op_sel_hi:[1,0]
	v_pk_mul_f32 v[28:29], v[28:29], v[96:97] op_sel_hi:[1,0]
	v_pk_mul_f32 v[26:27], v[26:27], v[96:97] op_sel_hi:[1,0]
	v_pk_mul_f32 v[24:25], v[24:25], v[96:97] op_sel_hi:[1,0]
	v_pk_mul_f32 v[22:23], v[22:23], v[96:97] op_sel_hi:[1,0]
	v_pk_mul_f32 v[20:21], v[20:21], v[96:97] op_sel_hi:[1,0]
	v_pk_mul_f32 v[18:19], v[18:19], v[96:97] op_sel_hi:[1,0]
	v_pk_mul_f32 v[16:17], v[16:17], v[96:97] op_sel_hi:[1,0]
	s_branch .LBB0_113

; __global__ __launch_bounds__(512, 2) void mega(Params p) {
;     ...
;       for (int rep = 0; rep < REP_DIFF; ++rep)
;       for (int t = blockIdx.x; t < 1024; t += gridDim.x) {
;         int bid = t & 255, rnd = t >> 8, h = bid & 7, qbg = (bid >> 3) + 32 * rnd;
;         int b = qbg / nqb_d, qb = qbg % nqb_d;
;         int ttid = tid; asm volatile("" : "+v"(ttid));
;         long tok0 = (long)b * S, q0 = tok0 + (long)qb * 128;
;         attn_diff_dma((const bf16_t*)(ws + O_DQ) + q0 * 1024 + h * 128, (const bf16_t*)(ws + O_DK) + tok0 * 1024 + h * 128,
;                       (const bf16_t*)(ws + O_DV) + tok0 * 1024 + h * 128, (bf16_t*)(ws + O_ODIFF) + q0 * 1024 + h * 128, S, shm, lam, p.g_sub, ttid);
.LBB0_125:
	v_readlane_b32 s4, v249, 2
	v_readlane_b32 s5, v249, 3
	s_andn2_b64 vcc, exec, s[4:5]
	s_mov_b32 s70, 0x4138aa3b
	s_cbranch_vccnz .LBB0_141
	v_readlane_b32 s12, v249, 37
	v_readlane_b32 s13, v249, 38
	s_add_u32 s20, s12, 0xe000000
	s_addc_u32 s21, s13, 0
	s_add_u32 s23, s12, 0x10000000
	s_addc_u32 s24, s13, 0
	s_add_u32 s25, s12, 0x12000000
	s_addc_u32 s26, s13, 0
	s_add_u32 s27, s12, 0x9800000
	s_addc_u32 s28, s13, 0
	s_lshr_b32 s29, s95, 7
	s_abs_i32 s30, s29
	v_cvt_f32_u32_e32 v0, s30
	s_sub_i32 s4, 0, s30
	s_ashr_i32 s34, s29, 31
	v_readlane_b32 s31, v249, 31
	v_rcp_iflag_f32_e32 v0, v0
	s_mov_b32 s40, s68
	v_mul_f32_e32 v0, 0x4f7ffffe, v0
	v_cvt_u32_f32_e32 v0, v0
	s_nop 0
	v_readfirstlane_b32 s5, v0
	s_mul_i32 s4, s4, s5
	s_mul_hi_u32 s4, s5, s4
	s_add_i32 s35, s5, s4
	s_add_u32 s36, s12, 0x10040000
	s_addc_u32 s37, s13, 0
	s_branch .LBB0_128

; __device__ __forceinline__ int v_rd_base(int lane) { return ((lane & 3) << 3) | (((lane >> 2) & 3) << 6) | (((lane >> 4) & 1) << 5) | (((lane >> 5) & 1) << 8); }
; __device__ __forceinline__ bf16x8 ld8(const bf16_t* p) { return gld8(p); }
; #define TILE_BAR() do { asm volatile("s_waitcnt vmcnt(0) lgkmcnt(0)" ::: "memory"); __builtin_amdgcn_s_barrier(); } while (0)
; #define TILE_BAR() do { asm volatile("s_waitcnt vmcnt(0) lgkmcnt(0)" ::: "memory"); __builtin_amdgcn_s_barrier(); } while (0)
; __device__ __forceinline__ void attn_diff_dma(const bf16_t* __restrict__ Qb, const bf16_t* __restrict__ Kh, const bf16_t* __restrict__ Vh, bf16_t* __restrict__ Ob,
;                                               int seq, char* lds, float lam, const float* __restrict__ gsub, const int tid) {
;     ...
;   const int wid = tid >> 6, lane = tid & 63, r32 = lane & 31, hi = lane >> 5;
;   const int comp = wid >> 2, wrow = wid & 3;
;   const int wu = __builtin_amdgcn_readfirstlane(wid);
;   char* V_lds = lds; char* K_lds = lds + 3 * SHM_VV;
;   float* wsl = (float*)(lds + 3 * SHM_VV + 2 * SHM_K) + wid * 64; float* li_l = wsl; float* al_l = wsl + 32;
;   float m_reg = -1e30f, l_reg = 0; f32x16 o[4] = {}; bf16x8 qr[4];
;   const bf16_t* Qw = Qb + (long)(wrow * QBLK + r32) * LD + comp * 64 + hi * 8;
; #pragma unroll
;   for (int d0 = 0; d0 < 4; ++d0) qr[d0] = ld8(Qw + d0 * 16);
;   unsigned kof[2], vof[2];
; #pragma unroll
;   for (int i = 0; i < 2; ++i) { const int ob = (i * 8 + wid) * 1024 + lane * 16, row = ob >> 8, within = ob & 255;
;     kof[i] = (unsigned)(row * (LD * 2) + (within ^ ((row & 7) << 4))); }
; #pragma unroll
;   for (int i = 0; i < 2; ++i) { const int ob = (i * 8 + wid) * 1024 + lane * 16, st = ob >> 9, sw = (ob & 511) >> 1;
;     const int kk = (st >> 2) * 8 + (sw >> 5), c = (st & 3) * 32 + (sw & 31);
;     const int k = (kk & ~0xC) | ((kk & 4) << 1) | ((kk & 8) >> 1);
;     vof[i] = (unsigned)(k * (LD * 2) + c * 2); }
;   const int vb0 = (int)(uintptr_t)V_lds + v_rd_base(lane);
;   int ka[4];
; #pragma unroll
;   for (int q = 0; q < 4; ++q) ka[q] = (int)(uintptr_t)K_lds + r32 * 256 + comp * 128 + ((q * 32 + hi * 16) ^ ((r32 & 7) << 4));
;     ...
;   f32x16 pA0, pA1, pB0, pB1; float mnA, mnB, alA, alB; bf16x8 pa0, pa1, pa2, pa3; const int NT = seq / KVBLK;
;   DMA_TILE(0, 0, 0); TILE_BAR();
.Lprio_d:
	s_lshl_b32 s4, s31, 1
	s_ashr_i32 s5, s40, 3
	s_and_b32 s50, s4, 0x700
	s_bfe_u32 s4, s40, 0x50003
	s_andn2_b32 s5, s5, 31
	s_or_b32 s5, s4, s5
	s_abs_i32 s12, s5
	s_mul_hi_u32 s13, s12, s35
	s_mul_i32 s14, s13, s30
	s_ashr_i32 s4, s40, 31
	s_sub_i32 s12, s12, s14
	s_xor_b32 s4, s4, s34
	s_add_i32 s14, s13, 1
	s_sub_i32 s15, s12, s30
	s_cmp_ge_u32 s12, s30
	s_cselect_b32 s13, s14, s13
	s_cselect_b32 s12, s15, s12
	s_add_i32 s14, s13, 1
	s_cmp_ge_u32 s12, s30
	s_cselect_b32 s12, s14, s13
	s_xor_b32 s12, s12, s4
	s_sub_i32 s4, s12, s4
	s_mul_i32 s12, s4, s29
	s_sub_i32 s12, s5, s12
	s_ashr_i32 s5, s4, 31
	s_lshl_b64 s[4:5], s[4:5], s18
	s_ashr_i32 s13, s12, 31
	s_lshl_b64 s[12:13], s[12:13], 17
	s_lshl_b64 s[14:15], s[4:5], 10
	s_add_u32 s12, s12, s14
	s_addc_u32 s13, s13, s15
	s_lshl_b64 s[12:13], s[12:13], 1
	s_add_u32 s14, s20, s12
	v_mov_b32_e32 v130, v168
	s_addc_u32 s15, s21, s13
	s_lshl_b32 s16, s40, 7
	s_and_b32 s41, s16, 0x380
	v_ashrrev_i32_e32 v4, 6, v130
	s_lshl_b32 s16, s41, 1
	v_and_b32_e32 v6, 31, v130
	v_lshlrev_b32_e32 v0, 5, v4
	s_movk_i32 s57, 0x60
	s_add_u32 s42, s14, s16
	v_ashrrev_i32_e32 v7, 8, v130
	v_and_or_b32 v0, v0, s57, v6
	s_addc_u32 s43, s15, 0
	v_lshlrev_b32_e32 v162, 11, v0
	v_lshlrev_b32_e32 v2, 6, v7
	v_lshl_add_u64 v[0:1], s[42:43], 0, v[162:163]
	v_ashrrev_i32_e32 v3, 31, v2
	v_lshl_add_u64 v[0:1], v[2:3], 1, v[0:1]
	v_lshrrev_b32_e32 v2, 1, v130
	v_and_b32_e32 v162, 16, v2
	v_lshl_add_u64 v[0:1], v[0:1], 0, v[162:163]
	global_load_dwordx4 v[108:111], v[0:1], off
	global_load_dwordx4 v[104:107], v[0:1], off offset:32
	global_load_dwordx4 v[100:103], v[0:1], off offset:64
	global_load_dwordx4 v[96:99], v[0:1], off offset:96
	v_and_b32_e32 v5, 63, v130
	v_lshlrev_b32_e32 v0, 10, v4
	v_lshlrev_b32_e32 v40, 4, v5
	v_or_b32_e32 v1, v0, v40
	v_ashrrev_i32_e32 v8, 8, v1
	s_lshl_b64 s[4:5], s[4:5], 11
	v_lshlrev_b32_e32 v9, 11, v8
	v_lshlrev_b32_e32 v8, 4, v8
	v_add_u32_e32 v1, 0x2000, v1
	s_add_u32 s14, s23, s4
	v_and_b32_e32 v3, 0xf0, v40
	v_and_b32_e32 v8, 0x70, v8
	v_ashrrev_i32_e32 v1, 8, v1
	s_addc_u32 s15, s24, s5
	v_bitop3_b32 v134, v8, v9, v3 bitop3:0xde
	v_lshlrev_b32_e32 v8, 11, v1
	v_lshlrev_b32_e32 v1, 4, v1
	s_add_u32 s14, s14, s16
	v_and_b32_e32 v1, 0x70, v1
	v_lshlrev_b32_e32 v41, 3, v5
	v_ashrrev_i32_e32 v5, 8, v0
	s_addc_u32 s15, s15, 0
	v_bitop3_b32 v135, v1, v8, v3 bitop3:0xde
	v_bfe_u32 v1, v130, 2, 2
	v_and_b32_e32 v42, 24, v41
	v_and_b32_e32 v8, 0x1ffff0, v5
	v_lshrrev_b32_e32 v5, 1, v5
	s_add_u32 s17, s25, s4
	v_and_or_b32 v3, v130, s57, v42
	v_and_or_b32 v1, v2, 8, v1
	v_and_b32_e32 v5, 4, v5
	v_add_u32_e32 v0, 0x2000, v0
	s_addc_u32 s44, s26, s5
	v_lshlrev_b32_e32 v3, 1, v3
	v_or3_b32 v5, v8, v5, v1
	v_ashrrev_i32_e32 v0, 8, v0
	s_add_u32 s16, s17, s16
	v_lshl_or_b32 v136, v5, 11, v3
	v_and_b32_e32 v5, 0x1ffff0, v0
	v_lshrrev_b32_e32 v0, 1, v0
	s_addc_u32 s17, s44, 0
	v_and_b32_e32 v0, 4, v0
	s_add_i32 s42, 0, 0xc000
	v_or3_b32 v0, v5, v0, v1
	s_cmp_lg_u32 s42, -1
	v_lshl_or_b32 v137, v0, 11, v3
	v_lshlrev_b32_e32 v0, 8, v6
	s_cselect_b32 s42, s42, 0
	v_lshlrev_b32_e32 v1, 7, v7
	v_add3_u32 v43, v0, s42, v1
	v_readfirstlane_b32 s42, v4
	s_cmp_lg_u32 0, -1
	v_lshlrev_b32_e32 v0, 4, v130
	s_cselect_b32 s56, 0, 0
	s_lshl_b32 s42, s42, 10
	v_and_b32_e32 v44, 0x70, v0
	s_add_i32 s42, s42, 0
	v_bitop3_b32 v0, v2, v44, 16 bitop3:0x6c
	s_add_i32 s43, s42, 0xc000
	v_bfe_u32 v244, v160, 2, 1
	v_bfe_u32 v245, v160, 3, 1
	v_xor_b32_e32 v243, v244, v245
	v_sub_u32_e32 v242, v244, v245
	v_lshlrev_b32_e32 v242, 10, v242
	v_lshlrev_b32_e32 v243, 6, v243
	v_add_u32_e32 v138, v43, v0
	v_xor_b32_e32 v138, v138, v243
	v_add_u32_e32 v138, v138, v242
	s_mov_b64 s[52:53], s[14:15]
	s_mov_b64 s[54:55], s[16:17]
	v_mov_b32_e32 v0, v137
	v_mov_b32_e32 v1, v134
	v_mov_b32_e32 v2, v136
	v_mov_b32_e32 v3, v135
	s_mov_b32 m0, s43
	s_add_i32 s44, s42, 0xe000
	v_bitop3_b32 v20, v162, v44, 32 bitop3:0x36
	global_load_lds_dwordx4 v1, s[52:53]
	s_mov_b32 m0, s44
	v_add_u32_e32 v141, v20, v43
	v_xor_b32_e32 v141, v141, v243
	v_add_u32_e32 v141, v141, v242
	global_load_lds_dwordx4 v3, s[52:53]
	s_mov_b32 m0, s42
	s_mov_b32 s52, 0
	global_load_lds_dwordx4 v2, s[54:55]
	s_add_i32 m0, s42, 0x2000
	s_mov_b32 s53, s52
	global_load_lds_dwordx4 v0, s[54:55]
	s_waitcnt vmcnt(0) lgkmcnt(0)
	s_barrier
; #define TILE_BAR() do { asm volatile("s_waitcnt vmcnt(0) lgkmcnt(0)" ::: "memory"); __builtin_amdgcn_s_barrier(); } while (0)
; #define TILE_BAR() do { asm volatile("s_waitcnt vmcnt(0) lgkmcnt(0)" ::: "memory"); __builtin_amdgcn_s_barrier(); } while (0)
; template <int MLA>
; __device__ __forceinline__ void partialSM(f32x16& p0, f32x16& p1, float& m_reg, float& mn, float& alpha) {
;   constexpr float SCALE = AttC<MLA>::SCALE;
;   constexpr float C = SCALE * 1.4426950408889634f;
;   float pmax = p0[0];
; #pragma unroll
;   for (int r = 1; r < 16; ++r) pmax = fmaxf(pmax, p0[r]);
; #pragma unroll
;   for (int r = 0; r < 16; ++r) pmax = fmaxf(pmax, p1[r]);
;   { auto rr = __builtin_amdgcn_permlane32_swap(__float_as_uint(pmax), __float_as_uint(pmax), false, false);
;     pmax = fmaxf(__uint_as_float(rr[0]), __uint_as_float(rr[1])); }
;   if (__builtin_expect(__all(pmax - m_reg <= THR / SCALE), 1)) { mn = m_reg; alpha = 1.f; }
;   else { mn = fmaxf(m_reg, pmax); alpha = __builtin_amdgcn_exp2f((m_reg - mn) * C); m_reg = mn; }
;   float mnC = -mn * C;
; #pragma unroll
;   for (int r = 0; r < 16; ++r) p0[r] = fmaf(p0[r], C, mnC);
; #pragma unroll
;   for (int r = 0; r < 16; ++r) p1[r] = fmaf(p1[r], C, mnC);
; #pragma unroll
;   for (int r = 0; r < 16; ++r) p0[r] = __builtin_amdgcn_exp2f(p0[r]);
; }
; __device__ __forceinline__ void attn_diff_dma(const bf16_t* __restrict__ Qb, const bf16_t* __restrict__ Kh, const bf16_t* __restrict__ Vh, bf16_t* __restrict__ Ob,
;                                               int seq, char* lds, float lam, const float* __restrict__ gsub, const int tid) {
;     ...
;   DMA_TILE(0, 0, 0); TILE_BAR();
;   qkt_diff<0>(pA0, pA1, ka, qr); partialSM<0>(pA0, pA1, m_reg, mnA, alA);
;   DMA_TILE(KVBLK, 1, 1); TILE_BAR();
	ds_read_b128 v[0:3], v138
	ds_read_b128 v[16:19], v138 offset:8192
	s_waitcnt vmcnt(0) lgkmcnt(0)
	v_mfma_f32_32x32x16_bf16 v[0:15], v[0:3], v[108:111], 0
	ds_read_b128 v[32:35], v141
	ds_read_b128 v[36:39], v141 offset:8192
	s_add_u32 s14, s14, 0x20000
	s_mov_b32 s54, s52
	s_mov_b32 s55, s52
	s_mov_b32 s58, s52
	s_mov_b32 s59, s52
	s_mov_b32 s60, s52
	v_mfma_f32_32x32x16_bf16 v[16:31], v[16:19], v[108:111], 0
	s_mov_b32 s61, s52
	s_mov_b32 s62, s52
	s_mov_b32 s63, s52
	s_mov_b32 s64, s52
	s_mov_b32 s65, s52
	s_mov_b32 s66, s52
	s_mov_b32 s67, s52
	s_waitcnt lgkmcnt(1)
	v_mfma_f32_32x32x16_bf16 v[0:15], v[32:35], v[104:107], v[0:15]
	v_bitop3_b32 v32, v162, v44, 64 bitop3:0x36
	v_add_u32_e32 v140, v32, v43
	v_xor_b32_e32 v140, v140, v243
	v_add_u32_e32 v140, v140, v242
	ds_read_b128 v[32:35], v140
	s_addc_u32 s15, s15, 0
	v_mov_b32_e32 v52, v136
	s_mov_b32 s47, 1
	v_mov_b32_e32 v131, 0
	s_waitcnt lgkmcnt(1)
	v_mfma_f32_32x32x16_bf16 v[16:31], v[36:39], v[104:107], v[16:31]
	v_lshlrev_b32_e32 v36, 1, v130
	v_and_b32_e32 v36, 32, v36
	v_and_or_b32 v36, v40, s48, v36
	v_and_b32_e32 v37, 0x100, v41
	v_or3_b32 v40, v36, v37, v42
	ds_read_b128 v[36:39], v140 offset:8192
	v_add_u32_e32 v133, s56, v40
	s_waitcnt lgkmcnt(1)
	v_mfma_f32_32x32x16_bf16 v[0:15], v[32:35], v[100:103], v[0:15]
	v_bitop3_b32 v32, v162, v44, s57 bitop3:0x36
	v_add_u32_e32 v139, v32, v43
	v_xor_b32_e32 v139, v139, v243
	v_add_u32_e32 v139, v139, v242
	ds_read_b128 v[32:35], v139
	ds_read_b128 v[48:51], v139 offset:8192
	s_mov_b32 s56, s52
	s_mov_b32 s57, s52
	s_waitcnt lgkmcnt(2)
	v_mfma_f32_32x32x16_bf16 v[16:31], v[36:39], v[100:103], v[16:31]
	s_waitcnt lgkmcnt(1)
	v_mfma_f32_32x32x16_bf16 v[0:15], v[32:35], v[96:99], v[0:15]
	v_mov_b64_e32 v[32:33], s[52:53]
	v_mov_b64_e32 v[34:35], s[54:55]
	v_mov_b64_e32 v[36:37], s[56:57]
	v_mov_b64_e32 v[38:39], s[58:59]
	v_mov_b64_e32 v[40:41], s[60:61]
	v_mov_b64_e32 v[42:43], s[62:63]
	v_mov_b64_e32 v[44:45], s[64:65]
	v_mov_b64_e32 v[46:47], s[66:67]
	s_add_u32 s54, s16, 0x20000
	s_waitcnt lgkmcnt(0)
	v_mfma_f32_32x32x16_bf16 v[16:31], v[48:51], v[96:99], v[16:31]
	s_nop 0
	v_max_f32_e32 v48, v1, v1
	v_max_f32_e32 v49, v0, v0
	s_addc_u32 s55, s17, 0
	s_add_i32 s16, s42, 0x10000
	v_max_f32_e32 v48, v49, v48
	v_mov_b32_e32 v49, v135
	v_mov_b32_e32 v50, v137
	v_mov_b32_e32 v51, v134
	s_mov_b32 m0, s16
	s_add_i32 s17, s42, 0x12000
	s_add_i32 s53, s42, 0x4000
	v_max3_f32 v48, v48, v2, v3
	global_load_lds_dwordx4 v51, s[14:15]
	s_mov_b32 m0, s17
	v_max3_f32 v48, v48, v4, v5
	global_load_lds_dwordx4 v49, s[14:15]
	s_mov_b32 m0, s53
	v_max3_f32 v48, v48, v6, v7
	global_load_lds_dwordx4 v52, s[54:55]
	s_add_i32 m0, s42, 0x6000
	v_max3_f32 v48, v48, v8, v9
	global_load_lds_dwordx4 v50, s[54:55]
	v_max3_f32 v48, v48, v10, v11
	v_max3_f32 v48, v48, v12, v13
	v_max3_f32 v48, v48, v14, v15
	v_max3_f32 v48, v48, v16, v17
	v_max3_f32 v48, v48, v18, v19
	v_max3_f32 v48, v48, v20, v21
	v_max3_f32 v48, v48, v22, v23
	v_max3_f32 v48, v48, v24, v25
	v_max3_f32 v48, v48, v26, v27
	v_max3_f32 v48, v48, v28, v29
	v_max3_f32 v48, v48, v30, v31
	v_mov_b32_e32 v49, v48
	s_nop 1
	v_permlane32_swap_b32_e32 v48, v49
	v_max_f32_e32 v49, v49, v49
	v_max_f32_e32 v48, v48, v48
	v_max_f32_e32 v48, v48, v49
	v_add_f32_e32 v49, 0x7149f2ca, v48
	v_cmp_ge_f32_e32 vcc, s70, v49
	s_cmp_eq_u64 vcc, exec
	v_max_f32_e32 v48, 0xf149f2ca, v48
	s_cselect_b64 vcc, -1, 0
	v_cndmask_b32_e32 v143, v48, v183, vcc
	v_sub_f32_e32 v49, 0xf149f2ca, v48
	v_mul_f32_e32 v48, 0xbf800000, v143
	v_fmamk_f32 v0, v0, 0x3f800000, v48
	v_exp_f32_e32 v113, v0
	v_fmamk_f32 v0, v1, 0x3f800000, v48
	v_exp_f32_e32 v155, v0
	v_fmamk_f32 v0, v2, 0x3f800000, v48
	v_exp_f32_e32 v152, v0
	v_fmamk_f32 v0, v3, 0x3f800000, v48
	v_exp_f32_e32 v156, v0
	v_fmamk_f32 v0, v4, 0x3f800000, v48
	v_exp_f32_e32 v153, v0
	v_fmamk_f32 v0, v5, 0x3f800000, v48
	v_exp_f32_e32 v158, v0
	v_fmamk_f32 v0, v6, 0x3f800000, v48
	v_exp_f32_e32 v154, v0
	v_fmamk_f32 v0, v7, 0x3f800000, v48
	v_exp_f32_e32 v159, v0
	v_fmamk_f32 v0, v8, 0x3f800000, v48
	v_mul_f32_e32 v49, 0x3f800000, v49
	v_exp_f32_e32 v144, v0
	v_fmamk_f32 v0, v9, 0x3f800000, v48
	v_exp_f32_e32 v49, v49
	v_exp_f32_e32 v148, v0
	v_fmamk_f32 v0, v10, 0x3f800000, v48
	v_exp_f32_e32 v145, v0
	v_fmamk_f32 v0, v11, 0x3f800000, v48
	v_exp_f32_e32 v149, v0
	v_fmamk_f32 v0, v12, 0x3f800000, v48
	s_mov_b32 s14, 0x3f800000
	v_exp_f32_e32 v146, v0
	v_fmamk_f32 v0, v13, 0x3f800000, v48
	v_pk_fma_f32 v[122:123], v[30:31], s[14:15], v[48:49] op_sel_hi:[1,0,0]
	v_pk_fma_f32 v[114:115], v[28:29], s[14:15], v[48:49] op_sel_hi:[1,0,0]
	v_pk_fma_f32 v[116:117], v[26:27], s[14:15], v[48:49] op_sel_hi:[1,0,0]
	v_pk_fma_f32 v[118:119], v[24:25], s[14:15], v[48:49] op_sel_hi:[1,0,0]
	v_pk_fma_f32 v[120:121], v[22:23], s[14:15], v[48:49] op_sel_hi:[1,0,0]
	v_pk_fma_f32 v[124:125], v[20:21], s[14:15], v[48:49] op_sel_hi:[1,0,0]
	v_pk_fma_f32 v[126:127], v[18:19], s[14:15], v[48:49] op_sel_hi:[1,0,0]
	v_pk_fma_f32 v[128:129], v[16:17], s[14:15], v[48:49] op_sel_hi:[1,0,0]
	v_exp_f32_e32 v150, v0
	v_fmamk_f32 v0, v14, 0x3f800000, v48
	v_fmac_f32_e32 v48, 0x3f800000, v15
	v_exp_f32_e32 v147, v0
	v_exp_f32_e32 v151, v48
	s_waitcnt vmcnt(0) lgkmcnt(0)
	s_or_b32 s4, s4, s50
	v_cndmask_b32_e64 v142, v49, 1.0, vcc
	s_add_u32 s14, s36, s4
	v_mov_b64_e32 v[62:63], v[46:47]
	v_mov_b64_e32 v[16:17], v[32:33]
	v_mov_b64_e32 v[0:1], v[32:33]
	s_addc_u32 s15, s37, s5
	s_mov_b32 s50, 2
	v_mov_b64_e32 v[60:61], v[44:45]
	v_mov_b64_e32 v[58:59], v[42:43]
	v_mov_b64_e32 v[56:57], v[40:41]
	v_mov_b64_e32 v[54:55], v[38:39]
	v_mov_b64_e32 v[52:53], v[36:37]
	v_mov_b64_e32 v[50:51], v[34:35]
	v_mov_b64_e32 v[48:49], v[32:33]
	v_mov_b64_e32 v[18:19], v[34:35]
	v_mov_b64_e32 v[20:21], v[36:37]
	v_mov_b64_e32 v[22:23], v[38:39]
	v_mov_b64_e32 v[24:25], v[40:41]
	v_mov_b64_e32 v[26:27], v[42:43]
	v_mov_b64_e32 v[28:29], v[44:45]
	v_mov_b64_e32 v[30:31], v[46:47]
	v_mov_b64_e32 v[2:3], v[34:35]
	v_mov_b64_e32 v[4:5], v[36:37]
	v_mov_b64_e32 v[6:7], v[38:39]
	v_mov_b64_e32 v[8:9], v[40:41]
	v_mov_b64_e32 v[10:11], v[42:43]
	v_mov_b64_e32 v[12:13], v[44:45]
	v_mov_b64_e32 v[14:15], v[46:47]
	s_mov_b32 s53, 2
	v_exp_f32_e32 v114, v114
	v_exp_f32_e32 v115, v115
	v_exp_f32_e32 v116, v116
	v_exp_f32_e32 v117, v117
	v_exp_f32_e32 v118, v118
	v_exp_f32_e32 v119, v119
	v_exp_f32_e32 v120, v120
	v_exp_f32_e32 v121, v121
	v_exp_f32_e32 v122, v122
	v_exp_f32_e32 v123, v123
	v_exp_f32_e32 v124, v124
	v_exp_f32_e32 v125, v125
	v_exp_f32_e32 v126, v126
	v_exp_f32_e32 v127, v127
	v_exp_f32_e32 v128, v128
	v_exp_f32_e32 v129, v129
	v_sub_f32_e32 v226, 0, v143
	v_sub_f32_e32 v227, 0, v143
	v_sub_f32_e32 v228, 0, v143
	v_sub_f32_e32 v229, 0, v143
	v_sub_f32_e32 v230, 0, v143
	v_sub_f32_e32 v231, 0, v143
	v_sub_f32_e32 v232, 0, v143
	v_sub_f32_e32 v233, 0, v143
	v_sub_f32_e32 v234, 0, v143
	v_sub_f32_e32 v235, 0, v143
	v_sub_f32_e32 v236, 0, v143
	v_sub_f32_e32 v237, 0, v143
	v_sub_f32_e32 v238, 0, v143
	v_sub_f32_e32 v239, 0, v143
	v_sub_f32_e32 v240, 0, v143
	v_sub_f32_e32 v241, 0, v143
	s_barrier
; #define SBAR() __builtin_amdgcn_sched_barrier(0)
; #define RESC(a) do { if (__any((a) < 1.f)) { if (hi == 0) al_l[r32] = (a); asm volatile("s_waitcnt lgkmcnt(0)" ::: "memory"); \
;     for (int d = 0; d < 4; ++d) for (int r = 0; r < 16; ++r) o[d][r] *= al_l[crow_(r, hi)]; } } while (0)
; #define TILE_BAR() do { asm volatile("s_waitcnt vmcnt(0) lgkmcnt(0)" ::: "memory"); __builtin_amdgcn_s_barrier(); } while (0)
; #define RESC(a) do { if (__any((a) < 1.f)) { for (int d = 0; d < 4; ++d) for (int r = 0; r < 16; ++r) o[d][r] *= (a); } } while (0)
; #define TILE_BAR() do { asm volatile("s_waitcnt vmcnt(0) lgkmcnt(0)" ::: "memory"); __builtin_amdgcn_s_barrier(); } while (0)
; __device__ __forceinline__ void finishSM(f32x16& p0, f32x16& p1, float alpha, float& l_reg, bf16x8& pa0, bf16x8& pa1, bf16x8& pa2, bf16x8& pa3) {
; #pragma unroll
;   for (int r = 0; r < 16; ++r) p1[r] = __builtin_amdgcn_exp2f(p1[r]);
;   float ps = 0;
; #pragma unroll
;   for (int r = 0; r < 16; ++r) ps += p0[r];
; #pragma unroll
;   for (int r = 0; r < 16; ++r) ps += p1[r];
;   { auto rr = __builtin_amdgcn_permlane32_swap(__float_as_uint(ps), __float_as_uint(ps), false, false);
;     ps = __uint_as_float(rr[0]) + __uint_as_float(rr[1]); }
;   l_reg = l_reg * alpha + ps;
;     ...
;   PK4(p0, 0, pa0); PK4(p0, 8, pa1); PK4(p1, 0, pa2); PK4(p1, 8, pa3);
;     ...
; }
; __device__ __forceinline__ void attn_diff_dma(const bf16_t* __restrict__ Qb, const bf16_t* __restrict__ Kh, const bf16_t* __restrict__ Vh, bf16_t* __restrict__ Ob,
;                                               int seq, char* lds, float lam, const float* __restrict__ gsub, const int tid) {
;     ...
;   for (int j = 1; j + 1 < NT; j += 2) {
;     SBAR(); qkt_diff<(int)SHM_K128>(pB0, pB1, ka, qr);
;     finishSM(pA0, pA1, alA, l_reg, pa0, pa1, pa2, pa3); SBAR();
;     DMA_TILE((j + 1) * KVBLK, 0, vnxt); SBAR();
;     pv_d0_t(o, vb0 + vprev * SHM_VV, pa0, pa1, pa2, pa3); partialSM<0>(pB0, pB1, m_reg, mnB, alB);
;     TILE_BAR();
;     RESC(alB);
;     { const int t = vprev; vprev = vcur; vcur = vnxt; vnxt = t; }
;     SBAR(); qkt_diff<0>(pA0, pA1, ka, qr);
;     finishSM(pB0, pB1, alB, l_reg, pa0, pa1, pa2, pa3); SBAR();
;     DMA_TILE((j + 2) * KVBLK, 1, vnxt); SBAR();
;     pv_d0_t(o, vb0 + vprev * SHM_VV, pa0, pa1, pa2, pa3); partialSM<0>(pA0, pA1, m_reg, mnA, alA);
.LBB0_129:
	s_mov_b32 s54, s47
	s_mov_b32 s47, s52
	ds_read_b128 v[64:67], v138 offset:16384
	ds_read_b128 v[68:71], v138 offset:24576
	ds_read_b128 v[170:173], v141 offset:16384
	ds_read_b128 v[188:191], v141 offset:24576
	v_add_f32_e32 v112, v155, v113
	s_waitcnt lgkmcnt(0)
	v_mfma_f32_32x32x16_bf16 v[80:95], v[64:67], v[108:111], v[226:241]
	v_add_f32_e32 v112, v152, v112
	v_add_f32_e32 v112, v156, v112
	v_add_f32_e32 v112, v153, v112
	v_add_f32_e32 v112, v158, v112
	v_add_f32_e32 v112, v154, v112
	v_add_f32_e32 v112, v159, v112
	v_add_f32_e32 v112, v144, v112
	v_mfma_f32_32x32x16_bf16 v[64:79], v[68:71], v[108:111], v[226:241]
	v_add_f32_e32 v112, v148, v112
	v_add_f32_e32 v112, v145, v112
	v_add_f32_e32 v112, v149, v112
	v_add_f32_e32 v112, v146, v112
	v_add_f32_e32 v112, v150, v112
	v_mfma_f32_32x32x16_bf16 v[80:95], v[170:173], v[104:107], v[80:95]
	v_add_f32_e32 v112, v147, v112
	v_add_f32_e32 v112, v151, v112
	v_mov_b32_e32 v132, v124
	v_add_f32_e32 v112, v128, v112
	v_mov_b32_e32 v162, v125
	v_mfma_f32_32x32x16_bf16 v[64:79], v[188:191], v[104:107], v[64:79]
	ds_read_b128 v[170:173], v140 offset:16384
	ds_read_b128 v[188:191], v140 offset:24576
	v_add_f32_e32 v112, v129, v112
	v_mov_b32_e32 v167, v120
	v_add_f32_e32 v112, v126, v112
	v_mov_b32_e32 v169, v121
	v_add_f32_e32 v112, v127, v112
	v_add_f32_e32 v112, v132, v112
	s_waitcnt lgkmcnt(0)
	v_mfma_f32_32x32x16_bf16 v[80:95], v[170:173], v[100:103], v[80:95]
	v_add_f32_e32 v112, v162, v112
	v_add_f32_e32 v112, v167, v112
	v_add_f32_e32 v112, v169, v112
	v_mfma_f32_32x32x16_bf16 v[64:79], v[188:191], v[100:103], v[64:79]
	ds_read_b128 v[170:173], v139 offset:16384
	ds_read_b128 v[188:191], v139 offset:24576
	s_waitcnt lgkmcnt(0)
	v_mfma_f32_32x32x16_bf16 v[80:95], v[170:173], v[96:99], v[80:95]
	v_mov_b32_e32 v170, v118
	v_mov_b32_e32 v171, v117
	v_mov_b32_e32 v172, v114
	v_mov_b32_e32 v173, v115
	v_add_f32_e32 v112, v170, v112
	v_add_f32_e32 v112, v119, v112
	v_add_f32_e32 v112, v116, v112
	v_mfma_f32_32x32x16_bf16 v[64:79], v[188:191], v[96:99], v[64:79]
	v_mov_b32_e32 v188, v122
	v_mov_b32_e32 v189, v123
	v_add_f32_e32 v112, v171, v112
	v_add_f32_e32 v112, v172, v112
	v_add_f32_e32 v112, v173, v112
	v_add_f32_e32 v112, v188, v112
	v_add_f32_e32 v117, v189, v112
	v_mov_b32_e32 v118, v117
	v_cvt_pk_bf16_f32 v112, v113, v155
	v_cvt_pk_bf16_f32 v113, v152, v156
	v_cvt_pk_bf16_f32 v114, v153, v158
	s_nop 1
	v_permlane32_swap_b32_e32 v117, v118
	v_cvt_pk_bf16_f32 v115, v154, v159
	v_cvt_pk_bf16_f32 v120, v144, v148
	v_cvt_pk_bf16_f32 v121, v145, v149
	v_cvt_pk_bf16_f32 v122, v146, v150
	v_cvt_pk_bf16_f32 v123, v147, v151
	v_cvt_pk_bf16_f32 v124, v128, v129
	v_cvt_pk_bf16_f32 v125, v126, v127
	v_cvt_pk_bf16_f32 v126, v132, v162
	v_cvt_pk_bf16_f32 v127, v167, v169
	v_cvt_pk_bf16_f32 v144, v170, v119
	v_cvt_pk_bf16_f32 v145, v116, v171
	v_cvt_pk_bf16_f32 v146, v172, v173
	v_cvt_pk_bf16_f32 v147, v188, v189
	s_add_u32 s4, s14, 0x2000000
	s_mov_b32 m0, s43
	s_addc_u32 s5, s15, 0
	s_mov_b64 s[56:57], s[14:15]
	s_lshl_b32 s52, s53, 14
	s_add_i32 s55, s42, s52
	s_nop 0
	global_load_lds_dwordx4 v134, s[56:57]
	s_mov_b32 m0, s44
	s_nop 0
	global_load_lds_dwordx4 v135, s[56:57]
	s_mov_b32 m0, s55
	s_nop 0
	global_load_lds_dwordx4 v136, s[4:5]
	s_add_i32 m0, s55, 0x2000
	s_nop 0
	global_load_lds_dwordx4 v137, s[4:5]
	s_lshl_b32 s55, s47, 14
	v_add_u32_e32 v132, s55, v133
	ds_read_b64_tr_b16 v[148:149], v132 offset:0
	ds_read_b64_tr_b16 v[150:151], v132 offset:0x800
	ds_read_b64_tr_b16 v[152:153], v132 offset:0x1000
	ds_read_b64_tr_b16 v[154:155], v132 offset:0x1800
	ds_read_b64_tr_b16 v[170:171], v132 offset:0x2000
	ds_read_b64_tr_b16 v[172:173], v132 offset:0x2800
	ds_read_b64_tr_b16 v[188:189], v132 offset:0x3000
	ds_read_b64_tr_b16 v[190:191], v132 offset:0x3800
	s_waitcnt lgkmcnt(0)
	s_nop 0
	v_mfma_f32_32x32x16_bf16 v[32:47], v[148:151], v[112:115], v[32:47]
	ds_read_b64_tr_b16 v[148:149], v132 offset:0x200
	ds_read_b64_tr_b16 v[150:151], v132 offset:0xa00
	v_mfma_f32_32x32x16_bf16 v[32:47], v[152:155], v[120:123], v[32:47]
	ds_read_b64_tr_b16 v[152:153], v132 offset:0x1200
	ds_read_b64_tr_b16 v[154:155], v132 offset:0x1a00
	v_mfma_f32_32x32x16_bf16 v[32:47], v[170:173], v[124:127], v[32:47]
	ds_read_b64_tr_b16 v[170:171], v132 offset:0x2200
	ds_read_b64_tr_b16 v[172:173], v132 offset:0x2a00
	v_mfma_f32_32x32x16_bf16 v[32:47], v[188:191], v[144:147], v[32:47]
	ds_read_b64_tr_b16 v[188:189], v132 offset:0x3200
	ds_read_b64_tr_b16 v[190:191], v132 offset:0x3a00
	s_waitcnt lgkmcnt(0)
	v_mfma_f32_32x32x16_bf16 v[48:63], v[148:151], v[112:115], v[48:63]
	ds_read_b64_tr_b16 v[148:149], v132 offset:0x400
	ds_read_b64_tr_b16 v[150:151], v132 offset:0xc00
	v_mfma_f32_32x32x16_bf16 v[48:63], v[152:155], v[120:123], v[48:63]
	ds_read_b64_tr_b16 v[152:153], v132 offset:0x1400
	ds_read_b64_tr_b16 v[154:155], v132 offset:0x1c00
	v_mfma_f32_32x32x16_bf16 v[48:63], v[170:173], v[124:127], v[48:63]
	ds_read_b64_tr_b16 v[170:171], v132 offset:0x2400
	ds_read_b64_tr_b16 v[172:173], v132 offset:0x2c00
	v_mfma_f32_32x32x16_bf16 v[48:63], v[188:191], v[144:147], v[48:63]
	ds_read_b64_tr_b16 v[188:189], v132 offset:0x3400
	ds_read_b64_tr_b16 v[190:191], v132 offset:0x3c00
	s_waitcnt lgkmcnt(0)
	v_mfma_f32_32x32x16_bf16 v[16:31], v[148:151], v[112:115], v[16:31]
	ds_read_b64_tr_b16 v[148:149], v132 offset:0x600
	ds_read_b64_tr_b16 v[150:151], v132 offset:0xe00
	v_mfma_f32_32x32x16_bf16 v[16:31], v[152:155], v[120:123], v[16:31]
	ds_read_b64_tr_b16 v[152:153], v132 offset:0x1600
	ds_read_b64_tr_b16 v[154:155], v132 offset:0x1e00
	v_mfma_f32_32x32x16_bf16 v[16:31], v[170:173], v[124:127], v[16:31]
	ds_read_b64_tr_b16 v[170:171], v132 offset:0x2600
	ds_read_b64_tr_b16 v[172:173], v132 offset:0x2e00
	v_mfma_f32_32x32x16_bf16 v[16:31], v[188:191], v[144:147], v[16:31]
	ds_read_b64_tr_b16 v[188:189], v132 offset:0x3600
	ds_read_b64_tr_b16 v[190:191], v132 offset:0x3e00
	s_waitcnt lgkmcnt(0)
	v_mfma_f32_32x32x16_bf16 v[0:15], v[148:151], v[112:115], v[0:15]
	v_max_f32_e32 v112, v80, v81
	v_max3_f32 v112, v112, v82, v83
	v_max3_f32 v112, v112, v84, v85
	v_max3_f32 v112, v112, v86, v87
	v_max3_f32 v112, v112, v88, v89
	v_max3_f32 v112, v112, v90, v91
	v_max3_f32 v112, v112, v92, v93
	v_mfma_f32_32x32x16_bf16 v[0:15], v[152:155], v[120:123], v[0:15]
	v_max3_f32 v112, v112, v94, v95
	v_max3_f32 v112, v112, v64, v65
	v_max3_f32 v112, v112, v66, v67
	v_max3_f32 v112, v112, v68, v69
	v_max3_f32 v112, v112, v70, v71
	v_max3_f32 v112, v112, v72, v73
	v_max3_f32 v112, v112, v74, v75
	v_max3_f32 v112, v112, v76, v77
	v_mfma_f32_32x32x16_bf16 v[0:15], v[170:173], v[124:127], v[0:15]
	v_max3_f32 v112, v112, v78, v79
	v_mov_b32_e32 v113, v112
	s_nop 1
	v_permlane32_swap_b32_e32 v112, v113
	v_max_f32_e32 v112, v112, v113
	v_cmp_ge_f32_e32 vcc, s70, v112
	v_mfma_f32_32x32x16_bf16 v[0:15], v[188:191], v[144:147], v[0:15]
	s_cmp_eq_u64 vcc, exec
	s_cselect_b64 s[4:5], -1, 0
	s_waitcnt vmcnt(0) lgkmcnt(0)
	s_barrier
; #define SBAR() __builtin_amdgcn_sched_barrier(0)
; #define RESC(a) do { if (__any((a) < 1.f)) { if (hi == 0) al_l[r32] = (a); asm volatile("s_waitcnt lgkmcnt(0)" ::: "memory"); \
;     for (int d = 0; d < 4; ++d) for (int r = 0; r < 16; ++r) o[d][r] *= al_l[crow_(r, hi)]; } } while (0)
; #define RESC(a) do { if (__any((a) < 1.f)) { for (int d = 0; d < 4; ++d) for (int r = 0; r < 16; ++r) o[d][r] *= (a); } } while (0)
; #define RESC(a) do { if (__any((a) < 1.f)) { for (int d = 0; d < 4; ++d) for (int r = 0; r < 16; ++r) o[d][r] *= (a); } } while (0)
; template <int MLA>
; __device__ __forceinline__ void partialSM(f32x16& p0, f32x16& p1, float& m_reg, float& mn, float& alpha) {
;   constexpr float SCALE = AttC<MLA>::SCALE;
;   constexpr float C = SCALE * 1.4426950408889634f;
;   float pmax = p0[0];
; #pragma unroll
;   for (int r = 1; r < 16; ++r) pmax = fmaxf(pmax, p0[r]);
; #pragma unroll
;   for (int r = 0; r < 16; ++r) pmax = fmaxf(pmax, p1[r]);
;   { auto rr = __builtin_amdgcn_permlane32_swap(__float_as_uint(pmax), __float_as_uint(pmax), false, false);
;     pmax = fmaxf(__uint_as_float(rr[0]), __uint_as_float(rr[1])); }
;   if (__builtin_expect(__all(pmax - m_reg <= THR / SCALE), 1)) { mn = m_reg; alpha = 1.f; }
;   else { mn = fmaxf(m_reg, pmax); alpha = __builtin_amdgcn_exp2f((m_reg - mn) * C); m_reg = mn; }
;   float mnC = -mn * C;
; #pragma unroll
;   for (int r = 0; r < 16; ++r) p0[r] = fmaf(p0[r], C, mnC);
; #pragma unroll
;   for (int r = 0; r < 16; ++r) p1[r] = fmaf(p1[r], C, mnC);
; #pragma unroll
;   for (int r = 0; r < 16; ++r) p0[r] = __builtin_amdgcn_exp2f(p0[r]);
; }
; __device__ __forceinline__ void attn_diff_dma(const bf16_t* __restrict__ Qb, const bf16_t* __restrict__ Kh, const bf16_t* __restrict__ Vh, bf16_t* __restrict__ Ob,
;                                               int seq, char* lds, float lam, const float* __restrict__ gsub, const int tid) {
;     ...
;     RESC(alB);
;     { const int t = vprev; vprev = vcur; vcur = vnxt; vnxt = t; }
;     SBAR(); qkt_diff<0>(pA0, pA1, ka, qr);
	s_cbranch_scc1 .Lal_c_d1
	v_max_f32_e32 v242, 0, v112
	v_exp_f32_e64 v116, -v242
	s_nop 0
	v_pk_mul_f32 v[46:47], v[46:47], v[116:117] op_sel_hi:[1,0]
	v_pk_mul_f32 v[44:45], v[44:45], v[116:117] op_sel_hi:[1,0]
	v_pk_mul_f32 v[42:43], v[42:43], v[116:117] op_sel_hi:[1,0]
	v_pk_mul_f32 v[40:41], v[40:41], v[116:117] op_sel_hi:[1,0]
	v_pk_mul_f32 v[38:39], v[38:39], v[116:117] op_sel_hi:[1,0]
	v_pk_mul_f32 v[36:37], v[36:37], v[116:117] op_sel_hi:[1,0]
	v_pk_mul_f32 v[34:35], v[34:35], v[116:117] op_sel_hi:[1,0]
	v_pk_mul_f32 v[32:33], v[32:33], v[116:117] op_sel_hi:[1,0]
	v_pk_mul_f32 v[62:63], v[62:63], v[116:117] op_sel_hi:[1,0]
	v_pk_mul_f32 v[60:61], v[60:61], v[116:117] op_sel_hi:[1,0]
	v_pk_mul_f32 v[58:59], v[58:59], v[116:117] op_sel_hi:[1,0]
	v_pk_mul_f32 v[56:57], v[56:57], v[116:117] op_sel_hi:[1,0]
	v_pk_mul_f32 v[54:55], v[54:55], v[116:117] op_sel_hi:[1,0]
	v_pk_mul_f32 v[52:53], v[52:53], v[116:117] op_sel_hi:[1,0]
	v_pk_mul_f32 v[50:51], v[50:51], v[116:117] op_sel_hi:[1,0]
	v_pk_mul_f32 v[48:49], v[48:49], v[116:117] op_sel_hi:[1,0]
	v_pk_mul_f32 v[30:31], v[30:31], v[116:117] op_sel_hi:[1,0]
	v_pk_mul_f32 v[28:29], v[28:29], v[116:117] op_sel_hi:[1,0]
	v_pk_mul_f32 v[26:27], v[26:27], v[116:117] op_sel_hi:[1,0]
	v_pk_mul_f32 v[24:25], v[24:25], v[116:117] op_sel_hi:[1,0]
	v_pk_mul_f32 v[22:23], v[22:23], v[116:117] op_sel_hi:[1,0]
	v_pk_mul_f32 v[20:21], v[20:21], v[116:117] op_sel_hi:[1,0]
	v_pk_mul_f32 v[18:19], v[18:19], v[116:117] op_sel_hi:[1,0]
	v_pk_mul_f32 v[16:17], v[16:17], v[116:117] op_sel_hi:[1,0]
	v_pk_mul_f32 v[14:15], v[14:15], v[116:117] op_sel_hi:[1,0]
	v_pk_mul_f32 v[12:13], v[12:13], v[116:117] op_sel_hi:[1,0]
	v_pk_mul_f32 v[10:11], v[10:11], v[116:117] op_sel_hi:[1,0]
	v_pk_mul_f32 v[8:9], v[8:9], v[116:117] op_sel_hi:[1,0]
	v_pk_mul_f32 v[6:7], v[6:7], v[116:117] op_sel_hi:[1,0]
	v_pk_mul_f32 v[4:5], v[4:5], v[116:117] op_sel_hi:[1,0]
	v_pk_mul_f32 v[2:3], v[2:3], v[116:117] op_sel_hi:[1,0]
	v_pk_mul_f32 v[0:1], v[0:1], v[116:117] op_sel_hi:[1,0]
	v_sub_f32_e32 v80, v80, v242
	v_sub_f32_e32 v81, v81, v242
	v_sub_f32_e32 v82, v82, v242
	v_sub_f32_e32 v83, v83, v242
	v_sub_f32_e32 v84, v84, v242
	v_sub_f32_e32 v85, v85, v242
	v_sub_f32_e32 v86, v86, v242
	v_sub_f32_e32 v87, v87, v242
	v_sub_f32_e32 v88, v88, v242
	v_sub_f32_e32 v89, v89, v242
	v_sub_f32_e32 v90, v90, v242
	v_sub_f32_e32 v91, v91, v242
	v_sub_f32_e32 v92, v92, v242
	v_sub_f32_e32 v93, v93, v242
	v_sub_f32_e32 v94, v94, v242
	v_sub_f32_e32 v95, v95, v242
	v_sub_f32_e32 v64, v64, v242
	v_sub_f32_e32 v65, v65, v242
	v_sub_f32_e32 v66, v66, v242
	v_sub_f32_e32 v67, v67, v242
	v_sub_f32_e32 v68, v68, v242
	v_sub_f32_e32 v69, v69, v242
	v_sub_f32_e32 v70, v70, v242
	v_sub_f32_e32 v71, v71, v242
	v_sub_f32_e32 v72, v72, v242
	v_sub_f32_e32 v73, v73, v242
	v_sub_f32_e32 v74, v74, v242
	v_sub_f32_e32 v75, v75, v242
	v_sub_f32_e32 v76, v76, v242
	v_sub_f32_e32 v77, v77, v242
	v_sub_f32_e32 v78, v78, v242
	v_sub_f32_e32 v79, v79, v242
	v_sub_f32_e32 v226, v226, v242
	v_sub_f32_e32 v227, v227, v242
	v_sub_f32_e32 v228, v228, v242
	v_sub_f32_e32 v229, v229, v242
	v_sub_f32_e32 v230, v230, v242
	v_sub_f32_e32 v231, v231, v242
	v_sub_f32_e32 v232, v232, v242
	v_sub_f32_e32 v233, v233, v242
	v_sub_f32_e32 v234, v234, v242
	v_sub_f32_e32 v235, v235, v242
	v_sub_f32_e32 v236, v236, v242
	v_sub_f32_e32 v237, v237, v242
	v_sub_f32_e32 v238, v238, v242
	v_sub_f32_e32 v239, v239, v242
	v_sub_f32_e32 v240, v240, v242
	v_sub_f32_e32 v241, v241, v242
	s_branch .LBB0_131
.Lal_c_d1:
	v_mov_b32_e32 v116, 1.0
.LBB0_131:
	v_exp_f32_e32 v125, v64
	v_exp_f32_e32 v126, v65
	v_exp_f32_e32 v127, v66
	v_exp_f32_e32 v128, v67
	v_exp_f32_e32 v129, v68
	v_exp_f32_e32 v143, v69
	v_exp_f32_e32 v144, v70
	v_exp_f32_e32 v145, v71
	v_exp_f32_e32 v146, v72
	v_exp_f32_e32 v147, v73
	v_exp_f32_e32 v148, v74
	v_exp_f32_e32 v149, v75
	v_exp_f32_e32 v150, v76
	v_exp_f32_e32 v151, v80
	v_exp_f32_e32 v152, v81
	v_exp_f32_e32 v153, v82
	v_exp_f32_e32 v154, v83
	v_exp_f32_e32 v155, v84
	v_exp_f32_e32 v156, v85
	v_exp_f32_e32 v158, v86
	v_exp_f32_e32 v159, v87
	v_exp_f32_e32 v162, v88
	v_exp_f32_e32 v167, v89
	v_exp_f32_e32 v169, v90
	v_exp_f32_e32 v170, v91
	v_exp_f32_e32 v171, v92
	v_exp_f32_e32 v172, v93
	v_exp_f32_e32 v173, v94
	v_exp_f32_e32 v188, v95
	v_exp_f32_e32 v189, v77
	v_exp_f32_e32 v190, v78
	v_exp_f32_e32 v124, v79
	ds_read_b128 v[64:67], v138
	ds_read_b128 v[68:71], v138 offset:8192
	ds_read_b128 v[112:115], v141
	ds_read_b128 v[120:123], v141 offset:8192
	v_mov_b32_e32 v191, v125
	s_waitcnt lgkmcnt(0)
	v_mfma_f32_32x32x16_bf16 v[80:95], v[64:67], v[108:111], v[226:241]
	v_mfma_f32_32x32x16_bf16 v[64:79], v[68:71], v[108:111], v[226:241]
	v_mov_b32_e32 v192, v124
	v_mfma_f32_32x32x16_bf16 v[80:95], v[112:115], v[104:107], v[80:95]
	v_mfma_f32_32x32x16_bf16 v[64:79], v[120:123], v[104:107], v[64:79]
	ds_read_b128 v[112:115], v140
	ds_read_b128 v[120:123], v140 offset:8192
	s_waitcnt lgkmcnt(0)
	v_mfma_f32_32x32x16_bf16 v[80:95], v[112:115], v[100:103], v[80:95]
	v_mfma_f32_32x32x16_bf16 v[64:79], v[120:123], v[100:103], v[64:79]
	ds_read_b128 v[112:115], v139
	ds_read_b128 v[120:123], v139 offset:8192
	s_waitcnt lgkmcnt(0)
; #define SBAR() __builtin_amdgcn_sched_barrier(0)
; __device__ __forceinline__ void finishSM(f32x16& p0, f32x16& p1, float alpha, float& l_reg, bf16x8& pa0, bf16x8& pa1, bf16x8& pa2, bf16x8& pa3) {
; #pragma unroll
;   for (int r = 0; r < 16; ++r) p1[r] = __builtin_amdgcn_exp2f(p1[r]);
;   float ps = 0;
; #pragma unroll
;   for (int r = 0; r < 16; ++r) ps += p0[r];
; #pragma unroll
;   for (int r = 0; r < 16; ++r) ps += p1[r];
;   { auto rr = __builtin_amdgcn_permlane32_swap(__float_as_uint(ps), __float_as_uint(ps), false, false);
;     ps = __uint_as_float(rr[0]) + __uint_as_float(rr[1]); }
;   l_reg = l_reg * alpha + ps;
;     ...
;   PK4(p0, 0, pa0); PK4(p0, 8, pa1); PK4(p1, 0, pa2); PK4(p1, 8, pa3);
;     ...
; }
; __device__ __forceinline__ void attn_diff_dma(const bf16_t* __restrict__ Qb, const bf16_t* __restrict__ Kh, const bf16_t* __restrict__ Vh, bf16_t* __restrict__ Ob,
;                                               int seq, char* lds, float lam, const float* __restrict__ gsub, const int tid) {
;     ...
;     SBAR(); qkt_diff<0>(pA0, pA1, ka, qr);
;     finishSM(pB0, pB1, alB, l_reg, pa0, pa1, pa2, pa3); SBAR();
;     DMA_TILE((j + 2) * KVBLK, 1, vnxt); SBAR();
;     pv_d0_t(o, vb0 + vprev * SHM_VV, pa0, pa1, pa2, pa3); partialSM<0>(pA0, pA1, m_reg, mnA, alA);
	v_mfma_f32_32x32x16_bf16 v[80:95], v[112:115], v[96:99], v[80:95]
	v_add_f32_e32 v112, v152, v151
	v_add_f32_e32 v112, v153, v112
	v_add_f32_e32 v112, v154, v112
	v_add_f32_e32 v112, v155, v112
	v_add_f32_e32 v112, v156, v112
	v_add_f32_e32 v112, v158, v112
	v_add_f32_e32 v112, v159, v112
	v_add_f32_e32 v112, v162, v112
	v_add_f32_e32 v112, v167, v112
	v_add_f32_e32 v112, v169, v112
	v_add_f32_e32 v112, v170, v112
	v_add_f32_e32 v112, v171, v112
	v_add_f32_e32 v112, v172, v112
	v_add_f32_e32 v112, v173, v112
	v_add_f32_e32 v112, v188, v112
	v_add_f32_e32 v112, v191, v112
	v_add_f32_e32 v112, v126, v112
	v_add_f32_e32 v112, v127, v112
	v_add_f32_e32 v112, v128, v112
	v_add_f32_e32 v112, v129, v112
	v_add_f32_e32 v112, v143, v112
	v_add_f32_e32 v112, v144, v112
	v_add_f32_e32 v112, v145, v112
	v_add_f32_e32 v112, v146, v112
	v_add_f32_e32 v112, v147, v112
	v_mfma_f32_32x32x16_bf16 v[64:79], v[120:123], v[96:99], v[64:79]
	v_add_f32_e32 v112, v148, v112
	v_add_f32_e32 v112, v149, v112
	v_add_f32_e32 v112, v150, v112
	v_add_f32_e32 v112, v189, v112
	v_add_f32_e32 v112, v190, v112
	v_add_f32_e32 v120, v192, v112
	v_mov_b32_e32 v121, v120
	v_cvt_pk_bf16_f32 v112, v151, v152
	v_cvt_pk_bf16_f32 v113, v153, v154
	v_cvt_pk_bf16_f32 v114, v155, v156
	v_cvt_pk_bf16_f32 v115, v158, v159
	s_nop 1
	v_permlane32_swap_b32_e32 v120, v121
	v_cvt_pk_bf16_f32 v122, v162, v167
	v_cvt_pk_bf16_f32 v123, v169, v170
	v_cvt_pk_bf16_f32 v124, v171, v172
	v_cvt_pk_bf16_f32 v125, v173, v188
	v_cvt_pk_bf16_f32 v126, v191, v126
	v_cvt_pk_bf16_f32 v127, v127, v128
	v_cvt_pk_bf16_f32 v128, v129, v143
	v_cvt_pk_bf16_f32 v129, v144, v145
	v_cvt_pk_bf16_f32 v144, v146, v147
	v_cvt_pk_bf16_f32 v145, v148, v149
	v_cvt_pk_bf16_f32 v146, v150, v189
	v_cvt_pk_bf16_f32 v147, v190, v192
	s_nop 0
	s_add_u32 s4, s14, 0x20000
	s_addc_u32 s5, s15, 0
	s_add_u32 s56, s14, 0x2020000
	s_mov_b32 m0, s16
	s_addc_u32 s57, s15, 0
	s_add_i32 s55, s42, s55
	s_nop 0
	global_load_lds_dwordx4 v134, s[4:5]
	s_mov_b32 m0, s17
	s_nop 0
	global_load_lds_dwordx4 v135, s[4:5]
	s_mov_b32 m0, s55
	s_nop 0
	global_load_lds_dwordx4 v136, s[56:57]
	s_add_i32 m0, s55, 0x2000
	s_nop 0
	global_load_lds_dwordx4 v137, s[56:57]
	v_lshl_add_u32 v143, s54, 14, v133
	ds_read_b64_tr_b16 v[148:149], v143 offset:0
	ds_read_b64_tr_b16 v[150:151], v143 offset:0x800
	ds_read_b64_tr_b16 v[152:153], v143 offset:0x1000
	ds_read_b64_tr_b16 v[154:155], v143 offset:0x1800
	ds_read_b64_tr_b16 v[170:171], v143 offset:0x2000
	ds_read_b64_tr_b16 v[172:173], v143 offset:0x2800
	ds_read_b64_tr_b16 v[188:189], v143 offset:0x3000
	ds_read_b64_tr_b16 v[190:191], v143 offset:0x3800
	s_waitcnt lgkmcnt(0)
	s_nop 0
	v_mfma_f32_32x32x16_bf16 v[32:47], v[148:151], v[112:115], v[32:47]
	ds_read_b64_tr_b16 v[148:149], v143 offset:0x200
	ds_read_b64_tr_b16 v[150:151], v143 offset:0xa00
	v_mfma_f32_32x32x16_bf16 v[32:47], v[152:155], v[122:125], v[32:47]
	ds_read_b64_tr_b16 v[152:153], v143 offset:0x1200
	ds_read_b64_tr_b16 v[154:155], v143 offset:0x1a00
	v_mfma_f32_32x32x16_bf16 v[32:47], v[170:173], v[126:129], v[32:47]
	ds_read_b64_tr_b16 v[170:171], v143 offset:0x2200
	ds_read_b64_tr_b16 v[172:173], v143 offset:0x2a00
	v_mfma_f32_32x32x16_bf16 v[32:47], v[188:191], v[144:147], v[32:47]
	ds_read_b64_tr_b16 v[188:189], v143 offset:0x3200
	ds_read_b64_tr_b16 v[190:191], v143 offset:0x3a00
	s_waitcnt lgkmcnt(0)
	v_mfma_f32_32x32x16_bf16 v[48:63], v[148:151], v[112:115], v[48:63]
	ds_read_b64_tr_b16 v[148:149], v143 offset:0x400
	ds_read_b64_tr_b16 v[150:151], v143 offset:0xc00
	v_mfma_f32_32x32x16_bf16 v[48:63], v[152:155], v[122:125], v[48:63]
	ds_read_b64_tr_b16 v[152:153], v143 offset:0x1400
	ds_read_b64_tr_b16 v[154:155], v143 offset:0x1c00
	v_mfma_f32_32x32x16_bf16 v[48:63], v[170:173], v[126:129], v[48:63]
	ds_read_b64_tr_b16 v[170:171], v143 offset:0x2400
	ds_read_b64_tr_b16 v[172:173], v143 offset:0x2c00
	v_mfma_f32_32x32x16_bf16 v[48:63], v[188:191], v[144:147], v[48:63]
	ds_read_b64_tr_b16 v[188:189], v143 offset:0x3400
	ds_read_b64_tr_b16 v[190:191], v143 offset:0x3c00
	s_waitcnt lgkmcnt(0)
	v_mfma_f32_32x32x16_bf16 v[16:31], v[148:151], v[112:115], v[16:31]
	ds_read_b64_tr_b16 v[148:149], v143 offset:0x600
	ds_read_b64_tr_b16 v[150:151], v143 offset:0xe00
	v_mfma_f32_32x32x16_bf16 v[16:31], v[152:155], v[122:125], v[16:31]
	ds_read_b64_tr_b16 v[152:153], v143 offset:0x1600
	ds_read_b64_tr_b16 v[154:155], v143 offset:0x1e00
	v_mfma_f32_32x32x16_bf16 v[16:31], v[170:173], v[126:129], v[16:31]
	ds_read_b64_tr_b16 v[170:171], v143 offset:0x2600
	ds_read_b64_tr_b16 v[172:173], v143 offset:0x2e00
	v_mfma_f32_32x32x16_bf16 v[16:31], v[188:191], v[144:147], v[16:31]
	ds_read_b64_tr_b16 v[188:189], v143 offset:0x3600
	ds_read_b64_tr_b16 v[190:191], v143 offset:0x3e00
	s_waitcnt lgkmcnt(0)
	v_mfma_f32_32x32x16_bf16 v[0:15], v[148:151], v[112:115], v[0:15]
	v_max_f32_e32 v112, v80, v81
	v_max3_f32 v112, v112, v82, v83
	v_max3_f32 v112, v112, v84, v85
	v_max3_f32 v112, v112, v86, v87
	v_max3_f32 v112, v112, v88, v89
	v_max3_f32 v112, v112, v90, v91
	v_max3_f32 v112, v112, v92, v93
	v_mfma_f32_32x32x16_bf16 v[0:15], v[152:155], v[122:125], v[0:15]
	v_max3_f32 v112, v112, v94, v95
	v_max3_f32 v112, v112, v64, v65
	v_max3_f32 v112, v112, v66, v67
	v_max3_f32 v112, v112, v68, v69
	v_max3_f32 v112, v112, v70, v71
	v_max3_f32 v112, v112, v72, v73
	v_max3_f32 v112, v112, v74, v75
	v_max3_f32 v112, v112, v76, v77
	v_mfma_f32_32x32x16_bf16 v[0:15], v[170:173], v[126:129], v[0:15]
	v_max3_f32 v112, v112, v78, v79
	v_mov_b32_e32 v113, v112
	s_nop 1
	v_permlane32_swap_b32_e32 v112, v113
	v_max_f32_e32 v112, v112, v113
	v_cmp_ge_f32_e32 vcc, s70, v112
	v_mfma_f32_32x32x16_bf16 v[0:15], v[188:191], v[144:147], v[0:15]
	s_cmp_eq_u64 vcc, exec
	s_cselect_b64 s[4:5], -1, 0
	s_waitcnt vmcnt(0) lgkmcnt(0)
	s_barrier
; #define RESC(a) do { if (__any((a) < 1.f)) { if (hi == 0) al_l[r32] = (a); asm volatile("s_waitcnt lgkmcnt(0)" ::: "memory"); \
;     for (int d = 0; d < 4; ++d) for (int r = 0; r < 16; ++r) o[d][r] *= al_l[crow_(r, hi)]; } } while (0)
; #define TILE_BAR() do { asm volatile("s_waitcnt vmcnt(0) lgkmcnt(0)" ::: "memory"); __builtin_amdgcn_s_barrier(); } while (0)
; #define RESC(a) do { if (__any((a) < 1.f)) { for (int d = 0; d < 4; ++d) for (int r = 0; r < 16; ++r) o[d][r] *= (a); } } while (0)
; #define TILE_BAR() do { asm volatile("s_waitcnt vmcnt(0) lgkmcnt(0)" ::: "memory"); __builtin_amdgcn_s_barrier(); } while (0)
; #define RESC(a) do { if (__any((a) < 1.f)) { for (int d = 0; d < 4; ++d) for (int r = 0; r < 16; ++r) o[d][r] *= (a); } } while (0)
; template <int MLA>
; __device__ __forceinline__ void partialSM(f32x16& p0, f32x16& p1, float& m_reg, float& mn, float& alpha) {
;     ...
;   if (__builtin_expect(__all(pmax - m_reg <= THR / SCALE), 1)) { mn = m_reg; alpha = 1.f; }
;   else { mn = fmaxf(m_reg, pmax); alpha = __builtin_amdgcn_exp2f((m_reg - mn) * C); m_reg = mn; }
;   float mnC = -mn * C;
; #pragma unroll
;   for (int r = 0; r < 16; ++r) p0[r] = fmaf(p0[r], C, mnC);
; #pragma unroll
;   for (int r = 0; r < 16; ++r) p1[r] = fmaf(p1[r], C, mnC);
; #pragma unroll
;   for (int r = 0; r < 16; ++r) p0[r] = __builtin_amdgcn_exp2f(p0[r]);
; }
; __device__ __forceinline__ void finishSM(f32x16& p0, f32x16& p1, float alpha, float& l_reg, bf16x8& pa0, bf16x8& pa1, bf16x8& pa2, bf16x8& pa3) {
; #pragma unroll
;   for (int r = 0; r < 16; ++r) p1[r] = __builtin_amdgcn_exp2f(p1[r]);
; __device__ __forceinline__ void attn_diff_dma(const bf16_t* __restrict__ Qb, const bf16_t* __restrict__ Kh, const bf16_t* __restrict__ Vh, bf16_t* __restrict__ Ob,
;                                               int seq, char* lds, float lam, const float* __restrict__ gsub, const int tid) {
;     ...
;     pv_d0_t(o, vb0 + vprev * SHM_VV, pa0, pa1, pa2, pa3); partialSM<0>(pA0, pA1, m_reg, mnA, alA);
;     TILE_BAR();
;     RESC(alA);
;     { const int t = vprev; vprev = vcur; vcur = vnxt; vnxt = t; }
	s_cbranch_scc1 .Lal_c_d2
	v_max_f32_e32 v242, 0, v112
	v_exp_f32_e64 v112, -v242
	s_nop 0
	v_pk_mul_f32 v[46:47], v[46:47], v[112:113] op_sel_hi:[1,0]
	v_pk_mul_f32 v[44:45], v[44:45], v[112:113] op_sel_hi:[1,0]
	v_pk_mul_f32 v[42:43], v[42:43], v[112:113] op_sel_hi:[1,0]
	v_pk_mul_f32 v[40:41], v[40:41], v[112:113] op_sel_hi:[1,0]
	v_pk_mul_f32 v[38:39], v[38:39], v[112:113] op_sel_hi:[1,0]
	v_pk_mul_f32 v[36:37], v[36:37], v[112:113] op_sel_hi:[1,0]
	v_pk_mul_f32 v[34:35], v[34:35], v[112:113] op_sel_hi:[1,0]
	v_pk_mul_f32 v[32:33], v[32:33], v[112:113] op_sel_hi:[1,0]
	v_pk_mul_f32 v[62:63], v[62:63], v[112:113] op_sel_hi:[1,0]
	v_pk_mul_f32 v[60:61], v[60:61], v[112:113] op_sel_hi:[1,0]
	v_pk_mul_f32 v[58:59], v[58:59], v[112:113] op_sel_hi:[1,0]
	v_pk_mul_f32 v[56:57], v[56:57], v[112:113] op_sel_hi:[1,0]
	v_pk_mul_f32 v[54:55], v[54:55], v[112:113] op_sel_hi:[1,0]
	v_pk_mul_f32 v[52:53], v[52:53], v[112:113] op_sel_hi:[1,0]
	v_pk_mul_f32 v[50:51], v[50:51], v[112:113] op_sel_hi:[1,0]
	v_pk_mul_f32 v[48:49], v[48:49], v[112:113] op_sel_hi:[1,0]
	v_pk_mul_f32 v[30:31], v[30:31], v[112:113] op_sel_hi:[1,0]
	v_pk_mul_f32 v[28:29], v[28:29], v[112:113] op_sel_hi:[1,0]
	v_pk_mul_f32 v[26:27], v[26:27], v[112:113] op_sel_hi:[1,0]
	v_pk_mul_f32 v[24:25], v[24:25], v[112:113] op_sel_hi:[1,0]
	v_pk_mul_f32 v[22:23], v[22:23], v[112:113] op_sel_hi:[1,0]
	v_pk_mul_f32 v[20:21], v[20:21], v[112:113] op_sel_hi:[1,0]
	v_pk_mul_f32 v[18:19], v[18:19], v[112:113] op_sel_hi:[1,0]
	v_pk_mul_f32 v[16:17], v[16:17], v[112:113] op_sel_hi:[1,0]
	v_pk_mul_f32 v[14:15], v[14:15], v[112:113] op_sel_hi:[1,0]
	v_pk_mul_f32 v[12:13], v[12:13], v[112:113] op_sel_hi:[1,0]
	v_pk_mul_f32 v[10:11], v[10:11], v[112:113] op_sel_hi:[1,0]
	v_pk_mul_f32 v[8:9], v[8:9], v[112:113] op_sel_hi:[1,0]
	v_pk_mul_f32 v[6:7], v[6:7], v[112:113] op_sel_hi:[1,0]
	v_pk_mul_f32 v[4:5], v[4:5], v[112:113] op_sel_hi:[1,0]
	v_pk_mul_f32 v[2:3], v[2:3], v[112:113] op_sel_hi:[1,0]
	v_pk_mul_f32 v[0:1], v[0:1], v[112:113] op_sel_hi:[1,0]
	v_sub_f32_e32 v80, v80, v242
	v_sub_f32_e32 v81, v81, v242
	v_sub_f32_e32 v82, v82, v242
	v_sub_f32_e32 v83, v83, v242
	v_sub_f32_e32 v84, v84, v242
	v_sub_f32_e32 v85, v85, v242
	v_sub_f32_e32 v86, v86, v242
	v_sub_f32_e32 v87, v87, v242
	v_sub_f32_e32 v88, v88, v242
	v_sub_f32_e32 v89, v89, v242
	v_sub_f32_e32 v90, v90, v242
	v_sub_f32_e32 v91, v91, v242
	v_sub_f32_e32 v92, v92, v242
	v_sub_f32_e32 v93, v93, v242
	v_sub_f32_e32 v94, v94, v242
	v_sub_f32_e32 v95, v95, v242
	v_sub_f32_e32 v64, v64, v242
	v_sub_f32_e32 v65, v65, v242
	v_sub_f32_e32 v66, v66, v242
	v_sub_f32_e32 v67, v67, v242
	v_sub_f32_e32 v68, v68, v242
	v_sub_f32_e32 v69, v69, v242
	v_sub_f32_e32 v70, v70, v242
	v_sub_f32_e32 v71, v71, v242
	v_sub_f32_e32 v72, v72, v242
	v_sub_f32_e32 v73, v73, v242
	v_sub_f32_e32 v74, v74, v242
	v_sub_f32_e32 v75, v75, v242
	v_sub_f32_e32 v76, v76, v242
	v_sub_f32_e32 v77, v77, v242
	v_sub_f32_e32 v78, v78, v242
	v_sub_f32_e32 v79, v79, v242
	v_sub_f32_e32 v226, v226, v242
	v_sub_f32_e32 v227, v227, v242
	v_sub_f32_e32 v228, v228, v242
	v_sub_f32_e32 v229, v229, v242
	v_sub_f32_e32 v230, v230, v242
	v_sub_f32_e32 v231, v231, v242
	v_sub_f32_e32 v232, v232, v242
	v_sub_f32_e32 v233, v233, v242
	v_sub_f32_e32 v234, v234, v242
	v_sub_f32_e32 v235, v235, v242
	v_sub_f32_e32 v236, v236, v242
	v_sub_f32_e32 v237, v237, v242
	v_sub_f32_e32 v238, v238, v242
	v_sub_f32_e32 v239, v239, v242
	v_sub_f32_e32 v240, v240, v242
	v_sub_f32_e32 v241, v241, v242
	s_branch .LBB0_133
.Lal_c_d2:
	v_mov_b32_e32 v112, 1.0
.LBB0_133:
	v_exp_f32_e32 v113, v80
	v_exp_f32_e32 v155, v81
	v_exp_f32_e32 v152, v82
	v_exp_f32_e32 v156, v83
	v_exp_f32_e32 v153, v84
	v_exp_f32_e32 v158, v85
	v_exp_f32_e32 v154, v86
	v_exp_f32_e32 v159, v87
	v_exp_f32_e32 v144, v88
	v_exp_f32_e32 v148, v89
	v_exp_f32_e32 v145, v90
	v_exp_f32_e32 v149, v91
	v_exp_f32_e32 v146, v92
	v_exp_f32_e32 v150, v93
	v_exp_f32_e32 v147, v94
	v_exp_f32_e32 v151, v95
	v_add_f32_e32 v80, v117, v118
	s_add_u32 s14, s14, 0x40000
	v_fmac_f32_e32 v80, v142, v131
	v_add_f32_e32 v131, v120, v121
	s_mov_b32 s4, 0x3f800000
	s_addc_u32 s15, s15, 0
	s_add_i32 s50, s50, 2
	v_fmac_f32_e32 v131, v80, v116
	v_exp_f32_e32 v128, v64
	v_exp_f32_e32 v129, v65
	v_exp_f32_e32 v126, v66
	v_exp_f32_e32 v127, v67
	v_exp_f32_e32 v124, v68
	v_exp_f32_e32 v125, v69
	v_exp_f32_e32 v120, v70
	v_exp_f32_e32 v121, v71
	v_exp_f32_e32 v118, v72
	v_exp_f32_e32 v119, v73
	v_exp_f32_e32 v116, v74
	v_exp_f32_e32 v117, v75
	v_exp_f32_e32 v114, v76
	v_exp_f32_e32 v115, v77
	s_cmp_ge_u32 s50, s19
	v_exp_f32_e32 v122, v78
	v_exp_f32_e32 v123, v79
	s_cbranch_scc1 .LBB0_135
	s_mov_b32 s52, s53
	s_mov_b32 s53, s54
	v_mov_b32_e32 v142, v112
	s_branch .LBB0_129
; #define SBAR() __builtin_amdgcn_sched_barrier(0)
; template <int MLA>
; __device__ __forceinline__ void partialSM(f32x16& p0, f32x16& p1, float& m_reg, float& mn, float& alpha) {
;   constexpr float SCALE = AttC<MLA>::SCALE;
;   constexpr float C = SCALE * 1.4426950408889634f;
;   float pmax = p0[0];
; #pragma unroll
;   for (int r = 1; r < 16; ++r) pmax = fmaxf(pmax, p0[r]);
; #pragma unroll
;   for (int r = 0; r < 16; ++r) pmax = fmaxf(pmax, p1[r]);
;   { auto rr = __builtin_amdgcn_permlane32_swap(__float_as_uint(pmax), __float_as_uint(pmax), false, false);
;     pmax = fmaxf(__uint_as_float(rr[0]), __uint_as_float(rr[1])); }
;   if (__builtin_expect(__all(pmax - m_reg <= THR / SCALE), 1)) { mn = m_reg; alpha = 1.f; }
;   else { mn = fmaxf(m_reg, pmax); alpha = __builtin_amdgcn_exp2f((m_reg - mn) * C); m_reg = mn; }
;   float mnC = -mn * C;
; #pragma unroll
;   for (int r = 0; r < 16; ++r) p0[r] = fmaf(p0[r], C, mnC);
; #pragma unroll
;   for (int r = 0; r < 16; ++r) p1[r] = fmaf(p1[r], C, mnC);
; #pragma unroll
;   for (int r = 0; r < 16; ++r) p0[r] = __builtin_amdgcn_exp2f(p0[r]);
; }
; __device__ __forceinline__ void attn_diff_dma(const bf16_t* __restrict__ Qb, const bf16_t* __restrict__ Kh, const bf16_t* __restrict__ Vh, bf16_t* __restrict__ Ob,
;                                               int seq, char* lds, float lam, const float* __restrict__ gsub, const int tid) {
;     ...
;   SBAR(); qkt_diff<(int)SHM_K128>(pB0, pB1, ka, qr);
;   finishSM(pA0, pA1, alA, l_reg, pa0, pa1, pa2, pa3); SBAR();
;   pv_d0_t(o, vb0 + vprev * SHM_VV, pa0, pa1, pa2, pa3); partialSM<0>(pB0, pB1, m_reg, mnB, alB);
.LBB0_135:
	v_sub_f32_e32 v143, 0, v226
	ds_read_b128 v[64:67], v138 offset:16384
	ds_read_b128 v[68:71], v138 offset:24576
	s_waitcnt lgkmcnt(0)
	v_mfma_f32_32x32x16_bf16 v[80:95], v[64:67], v[108:111], 0
	v_mfma_f32_32x32x16_bf16 v[64:79], v[68:71], v[108:111], 0
	ds_read_b128 v[108:111], v141 offset:16384
	ds_read_b128 v[134:137], v141 offset:24576
	s_waitcnt lgkmcnt(0)
	v_mfma_f32_32x32x16_bf16 v[80:95], v[108:111], v[104:107], v[80:95]
	v_mfma_f32_32x32x16_bf16 v[64:79], v[134:137], v[104:107], v[64:79]
	ds_read_b128 v[104:107], v140 offset:16384
	ds_read_b128 v[108:111], v140 offset:24576
	s_waitcnt lgkmcnt(0)
	v_mfma_f32_32x32x16_bf16 v[80:95], v[104:107], v[100:103], v[80:95]
	v_mfma_f32_32x32x16_bf16 v[64:79], v[108:111], v[100:103], v[64:79]
	ds_read_b128 v[100:103], v139 offset:16384
	ds_read_b128 v[104:107], v139 offset:24576
	v_mov_b32_e32 v109, v126
	v_mov_b32_e32 v110, v127
	v_mov_b32_e32 v111, v124
	v_mov_b32_e32 v124, v125
	v_mov_b32_e32 v125, v114
	v_mov_b32_e32 v126, v115
	s_waitcnt lgkmcnt(0)
	v_mfma_f32_32x32x16_bf16 v[80:95], v[100:103], v[96:99], v[80:95]
	v_cvt_pk_bf16_f32 v100, v113, v155
	v_cvt_pk_bf16_f32 v101, v152, v156
	v_cvt_pk_bf16_f32 v102, v153, v158
	v_cvt_pk_bf16_f32 v103, v154, v159
	s_nop 0
	v_mfma_f32_32x32x16_bf16 v[64:79], v[104:107], v[96:99], v[64:79]
	v_add_f32_e32 v97, 0, v113
	v_add_f32_e32 v97, v155, v97
	v_add_f32_e32 v97, v152, v97
	v_add_f32_e32 v97, v156, v97
	v_add_f32_e32 v97, v153, v97
	v_add_f32_e32 v97, v158, v97
	v_add_f32_e32 v97, v154, v97
	v_add_f32_e32 v97, v159, v97
	v_add_f32_e32 v97, v144, v97
	v_add_f32_e32 v97, v148, v97
	v_add_f32_e32 v97, v145, v97
	v_add_f32_e32 v97, v149, v97
	v_mov_b32_e32 v96, v128
	v_add_f32_e32 v97, v146, v97
	v_mov_b32_e32 v99, v129
	v_add_f32_e32 v97, v150, v97
	v_add_f32_e32 v97, v147, v97
	v_add_f32_e32 v97, v151, v97
	v_add_f32_e32 v97, v96, v97
	v_add_f32_e32 v97, v99, v97
	v_add_f32_e32 v97, v109, v97
	v_add_f32_e32 v97, v110, v97
	v_add_f32_e32 v97, v111, v97
	v_add_f32_e32 v97, v124, v97
	v_add_f32_e32 v97, v120, v97
	v_add_f32_e32 v97, v121, v97
	v_add_f32_e32 v97, v118, v97
	v_add_f32_e32 v97, v119, v97
	v_add_f32_e32 v97, v116, v97
	v_add_f32_e32 v97, v117, v97
	v_add_f32_e32 v97, v125, v97
	v_add_f32_e32 v97, v126, v97
	v_add_f32_e32 v97, v122, v97
	v_add_f32_e32 v97, v123, v97
	v_mov_b32_e32 v98, v97
	s_nop 1
	v_permlane32_swap_b32_e32 v97, v98
	v_cvt_pk_bf16_f32 v104, v144, v148
	v_cvt_pk_bf16_f32 v105, v145, v149
	v_cvt_pk_bf16_f32 v106, v146, v150
	v_cvt_pk_bf16_f32 v107, v147, v151
	v_cvt_pk_bf16_f32 v108, v96, v99
	v_cvt_pk_bf16_f32 v109, v109, v110
	v_cvt_pk_bf16_f32 v110, v111, v124
	v_cvt_pk_bf16_f32 v111, v120, v121
	v_cvt_pk_bf16_f32 v114, v118, v119
	v_cvt_pk_bf16_f32 v115, v116, v117
	v_cvt_pk_bf16_f32 v116, v125, v126
	v_cvt_pk_bf16_f32 v117, v122, v123
	v_add_u32_e32 v96, s52, v133
	ds_read_b64_tr_b16 v[118:119], v96 offset:0
	ds_read_b64_tr_b16 v[120:121], v96 offset:0x800
	ds_read_b64_tr_b16 v[122:123], v96 offset:0x1000
	ds_read_b64_tr_b16 v[124:125], v96 offset:0x1800
	ds_read_b64_tr_b16 v[126:127], v96 offset:0x2000
	ds_read_b64_tr_b16 v[128:129], v96 offset:0x2800
	ds_read_b64_tr_b16 v[134:135], v96 offset:0x3000
	ds_read_b64_tr_b16 v[136:137], v96 offset:0x3800
	s_waitcnt lgkmcnt(0)
	s_nop 0
	v_mfma_f32_32x32x16_bf16 v[32:47], v[118:121], v[100:103], v[32:47]
	ds_read_b64_tr_b16 v[118:119], v96 offset:0x200
	ds_read_b64_tr_b16 v[120:121], v96 offset:0xa00
	v_mfma_f32_32x32x16_bf16 v[32:47], v[122:125], v[104:107], v[32:47]
	ds_read_b64_tr_b16 v[122:123], v96 offset:0x1200
	ds_read_b64_tr_b16 v[124:125], v96 offset:0x1a00
	v_mfma_f32_32x32x16_bf16 v[32:47], v[126:129], v[108:111], v[32:47]
	ds_read_b64_tr_b16 v[126:127], v96 offset:0x2200
	ds_read_b64_tr_b16 v[128:129], v96 offset:0x2a00
	v_mfma_f32_32x32x16_bf16 v[32:47], v[134:137], v[114:117], v[32:47]
	ds_read_b64_tr_b16 v[134:135], v96 offset:0x3200
	ds_read_b64_tr_b16 v[136:137], v96 offset:0x3a00
	s_waitcnt lgkmcnt(0)
	v_mfma_f32_32x32x16_bf16 v[48:63], v[118:121], v[100:103], v[48:63]
	ds_read_b64_tr_b16 v[118:119], v96 offset:0x400
	ds_read_b64_tr_b16 v[120:121], v96 offset:0xc00
	v_mfma_f32_32x32x16_bf16 v[48:63], v[122:125], v[104:107], v[48:63]
	ds_read_b64_tr_b16 v[122:123], v96 offset:0x1400
	ds_read_b64_tr_b16 v[124:125], v96 offset:0x1c00
	v_mfma_f32_32x32x16_bf16 v[48:63], v[126:129], v[108:111], v[48:63]
	ds_read_b64_tr_b16 v[126:127], v96 offset:0x2400
	ds_read_b64_tr_b16 v[128:129], v96 offset:0x2c00
	v_mfma_f32_32x32x16_bf16 v[48:63], v[134:137], v[114:117], v[48:63]
	ds_read_b64_tr_b16 v[134:135], v96 offset:0x3400
	ds_read_b64_tr_b16 v[136:137], v96 offset:0x3c00
	s_waitcnt lgkmcnt(0)
	v_mfma_f32_32x32x16_bf16 v[16:31], v[118:121], v[100:103], v[16:31]
	ds_read_b64_tr_b16 v[118:119], v96 offset:0x600
	ds_read_b64_tr_b16 v[120:121], v96 offset:0xe00
	v_mfma_f32_32x32x16_bf16 v[16:31], v[122:125], v[104:107], v[16:31]
	ds_read_b64_tr_b16 v[122:123], v96 offset:0x1600
	ds_read_b64_tr_b16 v[124:125], v96 offset:0x1e00
	v_mfma_f32_32x32x16_bf16 v[16:31], v[126:129], v[108:111], v[16:31]
	ds_read_b64_tr_b16 v[126:127], v96 offset:0x2600
	ds_read_b64_tr_b16 v[128:129], v96 offset:0x2e00
	v_mfma_f32_32x32x16_bf16 v[16:31], v[134:137], v[114:117], v[16:31]
	ds_read_b64_tr_b16 v[134:135], v96 offset:0x3600
	ds_read_b64_tr_b16 v[136:137], v96 offset:0x3e00
	s_waitcnt lgkmcnt(0)
	v_mfma_f32_32x32x16_bf16 v[0:15], v[118:121], v[100:103], v[0:15]
	v_max_f32_e32 v96, v81, v81
	v_max_f32_e32 v99, v80, v80
	v_max_f32_e32 v96, v99, v96
	v_max3_f32 v96, v96, v82, v83
	v_max3_f32 v96, v96, v84, v85
	v_max3_f32 v96, v96, v86, v87
	v_max3_f32 v96, v96, v88, v89
	v_max3_f32 v96, v96, v90, v91
	v_max3_f32 v96, v96, v92, v93
	v_mfma_f32_32x32x16_bf16 v[0:15], v[122:125], v[104:107], v[0:15]
	v_max3_f32 v96, v96, v94, v95
	v_max3_f32 v96, v96, v64, v65
	v_max3_f32 v96, v96, v66, v67
	v_max3_f32 v96, v96, v68, v69
	v_max3_f32 v96, v96, v70, v71
	v_max3_f32 v96, v96, v72, v73
	v_max3_f32 v96, v96, v74, v75
	v_max3_f32 v96, v96, v76, v77
	v_mfma_f32_32x32x16_bf16 v[0:15], v[126:129], v[108:111], v[0:15]
	v_max3_f32 v96, v96, v78, v79
	v_mov_b32_e32 v99, v96
	s_nop 1
	v_permlane32_swap_b32_e32 v96, v99
	v_max_f32_e32 v99, v99, v99
	v_max_f32_e32 v96, v96, v96
	v_max_f32_e32 v96, v96, v99
	v_sub_f32_e32 v99, v96, v143
	v_cmp_ge_f32_e32 vcc, s70, v99
	v_max_f32_e32 v99, v143, v143
	v_max_f32_e32 v99, v99, v96
	v_mfma_f32_32x32x16_bf16 v[0:15], v[134:137], v[114:117], v[0:15]
	v_sub_f32_e32 v96, v143, v99
	v_mul_f32_e32 v96, 0x3f800000, v96
	v_exp_f32_e32 v96, v96
	s_cmp_eq_u64 vcc, exec
	s_cselect_b64 s[4:5], -1, 0
	v_cndmask_b32_e64 v96, v96, 1.0, s[4:5]
	v_cmp_gt_f32_e32 vcc, 1.0, v96
	s_cbranch_vccz .LBB0_137
; #define SBAR() __builtin_amdgcn_sched_barrier(0)
; #define RESC(a) do { if (__any((a) < 1.f)) { if (hi == 0) al_l[r32] = (a); asm volatile("s_waitcnt lgkmcnt(0)" ::: "memory"); \
;     for (int d = 0; d < 4; ++d) for (int r = 0; r < 16; ++r) o[d][r] *= al_l[crow_(r, hi)]; } } while (0)
; #define RESC(a) do { if (__any((a) < 1.f)) { for (int d = 0; d < 4; ++d) for (int r = 0; r < 16; ++r) o[d][r] *= (a); } } while (0)
; #define RESC(a) do { if (__any((a) < 1.f)) { for (int d = 0; d < 4; ++d) for (int r = 0; r < 16; ++r) o[d][r] *= (a); } } while (0)
; __device__ __forceinline__ void finishSM(f32x16& p0, f32x16& p1, float alpha, float& l_reg, bf16x8& pa0, bf16x8& pa1, bf16x8& pa2, bf16x8& pa3) {
; #pragma unroll
;   for (int r = 0; r < 16; ++r) p1[r] = __builtin_amdgcn_exp2f(p1[r]);
;   float ps = 0;
; #pragma unroll
;   for (int r = 0; r < 16; ++r) ps += p0[r];
; #pragma unroll
;   for (int r = 0; r < 16; ++r) ps += p1[r];
;   { auto rr = __builtin_amdgcn_permlane32_swap(__float_as_uint(ps), __float_as_uint(ps), false, false);
;     ps = __uint_as_float(rr[0]) + __uint_as_float(rr[1]); }
;   l_reg = l_reg * alpha + ps;
;     ...
;   PK4(p0, 0, pa0); PK4(p0, 8, pa1); PK4(p1, 0, pa2); PK4(p1, 8, pa3);
;     ...
; }
; __device__ __forceinline__ void attn_diff_dma(const bf16_t* __restrict__ Qb, const bf16_t* __restrict__ Kh, const bf16_t* __restrict__ Vh, bf16_t* __restrict__ Ob,
;                                               int seq, char* lds, float lam, const float* __restrict__ gsub, const int tid) {
;     ...
;   RESC(alB);
;   finishSM(pB0, pB1, alB, l_reg, pa0, pa1, pa2, pa3); SBAR();
	v_pk_mul_f32 v[46:47], v[46:47], v[96:97] op_sel_hi:[1,0]
	v_pk_mul_f32 v[44:45], v[44:45], v[96:97] op_sel_hi:[1,0]
	v_pk_mul_f32 v[42:43], v[42:43], v[96:97] op_sel_hi:[1,0]
	v_pk_mul_f32 v[40:41], v[40:41], v[96:97] op_sel_hi:[1,0]
	v_pk_mul_f32 v[38:39], v[38:39], v[96:97] op_sel_hi:[1,0]
	v_pk_mul_f32 v[36:37], v[36:37], v[96:97] op_sel_hi:[1,0]
	v_pk_mul_f32 v[34:35], v[34:35], v[96:97] op_sel_hi:[1,0]
	v_pk_mul_f32 v[32:33], v[32:33], v[96:97] op_sel_hi:[1,0]
	v_pk_mul_f32 v[62:63], v[62:63], v[96:97] op_sel_hi:[1,0]
	v_pk_mul_f32 v[60:61], v[60:61], v[96:97] op_sel_hi:[1,0]
	v_pk_mul_f32 v[58:59], v[58:59], v[96:97] op_sel_hi:[1,0]
	v_pk_mul_f32 v[56:57], v[56:57], v[96:97] op_sel_hi:[1,0]
	v_pk_mul_f32 v[54:55], v[54:55], v[96:97] op_sel_hi:[1,0]
	v_pk_mul_f32 v[52:53], v[52:53], v[96:97] op_sel_hi:[1,0]
	v_pk_mul_f32 v[50:51], v[50:51], v[96:97] op_sel_hi:[1,0]
	v_pk_mul_f32 v[48:49], v[48:49], v[96:97] op_sel_hi:[1,0]
	v_pk_mul_f32 v[30:31], v[30:31], v[96:97] op_sel_hi:[1,0]
	v_pk_mul_f32 v[28:29], v[28:29], v[96:97] op_sel_hi:[1,0]
	v_pk_mul_f32 v[26:27], v[26:27], v[96:97] op_sel_hi:[1,0]
	v_pk_mul_f32 v[24:25], v[24:25], v[96:97] op_sel_hi:[1,0]
	v_pk_mul_f32 v[22:23], v[22:23], v[96:97] op_sel_hi:[1,0]
	v_pk_mul_f32 v[20:21], v[20:21], v[96:97] op_sel_hi:[1,0]
	v_pk_mul_f32 v[18:19], v[18:19], v[96:97] op_sel_hi:[1,0]
	v_pk_mul_f32 v[16:17], v[16:17], v[96:97] op_sel_hi:[1,0]
	v_pk_mul_f32 v[14:15], v[14:15], v[96:97] op_sel_hi:[1,0]
	v_pk_mul_f32 v[12:13], v[12:13], v[96:97] op_sel_hi:[1,0]
	v_pk_mul_f32 v[10:11], v[10:11], v[96:97] op_sel_hi:[1,0]
	v_pk_mul_f32 v[8:9], v[8:9], v[96:97] op_sel_hi:[1,0]
	v_pk_mul_f32 v[6:7], v[6:7], v[96:97] op_sel_hi:[1,0]
	v_pk_mul_f32 v[4:5], v[4:5], v[96:97] op_sel_hi:[1,0]
	v_pk_mul_f32 v[2:3], v[2:3], v[96:97] op_sel_hi:[1,0]
	v_pk_mul_f32 v[0:1], v[0:1], v[96:97] op_sel_hi:[1,0]
.LBB0_137:
	v_add_f32_e32 v97, v97, v98
	v_cndmask_b32_e64 v98, v99, v143, s[4:5]
	v_mul_f32_e32 v98, 0xbf800000, v98
	v_fmamk_f32 v80, v80, 0x3f800000, v98
	v_fmamk_f32 v81, v81, 0x3f800000, v98
	v_fmamk_f32 v82, v82, 0x3f800000, v98
	v_fmamk_f32 v83, v83, 0x3f800000, v98
	v_fmamk_f32 v84, v84, 0x3f800000, v98
	v_fmamk_f32 v85, v85, 0x3f800000, v98
	v_fmamk_f32 v86, v86, 0x3f800000, v98
	v_fmamk_f32 v87, v87, 0x3f800000, v98
	v_fmamk_f32 v88, v88, 0x3f800000, v98
	v_fmamk_f32 v89, v89, 0x3f800000, v98
	v_fmamk_f32 v90, v90, 0x3f800000, v98
	v_fmamk_f32 v91, v91, 0x3f800000, v98
	v_fmamk_f32 v92, v92, 0x3f800000, v98
	v_fmamk_f32 v93, v93, 0x3f800000, v98
	v_fmamk_f32 v94, v94, 0x3f800000, v98
	v_fmamk_f32 v95, v95, 0x3f800000, v98
	v_fmamk_f32 v64, v64, 0x3f800000, v98
	v_fmamk_f32 v65, v65, 0x3f800000, v98
	v_fmamk_f32 v66, v66, 0x3f800000, v98
	v_fmamk_f32 v67, v67, 0x3f800000, v98
	v_fmamk_f32 v68, v68, 0x3f800000, v98
	v_fmamk_f32 v69, v69, 0x3f800000, v98
	v_fmamk_f32 v70, v70, 0x3f800000, v98
	v_fmamk_f32 v71, v71, 0x3f800000, v98
	v_fmamk_f32 v72, v72, 0x3f800000, v98
	v_fmamk_f32 v73, v73, 0x3f800000, v98
	v_fmamk_f32 v74, v74, 0x3f800000, v98
	v_fmamk_f32 v75, v75, 0x3f800000, v98
	v_fmamk_f32 v76, v76, 0x3f800000, v98
	v_fmamk_f32 v77, v77, 0x3f800000, v98
	v_fmamk_f32 v78, v78, 0x3f800000, v98
	v_fmac_f32_e32 v98, 0x3f800000, v79
	v_exp_f32_e32 v79, v80
	v_exp_f32_e32 v80, v81
	v_exp_f32_e32 v81, v82
	v_exp_f32_e32 v82, v83
	v_exp_f32_e32 v83, v84
	v_exp_f32_e32 v84, v85
	v_exp_f32_e32 v85, v86
	v_exp_f32_e32 v86, v87
	v_exp_f32_e32 v87, v88
	v_exp_f32_e32 v88, v89
	v_exp_f32_e32 v89, v90
	v_exp_f32_e32 v90, v91
	v_exp_f32_e32 v91, v92
	v_exp_f32_e32 v92, v93
	v_exp_f32_e32 v93, v94
	v_exp_f32_e32 v94, v95
	v_exp_f32_e32 v95, v64
	v_add_f32_e32 v64, 0, v79
	v_add_f32_e32 v64, v80, v64
	v_add_f32_e32 v64, v81, v64
	v_add_f32_e32 v64, v82, v64
	v_add_f32_e32 v64, v83, v64
	v_add_f32_e32 v64, v84, v64
	v_add_f32_e32 v64, v85, v64
	v_add_f32_e32 v64, v86, v64
	v_add_f32_e32 v64, v87, v64
	v_add_f32_e32 v64, v88, v64
	v_add_f32_e32 v64, v89, v64
	v_add_f32_e32 v64, v90, v64
	v_add_f32_e32 v64, v91, v64
	v_exp_f32_e32 v99, v65
	v_add_f32_e32 v64, v92, v64
	v_exp_f32_e32 v100, v66
	v_add_f32_e32 v64, v93, v64
	v_exp_f32_e32 v101, v67
	v_add_f32_e32 v64, v94, v64
	v_exp_f32_e32 v102, v68
	v_add_f32_e32 v64, v95, v64
	v_exp_f32_e32 v103, v69
	v_add_f32_e32 v64, v99, v64
	v_exp_f32_e32 v104, v70
	v_add_f32_e32 v64, v100, v64
	v_exp_f32_e32 v105, v71
	v_add_f32_e32 v64, v101, v64
	v_exp_f32_e32 v106, v72
	v_add_f32_e32 v64, v102, v64
	v_exp_f32_e32 v107, v73
	v_add_f32_e32 v64, v103, v64
	v_exp_f32_e32 v108, v74
	v_add_f32_e32 v64, v104, v64
	v_exp_f32_e32 v109, v75
	v_add_f32_e32 v64, v105, v64
	v_exp_f32_e32 v110, v76
	v_add_f32_e32 v64, v106, v64
	v_exp_f32_e32 v111, v77
	v_add_f32_e32 v64, v107, v64
	v_fmac_f32_e32 v97, v131, v112
	v_exp_f32_e32 v112, v78
	v_add_f32_e32 v64, v108, v64
	v_exp_f32_e32 v98, v98
	v_add_f32_e32 v64, v109, v64
	v_add_f32_e32 v64, v110, v64
	v_add_f32_e32 v64, v111, v64
	v_add_f32_e32 v64, v112, v64
	v_add_f32_e32 v64, v98, v64
	v_mov_b32_e32 v65, v64
	s_nop 1
	v_permlane32_swap_b32_e32 v64, v65
	v_add_f32_e32 v113, v64, v65
	v_cvt_pk_bf16_f32 v64, v79, v80
	v_cvt_pk_bf16_f32 v65, v81, v82
	v_cvt_pk_bf16_f32 v66, v83, v84
	v_cvt_pk_bf16_f32 v67, v85, v86
	v_cvt_pk_bf16_f32 v68, v87, v88
	v_cvt_pk_bf16_f32 v69, v89, v90
	v_cvt_pk_bf16_f32 v70, v91, v92
	v_cvt_pk_bf16_f32 v71, v93, v94
	s_nop 0
	v_cvt_pk_bf16_f32 v72, v95, v99
	v_cvt_pk_bf16_f32 v73, v100, v101
	v_cvt_pk_bf16_f32 v74, v102, v103
	v_cvt_pk_bf16_f32 v75, v104, v105
	v_cvt_pk_bf16_f32 v76, v106, v107
	v_cvt_pk_bf16_f32 v77, v108, v109
	v_cvt_pk_bf16_f32 v78, v110, v111
	v_cvt_pk_bf16_f32 v79, v112, v98
	v_fmac_f32_e32 v113, v97, v96
	ds_read_b64_tr_b16 v[80:81], v132 offset:0
	ds_read_b64_tr_b16 v[82:83], v132 offset:0x800
	ds_read_b64_tr_b16 v[84:85], v132 offset:0x1000
	ds_read_b64_tr_b16 v[86:87], v132 offset:0x1800
	ds_read_b64_tr_b16 v[88:89], v132 offset:0x2000
	ds_read_b64_tr_b16 v[90:91], v132 offset:0x2800
	ds_read_b64_tr_b16 v[92:93], v132 offset:0x3000
	ds_read_b64_tr_b16 v[94:95], v132 offset:0x3800
	s_waitcnt lgkmcnt(0)
; __device__ __forceinline__ int crow_(int r, int hi) { return (r & 3) + 8 * (r >> 2) + 4 * hi; }
; __device__ __forceinline__ void attn_diff_dma(const bf16_t* __restrict__ Qb, const bf16_t* __restrict__ Kh, const bf16_t* __restrict__ Vh, bf16_t* __restrict__ Ob,
;                                               int seq, char* lds, float lam, const float* __restrict__ gsub, const int tid) {
;     ...
;   pv_d0_t(o, vb0 + vcur * SHM_VV, pa0, pa1, pa2, pa3);
;   int tide = tid; asm volatile("" : "+v"(tide));
;   const int wide = tide >> 6, r32e = tide & 31, hie = (tide >> 5) & 1, wrowe = wide & 3, compe = wide >> 2;
;   const float rl = __builtin_amdgcn_rcpf(l_reg);
;   __syncthreads();
;   float* X = (float*)lds + wrowe * QBLK + r32e;
;   if (compe == 1) {
; #pragma unroll
;     for (int d0 = 0; d0 < 4; ++d0)
; #pragma unroll
;       for (int r = 0; r < 16; ++r) X[(d0 * 32 + crow_(r, hie)) * 128] = o[d0][r] * rl;
;   }
	s_nop 0
	v_mfma_f32_32x32x16_bf16 v[32:47], v[80:83], v[64:67], v[32:47]
	ds_read_b64_tr_b16 v[80:81], v132 offset:0x200
	ds_read_b64_tr_b16 v[82:83], v132 offset:0xa00
	v_mfma_f32_32x32x16_bf16 v[32:47], v[84:87], v[68:71], v[32:47]
	ds_read_b64_tr_b16 v[84:85], v132 offset:0x1200
	ds_read_b64_tr_b16 v[86:87], v132 offset:0x1a00
	v_mfma_f32_32x32x16_bf16 v[32:47], v[88:91], v[72:75], v[32:47]
	ds_read_b64_tr_b16 v[88:89], v132 offset:0x2200
	ds_read_b64_tr_b16 v[90:91], v132 offset:0x2a00
	v_mfma_f32_32x32x16_bf16 v[32:47], v[92:95], v[76:79], v[32:47]
	ds_read_b64_tr_b16 v[92:93], v132 offset:0x3200
	ds_read_b64_tr_b16 v[94:95], v132 offset:0x3a00
	s_waitcnt lgkmcnt(0)
	v_mfma_f32_32x32x16_bf16 v[48:63], v[80:83], v[64:67], v[48:63]
	ds_read_b64_tr_b16 v[80:81], v132 offset:0x400
	ds_read_b64_tr_b16 v[82:83], v132 offset:0xc00
	v_mfma_f32_32x32x16_bf16 v[48:63], v[84:87], v[68:71], v[48:63]
	ds_read_b64_tr_b16 v[84:85], v132 offset:0x1400
	ds_read_b64_tr_b16 v[86:87], v132 offset:0x1c00
	v_mfma_f32_32x32x16_bf16 v[48:63], v[88:91], v[72:75], v[48:63]
	ds_read_b64_tr_b16 v[88:89], v132 offset:0x2400
	ds_read_b64_tr_b16 v[90:91], v132 offset:0x2c00
	v_mfma_f32_32x32x16_bf16 v[48:63], v[92:95], v[76:79], v[48:63]
	ds_read_b64_tr_b16 v[92:93], v132 offset:0x3400
	ds_read_b64_tr_b16 v[94:95], v132 offset:0x3c00
	s_waitcnt lgkmcnt(0)
	v_mfma_f32_32x32x16_bf16 v[16:31], v[80:83], v[64:67], v[16:31]
	ds_read_b64_tr_b16 v[80:81], v132 offset:0x600
	ds_read_b64_tr_b16 v[82:83], v132 offset:0xe00
	v_mfma_f32_32x32x16_bf16 v[16:31], v[84:87], v[68:71], v[16:31]
	ds_read_b64_tr_b16 v[84:85], v132 offset:0x1600
	ds_read_b64_tr_b16 v[86:87], v132 offset:0x1e00
	v_mfma_f32_32x32x16_bf16 v[16:31], v[88:91], v[72:75], v[16:31]
	ds_read_b64_tr_b16 v[88:89], v132 offset:0x2600
	ds_read_b64_tr_b16 v[90:91], v132 offset:0x2e00
	v_mfma_f32_32x32x16_bf16 v[16:31], v[92:95], v[76:79], v[16:31]
	ds_read_b64_tr_b16 v[92:93], v132 offset:0x3600
	ds_read_b64_tr_b16 v[94:95], v132 offset:0x3e00
	s_waitcnt lgkmcnt(0)
	v_mfma_f32_32x32x16_bf16 v[0:15], v[80:83], v[64:67], v[0:15]
	v_rcp_f32_e32 v156, v113
	v_lshrrev_b32_e32 v66, 1, v130
	v_and_b32_e32 v64, 31, v130
	v_and_b32_e32 v66, 0x60, v66
	v_lshlrev_b32_e32 v67, 2, v66
	v_bfe_u32 v65, v130, 5, 1
	v_mfma_f32_32x32x16_bf16 v[0:15], v[84:87], v[68:71], v[0:15]
	v_lshlrev_b32_e32 v68, 2, v64
	v_add3_u32 v67, 0, v67, v68
	v_and_b32_e32 v68, 0xffffff00, v130
	s_movk_i32 s4, 0x100
	v_cmp_eq_u32_e32 vcc, s4, v68
	v_lshl_add_u32 v71, v65, 11, v67
	s_waitcnt vmcnt(0)
	v_mfma_f32_32x32x16_bf16 v[0:15], v[88:91], v[72:75], v[0:15]
	s_barrier
	v_mfma_f32_32x32x16_bf16 v[0:15], v[92:95], v[76:79], v[0:15]
	s_and_saveexec_b64 s[4:5], vcc
	s_cbranch_execz .LBB0_139
	v_mul_f32_e32 v67, v156, v32
	v_mul_f32_e32 v68, v156, v33
	ds_write2st64_b32 v71, v67, v68 offset1:2
	v_mul_f32_e32 v67, v156, v34
	v_mul_f32_e32 v68, v156, v35
	ds_write2st64_b32 v71, v67, v68 offset0:4 offset1:6
	v_mul_f32_e32 v67, v156, v36
	v_mul_f32_e32 v68, v156, v37
	ds_write2st64_b32 v71, v67, v68 offset0:16 offset1:18
	v_mul_f32_e32 v67, v156, v38
	v_mul_f32_e32 v68, v156, v39
	ds_write2st64_b32 v71, v67, v68 offset0:20 offset1:22
	v_mul_f32_e32 v67, v156, v40
	v_mul_f32_e32 v68, v156, v41
	ds_write2st64_b32 v71, v67, v68 offset0:32 offset1:34
	v_mul_f32_e32 v67, v156, v42
	v_mul_f32_e32 v68, v156, v43
	ds_write2st64_b32 v71, v67, v68 offset0:36 offset1:38
	v_mul_f32_e32 v67, v156, v44
	v_mul_f32_e32 v68, v156, v45
	ds_write2st64_b32 v71, v67, v68 offset0:48 offset1:50
	v_mul_f32_e32 v67, v156, v46
	v_mul_f32_e32 v68, v156, v47
	ds_write2st64_b32 v71, v67, v68 offset0:52 offset1:54
	v_mul_f32_e32 v67, v156, v48
	v_mul_f32_e32 v68, v156, v49
	ds_write2st64_b32 v71, v67, v68 offset0:64 offset1:66
	v_mul_f32_e32 v67, v156, v50
	v_mul_f32_e32 v68, v156, v51
	ds_write2st64_b32 v71, v67, v68 offset0:68 offset1:70
	v_mul_f32_e32 v67, v156, v52
	v_mul_f32_e32 v68, v156, v53
	ds_write2st64_b32 v71, v67, v68 offset0:80 offset1:82
	v_mul_f32_e32 v67, v156, v54
	v_mul_f32_e32 v68, v156, v55
	ds_write2st64_b32 v71, v67, v68 offset0:84 offset1:86
	v_mul_f32_e32 v67, v156, v56
	v_mul_f32_e32 v68, v156, v57
	ds_write2st64_b32 v71, v67, v68 offset0:96 offset1:98
	v_mul_f32_e32 v67, v156, v58
	v_mul_f32_e32 v68, v156, v59
	ds_write2st64_b32 v71, v67, v68 offset0:100 offset1:102
	v_mul_f32_e32 v67, v156, v60
	v_mul_f32_e32 v68, v156, v61
	ds_write2st64_b32 v71, v67, v68 offset0:112 offset1:114
	v_mul_f32_e32 v67, v156, v62
	v_mul_f32_e32 v68, v156, v63
	ds_write2st64_b32 v71, v67, v68 offset0:116 offset1:118
	v_mul_f32_e32 v67, v156, v16
	v_mul_f32_e32 v68, v156, v17
	ds_write2st64_b32 v71, v67, v68 offset0:128 offset1:130
	v_mul_f32_e32 v67, v156, v18
	v_mul_f32_e32 v68, v156, v19
	ds_write2st64_b32 v71, v67, v68 offset0:132 offset1:134
	v_mul_f32_e32 v67, v156, v20
	v_mul_f32_e32 v68, v156, v21
	ds_write2st64_b32 v71, v67, v68 offset0:144 offset1:146
	v_mul_f32_e32 v67, v156, v22
	v_mul_f32_e32 v68, v156, v23
	ds_write2st64_b32 v71, v67, v68 offset0:148 offset1:150
	v_mul_f32_e32 v67, v156, v24
	v_mul_f32_e32 v68, v156, v25
	ds_write2st64_b32 v71, v67, v68 offset0:160 offset1:162
	v_mul_f32_e32 v67, v156, v26
	v_mul_f32_e32 v68, v156, v27
	ds_write2st64_b32 v71, v67, v68 offset0:164 offset1:166
	v_mul_f32_e32 v67, v156, v28
	v_mul_f32_e32 v68, v156, v29
	ds_write2st64_b32 v71, v67, v68 offset0:176 offset1:178
	v_mul_f32_e32 v67, v156, v30
	v_mul_f32_e32 v68, v156, v31
	ds_write2st64_b32 v71, v67, v68 offset0:180 offset1:182
	v_mul_f32_e32 v67, v156, v0
	v_mul_f32_e32 v68, v156, v1
	ds_write2st64_b32 v71, v67, v68 offset0:192 offset1:194
	v_mul_f32_e32 v67, v156, v2
	v_mul_f32_e32 v68, v156, v3
	ds_write2st64_b32 v71, v67, v68 offset0:196 offset1:198
	v_mul_f32_e32 v67, v156, v4
	v_mul_f32_e32 v68, v156, v5
	ds_write2st64_b32 v71, v67, v68 offset0:208 offset1:210
	v_mul_f32_e32 v67, v156, v6
	v_mul_f32_e32 v68, v156, v7
	ds_write2st64_b32 v71, v67, v68 offset0:212 offset1:214
	v_mul_f32_e32 v67, v156, v8
	v_mul_f32_e32 v68, v156, v9
	ds_write2st64_b32 v71, v67, v68 offset0:224 offset1:226
	v_mul_f32_e32 v67, v156, v10
	v_mul_f32_e32 v68, v156, v11
	ds_write2st64_b32 v71, v67, v68 offset0:228 offset1:230
	v_mul_f32_e32 v67, v156, v12
	v_mul_f32_e32 v68, v156, v13
	ds_write2st64_b32 v71, v67, v68 offset0:240 offset1:242
	v_mul_f32_e32 v67, v156, v14
	v_mul_f32_e32 v68, v156, v15
	ds_write2st64_b32 v71, v67, v68 offset0:244 offset1:246

; __device__ __forceinline__ void epi_apply(int mode, const Params& p, char* ws, float* outg, int S,
;                                           const float* crow, int chunk, int grow, int gcol, const float* rstat, const Side sd, const Col sc) {
;     ...
;     const float rs = rsqrtf((sd.d0[0] + sd.d0[1] + sd.d0[2] + sd.d0[3] + sd.d1[0] + sd.d1[1]) * (1.f / 768.f) + 1e-6f);
;     const int c = gcol % 192;
;     if (c >= 128) {
;       const int pos = grow & (S - 1), i = c - 128;
;       const float* cs = (const float*)(ws + O_COSM) + pos * 32; const float* sn = (const float*)(ws + O_SINM) + pos * 32;
;       if (i < 32) {
; #pragma unroll
;         for (int e = 0; e < 16; ++e) v[e] = (v[e] * cs[i + e] - cs_elem(crow, chunk + 2, e) * sn[i + e]) * rs;
;       } else {
; #pragma unroll
;         for (int e = 0; e < 16; ++e) v[e] = (v[e] * cs[i - 32 + e] + cs_elem(crow, chunk - 2, e) * sn[i - 32 + e]) * rs;
;       }
;     } else {
; #pragma unroll
;       for (int e = 0; e < 16; ++e) v[e] *= rs;
;     }
;     st_bf16x16((bf16_t*)(ws + O_Q) + (size_t)grow * 1536 + gcol, v);
.LBB0_219:
	s_and_b64 vcc, exec, s[26:27]
	s_cbranch_vccz .LBB0_229
	s_waitcnt vmcnt(0)
	v_add_f32_e32 v119, v120, v121
	v_add_f32_e32 v119, v122, v119
	v_add_f32_e32 v119, v123, v119
	v_add_f32_e32 v119, v124, v119
	v_add_f32_e32 v119, v125, v119
	v_fmamk_f32 v119, v119, 0x3aaaaaab, v174
	v_mul_f32_e32 v129, 0x4b800000, v119
	v_cmp_gt_f32_e32 vcc, s45, v119
	s_nop 1
	v_cndmask_b32_e32 v119, v119, v129, vcc
	v_rsq_f32_e32 v119, v119
	v_mul_hi_i32 v129, v130, s49
	v_lshrrev_b32_e32 v135, 31, v129
	v_mul_f32_e32 v137, 0x45800000, v119
	v_cndmask_b32_e32 v138, v119, v137, vcc
	v_mul_f32_e32 v138, 0x3dd53b94, v138
	v_lshrrev_b32_e32 v119, 5, v129
	v_add_u32_e32 v119, v119, v135
	v_mul_lo_u32 v119, v119, s48
	v_sub_u32_e32 v119, v130, v119
	v_cmp_gt_i32_e32 vcc, s77, v119
	s_and_saveexec_b64 s[26:27], vcc
	s_xor_b64 s[26:27], exec, s[26:27]
	v_pk_mul_f32 v[140:141], v[108:109], v[138:139] op_sel_hi:[1,0]
	v_pk_mul_f32 v[142:143], v[110:111], v[138:139] op_sel_hi:[1,0]
	v_pk_mul_f32 v[144:145], v[104:105], v[138:139] op_sel_hi:[1,0]
	v_pk_mul_f32 v[146:147], v[106:107], v[138:139] op_sel_hi:[1,0]
	v_pk_mul_f32 v[148:149], v[100:101], v[138:139] op_sel_hi:[1,0]
	v_pk_mul_f32 v[150:151], v[102:103], v[138:139] op_sel_hi:[1,0]
	v_pk_mul_f32 v[152:153], v[96:97], v[138:139] op_sel_hi:[1,0]
	v_mul_f32_e32 v129, v98, v138
	s_andn2_saveexec_b64 s[26:27], s[26:27]
	s_cbranch_execz .LBB0_228
	v_and_b32_e32 v129, s95, v128
	v_lshlrev_b32_e32 v162, 5, v129
	v_lshl_add_u64 v[140:141], v[162:163], 2, s[22:23]
	v_lshl_add_u64 v[156:157], v[140:141], 0, s[0:1]
	v_lshl_add_u64 v[154:155], v[140:141], 0, s[84:85]
	v_cmp_lt_u32_e32 vcc, s75, v119
	s_and_saveexec_b64 s[40:41], vcc
	s_xor_b64 s[40:41], exec, s[40:41]
	s_cbranch_execz .LBB0_225
	v_add_u32_e32 v162, 0xffffff60, v119
	v_lshlrev_b64 v[140:141], 2, v[162:163]
	v_lshl_add_u64 v[142:143], v[156:157], 0, v[140:141]
	v_lshl_add_u64 v[148:149], v[154:155], 0, v[140:141]
	flat_load_dwordx4 v[140:143], v[142:143]
	v_add_u32_e32 v129, -2, v173
	flat_load_dwordx4 v[148:151], v[148:149]
	v_lshlrev_b32_e32 v131, 4, v129
	v_and_b32_e32 v135, 12, v129
	v_or_b32_e32 v137, v135, v131
	v_lshl_add_u32 v137, v137, 2, v188
	ds_read_b128 v[144:147], v137
	v_add_u32_e32 v162, 0xffffff64, v119
	v_bitop3_b32 v137, v135, 4, v131 bitop3:0x36
	v_lshl_add_u32 v137, v137, 2, v188
	v_bitop3_b32 v131, v135, 8, v131 bitop3:0x36
	v_lshl_add_u32 v131, v131, 2, v188
	v_lshlrev_b32_e32 v129, 6, v129
	s_waitcnt vmcnt(0) lgkmcnt(0)
	v_pk_mul_f32 v[144:145], v[144:145], v[148:149]
	v_lshlrev_b64 v[148:149], 2, v[162:163]
	v_pk_fma_f32 v[140:141], v[108:109], v[140:141], v[144:145]
	v_pk_mul_f32 v[144:145], v[146:147], v[150:151]
	v_lshl_add_u64 v[150:151], v[156:157], 0, v[148:149]
	v_pk_fma_f32 v[142:143], v[110:111], v[142:143], v[144:145]
	ds_read_b128 v[144:147], v137
	v_lshl_add_u64 v[152:153], v[154:155], 0, v[148:149]
	flat_load_dwordx4 v[148:151], v[150:151]
	s_nop 0
	flat_load_dwordx4 v[190:193], v[152:153]
	v_add_u32_e32 v162, 0xffffff68, v119
	v_lshlrev_b64 v[152:153], 2, v[162:163]
	v_lshl_add_u64 v[158:159], v[156:157], 0, v[152:153]
	v_lshl_add_u64 v[152:153], v[154:155], 0, v[152:153]
	v_add_u32_e32 v162, 0xffffff6c, v119
	v_sub_u32_e32 v119, 1, v133
	v_and_b32_e32 v119, 12, v119
	v_lshlrev_b32_e32 v119, 2, v119
	v_add3_u32 v119, v188, v119, v129
	v_pk_mul_f32 v[140:141], v[138:139], v[140:141] op_sel_hi:[0,1]
	v_pk_mul_f32 v[142:143], v[138:139], v[142:143] op_sel_hi:[0,1]
	s_waitcnt vmcnt(0) lgkmcnt(0)
	v_pk_mul_f32 v[144:145], v[144:145], v[190:191]
	v_pk_mul_f32 v[146:147], v[146:147], v[192:193]
	v_pk_fma_f32 v[144:145], v[104:105], v[148:149], v[144:145]
	v_pk_fma_f32 v[146:147], v[106:107], v[150:151], v[146:147]
	ds_read_b128 v[148:151], v131
	flat_load_dwordx4 v[190:193], v[158:159]
	flat_load_dwordx4 v[194:197], v[152:153]
	v_lshlrev_b64 v[152:153], 2, v[162:163]
	v_lshl_add_u64 v[156:157], v[156:157], 0, v[152:153]
	v_lshl_add_u64 v[170:171], v[154:155], 0, v[152:153]
	flat_load_dwordx4 v[152:155], v[156:157]
	v_pk_mul_f32 v[144:145], v[138:139], v[144:145] op_sel_hi:[0,1]
	v_pk_mul_f32 v[146:147], v[138:139], v[146:147] op_sel_hi:[0,1]
	s_waitcnt vmcnt(0) lgkmcnt(0)
	v_pk_mul_f32 v[148:149], v[148:149], v[194:195]
	v_pk_mul_f32 v[150:151], v[150:151], v[196:197]
	v_pk_fma_f32 v[148:149], v[100:101], v[190:191], v[148:149]
	v_pk_fma_f32 v[150:151], v[102:103], v[192:193], v[150:151]
	flat_load_dwordx4 v[190:193], v[170:171]
	ds_read_b128 v[156:159], v119
	v_mov_b32_e32 v170, v154
	v_pk_mul_f32 v[148:149], v[138:139], v[148:149] op_sel_hi:[0,1]
	v_pk_mul_f32 v[150:151], v[138:139], v[150:151] op_sel_hi:[0,1]
	s_waitcnt vmcnt(0) lgkmcnt(0)
	v_pk_mul_f32 v[156:157], v[156:157], v[190:191]
	s_nop 0
	v_pk_fma_f32 v[152:153], v[96:97], v[152:153], v[156:157]
	v_mov_b32_e32 v156, v98
	v_mov_b32_e32 v157, v158
	v_mov_b32_e32 v171, v192
	v_pk_mul_f32 v[156:157], v[156:157], v[170:171]
	v_mov_b32_e32 v158, v99
	v_mov_b32_e32 v192, v155
	v_add_f32_e32 v119, v156, v157
	v_pk_mul_f32 v[154:155], v[158:159], v[192:193]
	v_pk_mul_f32 v[152:153], v[138:139], v[152:153] op_sel_hi:[0,1]
	v_mul_f32_e32 v129, v138, v119
	v_add_f32_e32 v131, v154, v155

; __device__ __forceinline__ void epi_apply(int mode, const Params& p, char* ws, float* outg, int S,
;                                           const float* crow, int chunk, int grow, int gcol, const float* rstat, const Side sd, const Col sc) {
;     ...
;     } else if (tn < 14) {
;       const int col = gcol - 1536;
;       if ((col & 63) == 0) {
;         const int pos = grow & (S - 1);
;         const float* cs = (const float*)(ws + O_COSD) + pos * 8; const float* sn = (const float*)(ws + O_SIND) + pos * 8;
; #pragma unroll
;         for (int e = 0; e < 8; ++e) { float a = v[e], b = v[e + 8], c = cs[e], s = sn[e]; v[e] = a * c - b * s; v[e + 8] = b * c + a * s; }
;       }
;       st_bf16x16((bf16_t*)(ws + O_DQ) + (size_t)grow * 1024 + (col & 1023) + (size_t)(col >> 10) * ((O_DK - O_DQ) / 2), v);
.LBB0_266:
	s_or_b64 exec, exec, s[4:5]
	v_add_u32_e32 v131, 0xfffffa00, v130
	v_ashrrev_i32_e32 v129, 31, v128
	v_lshlrev_b64 v[134:135], 11, v[128:129]
	v_and_b32_e32 v129, 0x3f0, v131
	v_ashrrev_i32_e32 v136, 10, v131
	v_lshl_add_u64 v[134:135], s[22:23], 0, v[134:135]
	v_lshlrev_b32_e32 v162, 1, v129
	v_ashrrev_i32_e32 v137, 31, v136
	v_lshl_add_u64 v[134:135], v[134:135], 0, v[162:163]
	v_lshlrev_b64 v[136:137], 25, v[136:137]
	v_lshl_add_u64 v[134:135], v[134:135], 0, v[136:137]
	v_cmp_gt_i32_e32 vcc, 0x400, v131
	v_mov_b32_e32 v246, 0x3e38aa3b
	s_nop 0
	v_cndmask_b32_e32 v247, 1.0, v246, vcc
	v_mul_f32_e32 v116, v116, v247
	v_mul_f32_e32 v117, v117, v247
	v_mul_f32_e32 v118, v118, v247
	v_mul_f32_e32 v119, v119, v247
	v_mul_f32_e32 v122, v122, v247
	v_mul_f32_e32 v123, v123, v247
	v_mul_f32_e32 v124, v124, v247
	v_mul_f32_e32 v125, v125, v247
	v_mul_f32_e32 v112, v112, v247
	v_mul_f32_e32 v113, v113, v247
	v_mul_f32_e32 v114, v114, v247
	v_mul_f32_e32 v115, v115, v247
	v_mul_f32_e32 v120, v120, v247
	v_mul_f32_e32 v121, v121, v247
	v_mul_f32_e32 v126, v126, v247
	v_mul_f32_e32 v127, v127, v247
	v_cvt_pk_bf16_f32 v116, v116, v117
	v_cvt_pk_bf16_f32 v117, v118, v119
	v_cvt_pk_bf16_f32 v118, v122, v123
	v_cvt_pk_bf16_f32 v119, v124, v125
	v_cvt_pk_bf16_f32 v112, v112, v113
	v_cvt_pk_bf16_f32 v113, v114, v115
	v_cvt_pk_bf16_f32 v114, v120, v121
	v_add_co_u32_e32 v120, vcc, 0xe000000, v134
	s_mov_b64 s[4:5], 0xe000000
	s_nop 0
	v_addc_co_u32_e32 v121, vcc, 0, v135, vcc
	v_lshl_add_u64 v[136:137], v[134:135], 0, s[4:5]
	v_cvt_pk_bf16_f32 v115, v126, v127
	flat_store_dwordx4 v[120:121], v[116:119]
	flat_store_dwordx4 v[136:137], v[112:115] offset:16

; __device__ __forceinline__ void epi_apply(int mode, const Params& p, char* ws, float* outg, int S,
;                                           const float* crow, int chunk, int grow, int gcol, const float* rstat, const Side sd, const Col sc) {
;     ...
;     const float rs = rsqrtf((sd.d0[0] + sd.d0[1] + sd.d0[2] + sd.d0[3] + sd.d1[0] + sd.d1[1]) * (1.f / 768.f) + 1e-6f);
;     const int c = gcol % 192;
;     if (c >= 128) {
;       const int pos = grow & (S - 1), i = c - 128;
;       const float* cs = (const float*)(ws + O_COSM) + pos * 32; const float* sn = (const float*)(ws + O_SINM) + pos * 32;
;       if (i < 32) {
; #pragma unroll
;         for (int e = 0; e < 16; ++e) v[e] = (v[e] * cs[i + e] - cs_elem(crow, chunk + 2, e) * sn[i + e]) * rs;
;       } else {
; #pragma unroll
;         for (int e = 0; e < 16; ++e) v[e] = (v[e] * cs[i - 32 + e] + cs_elem(crow, chunk - 2, e) * sn[i - 32 + e]) * rs;
;       }
;     } else {
; #pragma unroll
;       for (int e = 0; e < 16; ++e) v[e] *= rs;
;     }
;     st_bf16x16((bf16_t*)(ws + O_Q) + (size_t)grow * 1536 + gcol, v);
.LBB0_318:
	s_and_b64 vcc, exec, s[40:41]
	s_cbranch_vccz .LBB0_328
	s_waitcnt vmcnt(0)
	v_add_f32_e32 v55, v56, v57
	v_add_f32_e32 v55, v58, v55
	v_add_f32_e32 v55, v59, v55
	v_add_f32_e32 v55, v60, v55
	v_add_f32_e32 v55, v61, v55
	v_fmamk_f32 v55, v55, 0x3aaaaaab, v174
	v_mul_f32_e32 v65, 0x4b800000, v55
	v_cmp_gt_f32_e32 vcc, s45, v55
	s_nop 1
	v_cndmask_b32_e32 v55, v55, v65, vcc
	v_rsq_f32_e32 v55, v55
	v_mul_hi_i32 v65, v66, s49
	v_lshrrev_b32_e32 v71, 31, v65
	v_mul_f32_e32 v73, 0x45800000, v55
	v_cndmask_b32_e32 v74, v55, v73, vcc
	v_mul_f32_e32 v74, 0x3dd53b94, v74
	v_lshrrev_b32_e32 v55, 5, v65
	v_add_u32_e32 v55, v55, v71
	v_mul_lo_u32 v55, v55, s48
	v_sub_u32_e32 v55, v66, v55
	v_cmp_gt_i32_e32 vcc, s77, v55
	s_and_saveexec_b64 s[40:41], vcc
	s_xor_b64 s[40:41], exec, s[40:41]
	v_pk_mul_f32 v[76:77], v[44:45], v[74:75] op_sel_hi:[1,0]
	v_pk_mul_f32 v[78:79], v[46:47], v[74:75] op_sel_hi:[1,0]
	v_pk_mul_f32 v[80:81], v[40:41], v[74:75] op_sel_hi:[1,0]
	v_pk_mul_f32 v[82:83], v[42:43], v[74:75] op_sel_hi:[1,0]
	v_pk_mul_f32 v[84:85], v[36:37], v[74:75] op_sel_hi:[1,0]
	v_pk_mul_f32 v[86:87], v[38:39], v[74:75] op_sel_hi:[1,0]
	v_pk_mul_f32 v[88:89], v[32:33], v[74:75] op_sel_hi:[1,0]
	v_mul_f32_e32 v65, v34, v74
	s_andn2_saveexec_b64 s[40:41], s[40:41]
	s_cbranch_execz .LBB0_327
	v_and_b32_e32 v65, s95, v64
	v_lshlrev_b32_e32 v162, 5, v65
	v_lshl_add_u64 v[76:77], v[162:163], 2, s[22:23]
	v_lshl_add_u64 v[92:93], v[76:77], 0, s[0:1]
	v_lshl_add_u64 v[90:91], v[76:77], 0, s[84:85]
	v_cmp_lt_u32_e32 vcc, s75, v55
	s_and_saveexec_b64 s[42:43], vcc
	s_xor_b64 s[42:43], exec, s[42:43]
	s_cbranch_execz .LBB0_324
	v_add_u32_e32 v162, 0xffffff60, v55
	v_lshlrev_b64 v[76:77], 2, v[162:163]
	v_lshl_add_u64 v[78:79], v[92:93], 0, v[76:77]
	v_lshl_add_u64 v[84:85], v[90:91], 0, v[76:77]
	flat_load_dwordx4 v[76:79], v[78:79]
	v_add_u32_e32 v65, -2, v98
	flat_load_dwordx4 v[84:87], v[84:85]
	v_lshlrev_b32_e32 v67, 4, v65
	v_and_b32_e32 v71, 12, v65
	v_or_b32_e32 v73, v71, v67
	v_lshl_add_u32 v73, v73, 2, v99
	ds_read_b128 v[80:83], v73
	v_add_u32_e32 v162, 0xffffff64, v55
	v_bitop3_b32 v73, v71, 4, v67 bitop3:0x36
	v_lshl_add_u32 v73, v73, 2, v99
	v_bitop3_b32 v67, v71, 8, v67 bitop3:0x36
	v_lshl_add_u32 v67, v67, 2, v99
	v_lshlrev_b32_e32 v65, 6, v65
	s_waitcnt vmcnt(0) lgkmcnt(0)
	v_pk_mul_f32 v[80:81], v[80:81], v[84:85]
	v_lshlrev_b64 v[84:85], 2, v[162:163]
	v_pk_fma_f32 v[76:77], v[44:45], v[76:77], v[80:81]
	v_pk_mul_f32 v[80:81], v[82:83], v[86:87]
	v_lshl_add_u64 v[86:87], v[92:93], 0, v[84:85]
	v_pk_fma_f32 v[78:79], v[46:47], v[78:79], v[80:81]
	ds_read_b128 v[80:83], v73
	v_lshl_add_u64 v[88:89], v[90:91], 0, v[84:85]
	flat_load_dwordx4 v[84:87], v[86:87]
	s_nop 0
	flat_load_dwordx4 v[94:97], v[88:89]
	v_add_u32_e32 v162, 0xffffff68, v55
	v_lshlrev_b64 v[88:89], 2, v[162:163]
	v_add_u32_e32 v162, 0xffffff6c, v55
	v_sub_u32_e32 v55, 1, v69
	v_and_b32_e32 v55, 12, v55
	v_lshlrev_b32_e32 v55, 2, v55
	v_add3_u32 v55, v99, v55, v65
	v_pk_mul_f32 v[76:77], v[74:75], v[76:77] op_sel_hi:[0,1]
	v_pk_mul_f32 v[78:79], v[74:75], v[78:79] op_sel_hi:[0,1]
	s_waitcnt vmcnt(0) lgkmcnt(0)
	v_pk_mul_f32 v[80:81], v[80:81], v[94:95]
	v_pk_mul_f32 v[82:83], v[82:83], v[96:97]
	v_lshl_add_u64 v[94:95], v[92:93], 0, v[88:89]
	v_pk_fma_f32 v[80:81], v[40:41], v[84:85], v[80:81]
	v_pk_fma_f32 v[82:83], v[42:43], v[86:87], v[82:83]
	ds_read_b128 v[84:87], v67
	v_lshl_add_u64 v[88:89], v[90:91], 0, v[88:89]
	flat_load_dwordx4 v[94:97], v[94:95]
	s_nop 0
	flat_load_dwordx4 v[102:105], v[88:89]
	v_lshlrev_b64 v[88:89], 2, v[162:163]
	v_lshl_add_u64 v[92:93], v[92:93], 0, v[88:89]
	v_pk_mul_f32 v[80:81], v[74:75], v[80:81] op_sel_hi:[0,1]
	v_pk_mul_f32 v[82:83], v[74:75], v[82:83] op_sel_hi:[0,1]
	s_waitcnt vmcnt(0) lgkmcnt(0)
	v_pk_mul_f32 v[86:87], v[86:87], v[104:105]
	s_nop 0
	v_pk_fma_f32 v[86:87], v[38:39], v[96:97], v[86:87]
	v_lshl_add_u64 v[96:97], v[90:91], 0, v[88:89]
	v_pk_mul_f32 v[84:85], v[84:85], v[102:103]
	flat_load_dwordx4 v[88:91], v[92:93]
	flat_load_dwordx4 v[102:105], v[96:97]
	v_pk_fma_f32 v[84:85], v[36:37], v[94:95], v[84:85]
	ds_read_b128 v[92:95], v55
	v_pk_mul_f32 v[84:85], v[74:75], v[84:85] op_sel_hi:[0,1]
	v_pk_mul_f32 v[86:87], v[74:75], v[86:87] op_sel_hi:[0,1]
	s_waitcnt vmcnt(0) lgkmcnt(0)
	v_mov_b32_e32 v96, v90
	v_pk_mul_f32 v[92:93], v[92:93], v[102:103]
	v_mov_b32_e32 v97, v104
	v_pk_fma_f32 v[88:89], v[32:33], v[88:89], v[92:93]
	v_mov_b32_e32 v92, v34
	v_mov_b32_e32 v93, v94
	v_pk_mul_f32 v[92:93], v[92:93], v[96:97]
	v_mov_b32_e32 v94, v35
	v_mov_b32_e32 v104, v91
	v_add_f32_e32 v55, v92, v93
	v_pk_mul_f32 v[90:91], v[94:95], v[104:105]
	v_pk_mul_f32 v[88:89], v[74:75], v[88:89] op_sel_hi:[0,1]
	v_mul_f32_e32 v65, v74, v55
	v_add_f32_e32 v67, v90, v91

; __device__ __forceinline__ void epi_apply(int mode, const Params& p, char* ws, float* outg, int S,
;                                           const float* crow, int chunk, int grow, int gcol, const float* rstat, const Side sd, const Col sc) {
;     ...
;     } else if (tn < 14) {
;       const int col = gcol - 1536;
;       if ((col & 63) == 0) {
;         const int pos = grow & (S - 1);
;         const float* cs = (const float*)(ws + O_COSD) + pos * 8; const float* sn = (const float*)(ws + O_SIND) + pos * 8;
; #pragma unroll
;         for (int e = 0; e < 8; ++e) { float a = v[e], b = v[e + 8], c = cs[e], s = sn[e]; v[e] = a * c - b * s; v[e + 8] = b * c + a * s; }
;       }
;       st_bf16x16((bf16_t*)(ws + O_DQ) + (size_t)grow * 1024 + (col & 1023) + (size_t)(col >> 10) * ((O_DK - O_DQ) / 2), v);
.LBB0_365:
	s_or_b64 exec, exec, s[4:5]
	v_add_u32_e32 v67, 0xfffffa00, v66
	v_ashrrev_i32_e32 v65, 31, v64
	v_lshlrev_b64 v[70:71], 11, v[64:65]
	v_and_b32_e32 v65, 0x3f0, v67
	v_ashrrev_i32_e32 v72, 10, v67
	v_lshl_add_u64 v[70:71], s[22:23], 0, v[70:71]
	v_lshlrev_b32_e32 v162, 1, v65
	v_ashrrev_i32_e32 v73, 31, v72
	v_lshl_add_u64 v[70:71], v[70:71], 0, v[162:163]
	v_lshlrev_b64 v[72:73], 25, v[72:73]
	v_lshl_add_u64 v[70:71], v[70:71], 0, v[72:73]
	v_cmp_gt_i32_e32 vcc, 0x400, v67
	v_mov_b32_e32 v246, 0x3e38aa3b
	s_nop 0
	v_cndmask_b32_e32 v247, 1.0, v246, vcc
	v_mul_f32_e32 v52, v52, v247
	v_mul_f32_e32 v53, v53, v247
	v_mul_f32_e32 v54, v54, v247
	v_mul_f32_e32 v55, v55, v247
	v_mul_f32_e32 v58, v58, v247
	v_mul_f32_e32 v59, v59, v247
	v_mul_f32_e32 v60, v60, v247
	v_mul_f32_e32 v61, v61, v247
	v_mul_f32_e32 v48, v48, v247
	v_mul_f32_e32 v49, v49, v247
	v_mul_f32_e32 v50, v50, v247
	v_mul_f32_e32 v51, v51, v247
	v_mul_f32_e32 v56, v56, v247
	v_mul_f32_e32 v57, v57, v247
	v_mul_f32_e32 v62, v62, v247
	v_mul_f32_e32 v63, v63, v247
	v_cvt_pk_bf16_f32 v52, v52, v53
	v_cvt_pk_bf16_f32 v53, v54, v55
	v_cvt_pk_bf16_f32 v54, v58, v59
	v_cvt_pk_bf16_f32 v55, v60, v61
	v_cvt_pk_bf16_f32 v48, v48, v49
	v_cvt_pk_bf16_f32 v49, v50, v51
	v_cvt_pk_bf16_f32 v50, v56, v57
	v_add_co_u32_e32 v56, vcc, 0xe000000, v70
	s_mov_b64 s[4:5], 0xe000000
	s_nop 0
	v_addc_co_u32_e32 v57, vcc, 0, v71, vcc
	v_lshl_add_u64 v[72:73], v[70:71], 0, s[4:5]
	v_cvt_pk_bf16_f32 v51, v62, v63
	flat_store_dwordx4 v[56:57], v[52:55]
	flat_store_dwordx4 v[72:73], v[48:51] offset:16
